# score phases: pipelined q.subkey MFMA loops (8-deep LDS ring, q prefetch), batched sub-key staging loads
# speedup vs baseline: 1.0177x; 1.0094x over previous
; DEV void phase_peer_score(const Params& p, int layer, int M, char* smem) {
;     ...
;     if (h != hcur) {
;       hcur = h;
;       __syncthreads();
; #pragma unroll
;       for (int i = 0; i < 16; i++) {
;         int id = tid + i * 256; int row = id >> 4, cc = id & 15;
;         *(uint4*)(SKs + row * 144 + cc * 8) = *(const uint4*)(SK + ((size_t)h * 256 + row) * 128 + cc * 8);
;       }
;       __syncthreads();
;     }
.LBB0_163:
	s_and_b32 s19, s18, 7
	s_cmp_lg_u32 s19, s17
	s_mov_b64 s[0:1], -1
	s_cbranch_scc0 .LBB0_165
	s_lshl_b32 s52, s19, 8
	s_barrier
	s_mov_b64 s[0:1], 0
	v_lshl_add_u64 v[2:3], s[52:53], 0, v[36:37]
	v_lshlrev_b64 v[2:3], 8, v[2:3]
	v_lshl_add_u64 v[2:3], v[34:35], 0, v[2:3]
	global_load_dwordx4 v[148:151], v[2:3], off
	v_lshl_add_u64 v[2:3], s[52:53], 0, v[40:41]
	v_lshlrev_b64 v[2:3], 8, v[2:3]
	v_lshl_add_u64 v[2:3], v[34:35], 0, v[2:3]
	global_load_dwordx4 v[152:155], v[2:3], off
	v_lshl_add_u64 v[2:3], s[52:53], 0, v[44:45]
	v_lshlrev_b64 v[2:3], 8, v[2:3]
	v_lshl_add_u64 v[2:3], v[34:35], 0, v[2:3]
	global_load_dwordx4 v[156:159], v[2:3], off
	v_lshl_add_u64 v[2:3], s[52:53], 0, v[48:49]
	v_lshlrev_b64 v[2:3], 8, v[2:3]
	v_lshl_add_u64 v[2:3], v[34:35], 0, v[2:3]
	global_load_dwordx4 v[160:163], v[2:3], off
	v_lshl_add_u64 v[2:3], s[52:53], 0, v[52:53]
	v_lshlrev_b64 v[2:3], 8, v[2:3]
	v_lshl_add_u64 v[2:3], v[34:35], 0, v[2:3]
	global_load_dwordx4 v[164:167], v[2:3], off
	v_lshl_add_u64 v[2:3], s[52:53], 0, v[56:57]
	v_lshlrev_b64 v[2:3], 8, v[2:3]
	v_lshl_add_u64 v[2:3], v[34:35], 0, v[2:3]
	global_load_dwordx4 v[168:171], v[2:3], off
	v_lshl_add_u64 v[2:3], s[52:53], 0, v[60:61]
	v_lshlrev_b64 v[2:3], 8, v[2:3]
	v_lshl_add_u64 v[2:3], v[34:35], 0, v[2:3]
	global_load_dwordx4 v[172:175], v[2:3], off
	v_lshl_add_u64 v[2:3], s[52:53], 0, v[64:65]
	v_lshlrev_b64 v[2:3], 8, v[2:3]
	v_lshl_add_u64 v[2:3], v[34:35], 0, v[2:3]
	global_load_dwordx4 v[176:179], v[2:3], off
	s_waitcnt vmcnt(7)
	ds_write_b128 v38, v[148:151]
	v_lshl_add_u64 v[2:3], s[52:53], 0, v[68:69]
	v_lshlrev_b64 v[2:3], 8, v[2:3]
	v_lshl_add_u64 v[2:3], v[34:35], 0, v[2:3]
	global_load_dwordx4 v[148:151], v[2:3], off
	s_waitcnt vmcnt(7)
	ds_write_b128 v42, v[152:155]
	v_lshl_add_u64 v[2:3], s[52:53], 0, v[72:73]
	v_lshlrev_b64 v[2:3], 8, v[2:3]
	v_lshl_add_u64 v[2:3], v[34:35], 0, v[2:3]
	global_load_dwordx4 v[152:155], v[2:3], off
	s_waitcnt vmcnt(7)
	ds_write_b128 v46, v[156:159]
	v_lshl_add_u64 v[2:3], s[52:53], 0, v[76:77]
	v_lshlrev_b64 v[2:3], 8, v[2:3]
	v_lshl_add_u64 v[2:3], v[34:35], 0, v[2:3]
	global_load_dwordx4 v[156:159], v[2:3], off
	s_waitcnt vmcnt(7)
	ds_write_b128 v50, v[160:163]
	v_lshl_add_u64 v[2:3], s[52:53], 0, v[80:81]
	v_lshlrev_b64 v[2:3], 8, v[2:3]
	v_lshl_add_u64 v[2:3], v[34:35], 0, v[2:3]
	global_load_dwordx4 v[160:163], v[2:3], off
	s_waitcnt vmcnt(7)
	ds_write_b128 v54, v[164:167]
	v_lshl_add_u64 v[2:3], s[52:53], 0, v[84:85]
	v_lshlrev_b64 v[2:3], 8, v[2:3]
	v_lshl_add_u64 v[2:3], v[34:35], 0, v[2:3]
	global_load_dwordx4 v[164:167], v[2:3], off
	s_waitcnt vmcnt(7)
	ds_write_b128 v58, v[168:171]
	v_lshl_add_u64 v[2:3], s[52:53], 0, v[88:89]
	v_lshlrev_b64 v[2:3], 8, v[2:3]
	v_lshl_add_u64 v[2:3], v[34:35], 0, v[2:3]
	global_load_dwordx4 v[168:171], v[2:3], off
	s_waitcnt vmcnt(7)
	ds_write_b128 v62, v[172:175]
	v_lshl_add_u64 v[2:3], s[52:53], 0, v[92:93]
	v_lshlrev_b64 v[2:3], 8, v[2:3]
	v_lshl_add_u64 v[2:3], v[34:35], 0, v[2:3]
	global_load_dwordx4 v[172:175], v[2:3], off
	s_waitcnt vmcnt(7)
	ds_write_b128 v66, v[176:179]
	v_lshl_add_u64 v[2:3], s[52:53], 0, v[96:97]
	v_lshlrev_b64 v[2:3], 8, v[2:3]
	v_lshl_add_u64 v[2:3], v[34:35], 0, v[2:3]
	global_load_dwordx4 v[176:179], v[2:3], off
	s_waitcnt vmcnt(7)
	ds_write_b128 v70, v[148:151]
	s_waitcnt vmcnt(6)
	ds_write_b128 v74, v[152:155]
	s_waitcnt vmcnt(5)
	ds_write_b128 v78, v[156:159]
	s_waitcnt vmcnt(4)
	ds_write_b128 v82, v[160:163]
	s_waitcnt vmcnt(3)
	ds_write_b128 v86, v[164:167]
	s_waitcnt vmcnt(2)
	ds_write_b128 v90, v[168:171]
	s_waitcnt vmcnt(1)
	ds_write_b128 v94, v[172:175]
	s_waitcnt vmcnt(0)
	ds_write_b128 v98, v[176:179]
	s_waitcnt lgkmcnt(0)
	s_barrier

; DEV f32x4 mfma16(bf16x8 a, bf16x8 b, f32x4 c) { return __builtin_amdgcn_mfma_f32_16x16x32_bf16(a, b, c, 0, 0, 0); }
; DEV void peer_top16(const bf16_t* __restrict__ pq, const bf16_t* sk  , float (&l)[16]) {
;     ...
; #pragma unroll 1
;   for (int ks = 0; ks < 4; ks++) {
;     const bf16x8 bqk = *(const bf16x8*)(pq + ks * 32 + quad * 8);
; #pragma unroll
;     for (int nt = 0; nt < 8; nt++) {
;       bf16x8 ak = *(const bf16x8*)(sk + (nt * 16 + l15) * 144 + ks * 32 + quad * 8);
;       acc[nt] = mfma16(ak, bqk, acc[nt]);
;     }
;   }
.LBB0_168:
	global_load_dwordx4 v[148:151], v[102:103], off
	global_load_dwordx4 v[152:155], v[102:103], off offset:64
	global_load_dwordx4 v[156:159], v[102:103], off offset:128
	global_load_dwordx4 v[160:163], v[102:103], off offset:192
	ds_read_b128 v[164:167], v39
	ds_read_b128 v[168:171], v39 offset:4608
	ds_read_b128 v[172:175], v39 offset:9216
	ds_read_b128 v[176:179], v39 offset:13824
	ds_read_b128 v[180:183], v39 offset:18432
	ds_read_b128 v[184:187], v39 offset:23040
	ds_read_b128 v[188:191], v39 offset:27648
	ds_read_b128 v[108:111], v39 offset:32256
	s_waitcnt vmcnt(3) lgkmcnt(7)
	v_mfma_f32_16x16x32_bf16 v[30:33], v[164:167], v[148:151], v[30:33]
	ds_read_b128 v[164:167], v39 offset:64
	s_waitcnt lgkmcnt(7)
	v_mfma_f32_16x16x32_bf16 v[22:25], v[168:171], v[148:151], v[22:25]
	ds_read_b128 v[168:171], v39 offset:4672
	s_waitcnt lgkmcnt(7)
	v_mfma_f32_16x16x32_bf16 v[14:17], v[172:175], v[148:151], v[14:17]
	ds_read_b128 v[172:175], v39 offset:9280
	s_waitcnt lgkmcnt(7)
	v_mfma_f32_16x16x32_bf16 v[6:9], v[176:179], v[148:151], v[6:9]
	ds_read_b128 v[176:179], v39 offset:13888
	s_waitcnt lgkmcnt(7)
	v_mfma_f32_16x16x32_bf16 v[26:29], v[180:183], v[148:151], v[26:29]
	ds_read_b128 v[180:183], v39 offset:18496
	s_waitcnt lgkmcnt(7)
	v_mfma_f32_16x16x32_bf16 v[18:21], v[184:187], v[148:151], v[18:21]
	ds_read_b128 v[184:187], v39 offset:23104
	s_waitcnt lgkmcnt(7)
	v_mfma_f32_16x16x32_bf16 v[10:13], v[188:191], v[148:151], v[10:13]
	ds_read_b128 v[188:191], v39 offset:27712
	s_waitcnt lgkmcnt(7)
	v_mfma_f32_16x16x32_bf16 v[2:5], v[108:111], v[148:151], v[2:5]
	ds_read_b128 v[108:111], v39 offset:32320
	global_load_dwordx4 v[148:151], v[102:103], off offset:256
	s_waitcnt vmcnt(3) lgkmcnt(7)
	v_mfma_f32_16x16x32_bf16 v[30:33], v[164:167], v[152:155], v[30:33]
	ds_read_b128 v[164:167], v39 offset:128
	s_waitcnt lgkmcnt(7)
	v_mfma_f32_16x16x32_bf16 v[22:25], v[168:171], v[152:155], v[22:25]
	ds_read_b128 v[168:171], v39 offset:4736
	s_waitcnt lgkmcnt(7)
	v_mfma_f32_16x16x32_bf16 v[14:17], v[172:175], v[152:155], v[14:17]
	ds_read_b128 v[172:175], v39 offset:9344
	s_waitcnt lgkmcnt(7)
	v_mfma_f32_16x16x32_bf16 v[6:9], v[176:179], v[152:155], v[6:9]
	ds_read_b128 v[176:179], v39 offset:13952
	s_waitcnt lgkmcnt(7)
	v_mfma_f32_16x16x32_bf16 v[26:29], v[180:183], v[152:155], v[26:29]
	ds_read_b128 v[180:183], v39 offset:18560
	s_waitcnt lgkmcnt(7)
	v_mfma_f32_16x16x32_bf16 v[18:21], v[184:187], v[152:155], v[18:21]
	ds_read_b128 v[184:187], v39 offset:23168
	s_waitcnt lgkmcnt(7)
	v_mfma_f32_16x16x32_bf16 v[10:13], v[188:191], v[152:155], v[10:13]
	ds_read_b128 v[188:191], v39 offset:27776
	s_waitcnt lgkmcnt(7)
	v_mfma_f32_16x16x32_bf16 v[2:5], v[108:111], v[152:155], v[2:5]
	ds_read_b128 v[108:111], v39 offset:32384
	global_load_dwordx4 v[152:155], v[102:103], off offset:320
	s_waitcnt vmcnt(3) lgkmcnt(7)
	v_mfma_f32_16x16x32_bf16 v[30:33], v[164:167], v[156:159], v[30:33]
	ds_read_b128 v[164:167], v39 offset:192
	s_waitcnt lgkmcnt(7)
	v_mfma_f32_16x16x32_bf16 v[22:25], v[168:171], v[156:159], v[22:25]
	ds_read_b128 v[168:171], v39 offset:4800
	s_waitcnt lgkmcnt(7)
	v_mfma_f32_16x16x32_bf16 v[14:17], v[172:175], v[156:159], v[14:17]
	ds_read_b128 v[172:175], v39 offset:9408
	s_waitcnt lgkmcnt(7)
	v_mfma_f32_16x16x32_bf16 v[6:9], v[176:179], v[156:159], v[6:9]
	ds_read_b128 v[176:179], v39 offset:14016
	s_waitcnt lgkmcnt(7)
	v_mfma_f32_16x16x32_bf16 v[26:29], v[180:183], v[156:159], v[26:29]
	ds_read_b128 v[180:183], v39 offset:18624
	s_waitcnt lgkmcnt(7)
	v_mfma_f32_16x16x32_bf16 v[18:21], v[184:187], v[156:159], v[18:21]
	ds_read_b128 v[184:187], v39 offset:23232
	s_waitcnt lgkmcnt(7)
	v_mfma_f32_16x16x32_bf16 v[10:13], v[188:191], v[156:159], v[10:13]
	ds_read_b128 v[188:191], v39 offset:27840
	s_waitcnt lgkmcnt(7)
	v_mfma_f32_16x16x32_bf16 v[2:5], v[108:111], v[156:159], v[2:5]
	ds_read_b128 v[108:111], v39 offset:32448
	global_load_dwordx4 v[156:159], v[102:103], off offset:384
	s_waitcnt vmcnt(3) lgkmcnt(7)
	v_mfma_f32_16x16x32_bf16 v[30:33], v[164:167], v[160:163], v[30:33]
	s_waitcnt lgkmcnt(6)
	v_mfma_f32_16x16x32_bf16 v[22:25], v[168:171], v[160:163], v[22:25]
	s_waitcnt lgkmcnt(5)
	v_mfma_f32_16x16x32_bf16 v[14:17], v[172:175], v[160:163], v[14:17]
	s_waitcnt lgkmcnt(4)
	v_mfma_f32_16x16x32_bf16 v[6:9], v[176:179], v[160:163], v[6:9]
	s_waitcnt lgkmcnt(3)
	v_mfma_f32_16x16x32_bf16 v[26:29], v[180:183], v[160:163], v[26:29]
	s_waitcnt lgkmcnt(2)
	v_mfma_f32_16x16x32_bf16 v[18:21], v[184:187], v[160:163], v[18:21]
	s_waitcnt lgkmcnt(1)
	v_mfma_f32_16x16x32_bf16 v[10:13], v[188:191], v[160:163], v[10:13]
	s_waitcnt lgkmcnt(0)
; DEV f32x4 mfma16(bf16x8 a, bf16x8 b, f32x4 c) { return __builtin_amdgcn_mfma_f32_16x16x32_bf16(a, b, c, 0, 0, 0); }
; DEV void peer_top16(const bf16_t* __restrict__ pq, const bf16_t* sk  , float (&l)[16]) {
;     ...
;     const bf16x8 bqk = *(const bf16x8*)(pq + ks * 32 + quad * 8);
; #pragma unroll
;     for (int nt = 0; nt < 8; nt++) {
;       bf16x8 ak = *(const bf16x8*)(sk + (nt * 16 + l15) * 144 + ks * 32 + quad * 8);
;       acc[nt] = mfma16(ak, bqk, acc[nt]);
;     }
;   }
;   float hi[16];
; #pragma unroll
;   for (int nt = 0; nt < 4; nt++)
; #pragma unroll
;     for (int r = 0; r < 4; r++) {
;       l[nt * 4 + r] = __uint_as_float((__float_as_uint(acc[nt][r]) & ~127u) | (unsigned)(nt * 16 + quad * 4 + r));
;       hi[nt * 4 + r] = __uint_as_float((__float_as_uint(acc[nt + 4][r]) & ~127u) | (unsigned)((nt + 4) * 16 + quad * 4 + r));
;     }
;   sort16_desc(l);
	v_mfma_f32_16x16x32_bf16 v[2:5], v[108:111], v[160:163], v[2:5]
	global_load_dwordx4 v[160:163], v[102:103], off offset:448
	s_movk_i32 s0, 0x100
	v_lshlrev_b32_e32 v0, 2, v0
	s_movk_i32 s0, 0xff80
	v_and_or_b32 v30, v30, s0, v0
	v_and_b32_e32 v27, 0xffffff80, v27
	s_movk_i32 s0, 0x41
	v_or3_b32 v27, v0, v27, s0
	v_and_b32_e32 v28, 0xffffff80, v28
	s_movk_i32 s0, 0x42
	v_or3_b32 v28, v0, v28, s0
	v_and_b32_e32 v29, 0xffffff80, v29
	s_movk_i32 s0, 0x43
	v_or3_b32 v29, v0, v29, s0
	v_and_b32_e32 v18, 0xffffff80, v18
	s_movk_i32 s0, 0x50
	v_or3_b32 v18, v0, v18, s0
	v_and_b32_e32 v19, 0xffffff80, v19
	s_movk_i32 s0, 0x51
	v_or3_b32 v19, v0, v19, s0
	v_and_b32_e32 v20, 0xffffff80, v20
	s_movk_i32 s0, 0x52
	v_or3_b32 v20, v0, v20, s0
	v_and_b32_e32 v21, 0xffffff80, v21
	s_movk_i32 s0, 0x53
	v_or3_b32 v21, v0, v21, s0
	v_and_b32_e32 v10, 0xffffff80, v10
	s_movk_i32 s0, 0x60
	v_or3_b32 v10, v0, v10, s0
	v_and_b32_e32 v11, 0xffffff80, v11
	s_movk_i32 s0, 0x61
	v_or3_b32 v11, v0, v11, s0
	v_and_b32_e32 v12, 0xffffff80, v12
	s_movk_i32 s0, 0x62
	v_or3_b32 v12, v0, v12, s0
	v_and_b32_e32 v13, 0xffffff80, v13
	s_movk_i32 s0, 0x63
	v_or3_b32 v13, v0, v13, s0
	v_and_b32_e32 v2, 0xffffff80, v2
	s_movk_i32 s0, 0x70
	v_or3_b32 v2, v0, v2, s0
	v_and_b32_e32 v3, 0xffffff80, v3
	s_movk_i32 s0, 0x71
	v_and_b32_e32 v26, 0xffffff80, v26
	v_and_b32_e32 v31, 0xffffff80, v31
	v_or3_b32 v3, v0, v3, s0
	v_and_b32_e32 v4, 0xffffff80, v4
	s_movk_i32 s0, 0x72
	v_or3_b32 v26, v0, v26, 64
	v_or3_b32 v31, v0, v31, 1
	v_and_b32_e32 v32, 0xffffff80, v32
	v_and_b32_e32 v33, 0xffffff80, v33
	v_and_b32_e32 v22, 0xffffff80, v22
	v_and_b32_e32 v23, 0xffffff80, v23
	v_and_b32_e32 v24, 0xffffff80, v24
	v_and_b32_e32 v25, 0xffffff80, v25
	v_and_b32_e32 v14, 0xffffff80, v14
	v_and_b32_e32 v15, 0xffffff80, v15
	v_and_b32_e32 v16, 0xffffff80, v16
	v_and_b32_e32 v17, 0xffffff80, v17
	v_and_b32_e32 v6, 0xffffff80, v6
	v_and_b32_e32 v7, 0xffffff80, v7
	v_and_b32_e32 v8, 0xffffff80, v8
	v_or3_b32 v4, v0, v4, s0
	v_and_b32_e32 v9, 0xffffff80, v9
	v_and_b32_e32 v5, 0xffffff80, v5
	s_movk_i32 s0, 0x73
	v_or3_b32 v32, v0, v32, 2
	v_or3_b32 v33, v0, v33, 3
	v_or3_b32 v22, v0, v22, 16
	v_or3_b32 v23, v0, v23, 17
	v_or3_b32 v24, v0, v24, 18
	v_or3_b32 v25, v0, v25, 19
	v_or3_b32 v14, v0, v14, 32
	v_or3_b32 v15, v0, v15, 33
	v_or3_b32 v16, v0, v16, 34
	v_or3_b32 v17, v0, v17, 35
	v_or3_b32 v6, v0, v6, 48
	v_or3_b32 v7, v0, v7, 49
	v_or3_b32 v8, v0, v8, 50
	v_or3_b32 v9, v0, v9, 51
	v_or3_b32 v0, v0, v5, s0
	v_max_f32_e32 v5, v31, v31
	v_max_f32_e32 v31, v30, v5
	v_min_f32_e32 v5, v30, v5
	v_max_f32_e32 v30, v32, v32
	v_max_f32_e32 v32, v33, v33
	v_max_f32_e32 v67, v26, v27
	v_min_f32_e32 v26, v26, v27
	v_max_f32_e32 v27, v28, v28
	v_max_f32_e32 v28, v29, v29
	v_max_f32_e32 v33, v32, v30
	v_min_f32_e32 v30, v32, v30
	v_max_f32_e32 v32, v22, v23
	v_min_f32_e32 v22, v22, v23
	v_max_f32_e32 v23, v24, v24
	v_max_f32_e32 v24, v25, v25
	v_max_f32_e32 v29, v28, v27
	v_min_f32_e32 v27, v28, v27
	v_max_f32_e32 v28, v18, v19
	v_min_f32_e32 v18, v18, v19
	v_max_f32_e32 v19, v20, v20
	v_max_f32_e32 v20, v21, v21
	v_max_f32_e32 v25, v24, v23
	v_min_f32_e32 v23, v24, v23
	v_max_f32_e32 v24, v14, v15
	v_min_f32_e32 v14, v14, v15
	v_max_f32_e32 v15, v16, v16
	v_max_f32_e32 v16, v17, v17
	v_max_f32_e32 v21, v20, v19
	v_min_f32_e32 v19, v20, v19
	v_max_f32_e32 v20, v10, v11
	v_min_f32_e32 v10, v10, v11
	v_max_f32_e32 v11, v12, v12
	v_max_f32_e32 v12, v13, v13
	v_max_f32_e32 v17, v16, v15
	v_min_f32_e32 v15, v16, v15
	v_max_f32_e32 v16, v6, v7
	v_min_f32_e32 v6, v6, v7
	v_max_f32_e32 v7, v8, v8
	v_max_f32_e32 v8, v9, v9
	v_max_f32_e32 v13, v12, v11
	v_min_f32_e32 v11, v12, v11
	v_max_f32_e32 v12, v2, v3
	v_min_f32_e32 v2, v2, v3
	v_max_f32_e32 v3, v4, v4
	v_max_f32_e32 v9, v8, v7
	v_min_f32_e32 v7, v8, v7
	v_max_f32_e32 v4, v0, v3
	v_min_f32_e32 v0, v0, v3
	v_max_f32_e32 v8, v31, v30
	v_min_f32_e32 v30, v31, v30
	v_max_f32_e32 v31, v5, v33
	v_min_f32_e32 v5, v5, v33
	v_max_f32_e32 v33, v23, v32
	v_min_f32_e32 v23, v23, v32
	v_max_f32_e32 v32, v25, v22
	v_min_f32_e32 v22, v25, v22
	v_max_f32_e32 v25, v24, v15
	v_min_f32_e32 v15, v24, v15
	v_max_f32_e32 v24, v14, v17
	v_min_f32_e32 v14, v14, v17
	v_max_f32_e32 v17, v7, v16
	v_min_f32_e32 v7, v7, v16
	v_max_f32_e32 v16, v9, v6
	v_min_f32_e32 v6, v9, v6
	v_max_f32_e32 v3, v67, v27
	v_min_f32_e32 v27, v67, v27
	v_max_f32_e32 v67, v26, v29
	v_min_f32_e32 v26, v26, v29
	v_max_f32_e32 v29, v19, v28
	v_min_f32_e32 v19, v19, v28
	v_max_f32_e32 v28, v21, v18
	v_min_f32_e32 v18, v21, v18
	v_max_f32_e32 v21, v20, v11
	v_min_f32_e32 v11, v20, v11
	v_max_f32_e32 v20, v10, v13
	v_min_f32_e32 v10, v10, v13
	v_max_f32_e32 v13, v0, v12
	v_min_f32_e32 v0, v0, v12
	v_max_f32_e32 v12, v4, v2
	v_min_f32_e32 v2, v4, v2
	v_max_f32_e32 v9, v8, v31
	v_min_f32_e32 v8, v8, v31
	v_max_f32_e32 v31, v30, v5
	v_min_f32_e32 v5, v30, v5
	v_max_f32_e32 v30, v22, v23
	v_min_f32_e32 v22, v22, v23
	v_max_f32_e32 v23, v32, v33
	v_min_f32_e32 v32, v32, v33
	v_max_f32_e32 v33, v25, v24
	v_min_f32_e32 v24, v25, v24
	v_max_f32_e32 v25, v15, v14
	v_min_f32_e32 v14, v15, v14
	v_max_f32_e32 v15, v6, v7
	v_min_f32_e32 v6, v6, v7
	v_max_f32_e32 v7, v16, v17
	v_min_f32_e32 v16, v16, v17
	v_max_f32_e32 v4, v3, v67
	v_min_f32_e32 v3, v3, v67
	v_max_f32_e32 v67, v27, v26
	v_min_f32_e32 v26, v27, v26
	v_max_f32_e32 v27, v18, v19
	v_min_f32_e32 v18, v18, v19
	v_max_f32_e32 v19, v28, v29
	v_min_f32_e32 v28, v28, v29
	v_max_f32_e32 v29, v21, v20
	v_min_f32_e32 v20, v21, v20
	v_max_f32_e32 v21, v11, v10
	v_min_f32_e32 v10, v11, v10
	v_max_f32_e32 v11, v2, v0
	v_min_f32_e32 v0, v2, v0
	v_max_f32_e32 v2, v12, v13
; DEV void ce(float& a, float& b) { float hi = fmaxf(a, b), lo = fminf(a, b); a = hi; b = lo; }
; DEV void sort16_desc(float (&a)[16]) {
; #pragma unroll
;   for (int k = 2; k <= 16; k <<= 1)
; #pragma unroll
;     for (int j = k >> 1; j > 0; j >>= 1)
; #pragma unroll
;       for (int i = 0; i < 16; i++) {
;         const int p = i ^ j;
;         if (p > i) { if ((i & k) == 0) ce(a[i], a[p]); else ce(a[p], a[i]); }
;       }
; }
	v_min_f32_e32 v12, v12, v13
	v_max_f32_e32 v17, v9, v22
	v_min_f32_e32 v9, v9, v22
	v_max_f32_e32 v22, v8, v30
	v_min_f32_e32 v8, v8, v30
	v_max_f32_e32 v30, v31, v32
	v_min_f32_e32 v31, v31, v32
	v_max_f32_e32 v32, v5, v23
	v_min_f32_e32 v5, v5, v23
	v_max_f32_e32 v23, v6, v33
	v_min_f32_e32 v6, v6, v33
	v_max_f32_e32 v33, v15, v24
	v_min_f32_e32 v15, v15, v24
	v_max_f32_e32 v24, v16, v25
	v_min_f32_e32 v16, v16, v25
	v_max_f32_e32 v25, v7, v14
	v_min_f32_e32 v7, v7, v14
	v_max_f32_e32 v13, v4, v18
	v_min_f32_e32 v4, v4, v18
	v_max_f32_e32 v18, v3, v27
	v_min_f32_e32 v3, v3, v27
	v_max_f32_e32 v27, v67, v28
	v_min_f32_e32 v28, v67, v28
	v_max_f32_e32 v67, v26, v19
	v_min_f32_e32 v19, v26, v19
	v_max_f32_e32 v26, v0, v29
	v_min_f32_e32 v0, v0, v29
	v_max_f32_e32 v29, v11, v20
	v_min_f32_e32 v11, v11, v20
	v_max_f32_e32 v20, v12, v21
	v_min_f32_e32 v12, v12, v21
	v_max_f32_e32 v21, v2, v10
	v_min_f32_e32 v2, v2, v10
	v_max_f32_e32 v14, v17, v30
	v_min_f32_e32 v17, v17, v30
	v_max_f32_e32 v30, v22, v32
	v_min_f32_e32 v22, v22, v32
	v_max_f32_e32 v32, v9, v31
	v_min_f32_e32 v9, v9, v31
	v_max_f32_e32 v31, v8, v5
	v_min_f32_e32 v5, v8, v5
	v_max_f32_e32 v8, v16, v6
	v_min_f32_e32 v6, v16, v6
	v_max_f32_e32 v16, v7, v15
	v_min_f32_e32 v7, v7, v15
	v_max_f32_e32 v15, v24, v23
	v_min_f32_e32 v23, v24, v23
	v_max_f32_e32 v24, v25, v33
	v_min_f32_e32 v25, v25, v33
	v_max_f32_e32 v10, v13, v27
	v_min_f32_e32 v13, v13, v27
	v_max_f32_e32 v27, v18, v67
	v_min_f32_e32 v18, v18, v67
	v_max_f32_e32 v67, v4, v28
	v_min_f32_e32 v4, v4, v28
	v_max_f32_e32 v28, v3, v19
	v_min_f32_e32 v3, v3, v19
	v_max_f32_e32 v19, v12, v0
	v_min_f32_e32 v0, v12, v0
	v_max_f32_e32 v12, v2, v11
	v_min_f32_e32 v2, v2, v11
	v_max_f32_e32 v11, v20, v26
	v_min_f32_e32 v20, v20, v26
	v_max_f32_e32 v26, v21, v29
	v_min_f32_e32 v21, v21, v29
	v_max_f32_e32 v33, v14, v30
	v_min_f32_e32 v14, v14, v30
	v_max_f32_e32 v30, v17, v22
	v_min_f32_e32 v17, v17, v22
	v_max_f32_e32 v22, v32, v31
	v_min_f32_e32 v31, v32, v31
	v_max_f32_e32 v32, v9, v5
	v_min_f32_e32 v5, v9, v5
	v_max_f32_e32 v9, v7, v6
	v_min_f32_e32 v6, v7, v6
	v_max_f32_e32 v7, v16, v8
	v_min_f32_e32 v8, v16, v8
	v_max_f32_e32 v16, v25, v23
	v_min_f32_e32 v23, v25, v23
	v_max_f32_e32 v25, v24, v15
	v_min_f32_e32 v15, v24, v15
	v_max_f32_e32 v29, v10, v27
	v_min_f32_e32 v10, v10, v27
	v_max_f32_e32 v27, v13, v18
	v_min_f32_e32 v13, v13, v18
	v_max_f32_e32 v18, v67, v28
	v_min_f32_e32 v28, v67, v28
	v_max_f32_e32 v67, v4, v3
	v_min_f32_e32 v3, v4, v3
	v_max_f32_e32 v4, v2, v0
	v_min_f32_e32 v0, v2, v0
	v_max_f32_e32 v2, v12, v19
	v_min_f32_e32 v12, v12, v19
	v_max_f32_e32 v19, v21, v20
	v_min_f32_e32 v20, v21, v20
	v_max_f32_e32 v21, v26, v11
	v_min_f32_e32 v11, v26, v11
	v_max_f32_e32 v24, v33, v6
	v_min_f32_e32 v6, v33, v6
	v_max_f32_e32 v33, v14, v9
	v_min_f32_e32 v9, v14, v9
	v_max_f32_e32 v14, v30, v8
	v_min_f32_e32 v8, v30, v8
	v_max_f32_e32 v30, v17, v7
	v_min_f32_e32 v7, v17, v7
	v_max_f32_e32 v17, v22, v23
	v_min_f32_e32 v22, v22, v23
	v_max_f32_e32 v23, v31, v16
	v_min_f32_e32 v16, v31, v16
	v_max_f32_e32 v31, v32, v15
	v_min_f32_e32 v15, v32, v15
	v_max_f32_e32 v32, v5, v25
	v_min_f32_e32 v5, v5, v25
	v_max_f32_e32 v26, v29, v0
	v_min_f32_e32 v0, v29, v0
	v_max_f32_e32 v29, v10, v4
	v_min_f32_e32 v4, v10, v4
	v_max_f32_e32 v10, v27, v12
	v_min_f32_e32 v12, v27, v12
	v_max_f32_e32 v27, v13, v2
	v_min_f32_e32 v2, v13, v2
	v_max_f32_e32 v13, v18, v20
	v_min_f32_e32 v18, v18, v20
	v_max_f32_e32 v20, v28, v19
	v_min_f32_e32 v19, v28, v19
	v_max_f32_e32 v28, v67, v11
	v_min_f32_e32 v11, v67, v11
	v_max_f32_e32 v67, v3, v21
	v_min_f32_e32 v3, v3, v21
	v_max_f32_e32 v25, v24, v17
	v_min_f32_e32 v17, v24, v17
	v_max_f32_e32 v24, v33, v23
	v_min_f32_e32 v23, v33, v23
	v_max_f32_e32 v33, v14, v31
	v_min_f32_e32 v14, v14, v31
	v_max_f32_e32 v31, v30, v32
	v_min_f32_e32 v30, v30, v32
	v_max_f32_e32 v32, v6, v22
	v_min_f32_e32 v6, v6, v22
	v_max_f32_e32 v22, v9, v16
	v_min_f32_e32 v9, v9, v16
	v_max_f32_e32 v16, v8, v15
	v_min_f32_e32 v8, v8, v15
	v_max_f32_e32 v15, v7, v5
	v_min_f32_e32 v5, v7, v5
	v_max_f32_e32 v21, v26, v13
	v_min_f32_e32 v13, v26, v13
	v_max_f32_e32 v26, v29, v20
	v_min_f32_e32 v20, v29, v20
	v_max_f32_e32 v29, v10, v28
	v_min_f32_e32 v10, v10, v28
	v_max_f32_e32 v28, v27, v67
	v_min_f32_e32 v27, v27, v67
	v_max_f32_e32 v67, v0, v18
	v_min_f32_e32 v0, v0, v18
	v_max_f32_e32 v18, v4, v19
	v_min_f32_e32 v4, v4, v19
	v_max_f32_e32 v19, v12, v11
	v_min_f32_e32 v11, v12, v11
	v_max_f32_e32 v12, v2, v3
	v_min_f32_e32 v2, v2, v3
	v_max_f32_e32 v7, v25, v33
	v_min_f32_e32 v25, v25, v33
	v_max_f32_e32 v33, v24, v31
	v_min_f32_e32 v24, v24, v31
	v_max_f32_e32 v31, v17, v14
	v_min_f32_e32 v14, v17, v14
	v_max_f32_e32 v17, v23, v30
	v_min_f32_e32 v23, v23, v30
	v_max_f32_e32 v30, v32, v16
	v_min_f32_e32 v16, v32, v16
	v_max_f32_e32 v32, v22, v15
	v_min_f32_e32 v15, v22, v15
	v_max_f32_e32 v22, v6, v8
	v_min_f32_e32 v6, v6, v8
	v_max_f32_e32 v8, v9, v5
	v_min_f32_e32 v5, v9, v5
	v_max_f32_e32 v3, v21, v29
	v_min_f32_e32 v21, v21, v29
	v_max_f32_e32 v29, v26, v28
	v_min_f32_e32 v26, v26, v28
	v_max_f32_e32 v28, v13, v10
	v_min_f32_e32 v10, v13, v10
	v_max_f32_e32 v13, v20, v27
	v_min_f32_e32 v20, v20, v27
	v_max_f32_e32 v27, v67, v19
	v_min_f32_e32 v19, v67, v19
	v_max_f32_e32 v67, v18, v12
	v_min_f32_e32 v12, v18, v12
	v_max_f32_e32 v18, v0, v11
	v_min_f32_e32 v0, v0, v11
	v_max_f32_e32 v11, v4, v2
	v_min_f32_e32 v2, v4, v2
	v_min_f32_e32 v9, v7, v33
	v_min_f32_e32 v39, v25, v24
	v_min_f32_e32 v43, v31, v17
	v_min_f32_e32 v47, v14, v23
	v_min_f32_e32 v51, v30, v32
	v_min_f32_e32 v55, v16, v15
	v_min_f32_e32 v59, v22, v8
; DEV void merge_xor(float (&l)[16], int mask) {
;   float t[16];
; #pragma unroll
;   for (int i = 0; i < 16; i++) t[i] = __shfl_xor(l[15 - i], mask);
; #pragma unroll
;   for (int i = 0; i < 16; i++) l[i] = fmaxf(l[i], t[i]);
;   bitonic16(l);
; }
; DEV void peer_top16(const bf16_t* __restrict__ pq, const bf16_t* sk  , float (&l)[16]) {
;     ...
;   sort16_desc(l);
;   sort16_desc(hi);
; #pragma unroll
;   for (int i = 0; i < 16; i++) l[i] = fmaxf(l[i], hi[15 - i]);
;   bitonic16(l);
;   merge_xor(l, 16);
;   merge_xor(l, 32);
	v_min_f32_e32 v63, v6, v5
	v_min_f32_e32 v4, v3, v29
	v_min_f32_e32 v71, v21, v26
	v_min_f32_e32 v75, v28, v13
	v_min_f32_e32 v79, v10, v20
	v_min_f32_e32 v83, v27, v67
	v_min_f32_e32 v87, v19, v12
	v_min_f32_e32 v91, v18, v11
	v_min_f32_e32 v95, v0, v2
	v_max3_f32 v7, v7, v33, v95
	v_max3_f32 v0, v9, v0, v2
	v_max3_f32 v2, v25, v24, v91
	v_max3_f32 v9, v39, v18, v11
	v_max3_f32 v11, v31, v17, v87
	v_max3_f32 v12, v43, v19, v12
	v_max3_f32 v14, v14, v23, v83
	v_max3_f32 v17, v47, v27, v67
	v_max3_f32 v18, v30, v32, v79
	v_max3_f32 v10, v51, v10, v20
	v_max3_f32 v15, v16, v15, v75
	v_max3_f32 v13, v55, v28, v13
	v_max3_f32 v8, v22, v8, v71
	v_max3_f32 v16, v59, v21, v26
	v_max3_f32 v4, v6, v5, v4
	v_max3_f32 v3, v63, v3, v29
	v_max_f32_e32 v5, v7, v18
	v_min_f32_e32 v6, v7, v18
	v_max_f32_e32 v7, v0, v10
	v_min_f32_e32 v0, v0, v10
	v_max_f32_e32 v10, v2, v15
	v_min_f32_e32 v2, v2, v15
	v_max_f32_e32 v15, v9, v13
	v_min_f32_e32 v9, v9, v13
	v_max_f32_e32 v13, v11, v8
	v_min_f32_e32 v8, v11, v8
	v_max_f32_e32 v11, v12, v16
	v_min_f32_e32 v12, v12, v16
	v_max_f32_e32 v16, v14, v4
	v_min_f32_e32 v4, v14, v4
	v_max_f32_e32 v14, v17, v3
	v_min_f32_e32 v3, v17, v3
	v_max_f32_e32 v17, v5, v13
	v_min_f32_e32 v5, v5, v13
	v_max_f32_e32 v13, v7, v11
	v_min_f32_e32 v7, v7, v11
	v_max_f32_e32 v11, v10, v16
	v_min_f32_e32 v10, v10, v16
	v_max_f32_e32 v16, v15, v14
	v_min_f32_e32 v14, v15, v14
	v_max_f32_e32 v15, v6, v8
	v_min_f32_e32 v6, v6, v8
	v_max_f32_e32 v8, v0, v12
	v_min_f32_e32 v0, v0, v12
	v_max_f32_e32 v12, v2, v4
	v_min_f32_e32 v2, v2, v4
	v_max_f32_e32 v4, v9, v3
	v_min_f32_e32 v3, v9, v3
	v_max_f32_e32 v9, v17, v11
	v_min_f32_e32 v11, v17, v11
	v_max_f32_e32 v17, v13, v16
	v_min_f32_e32 v13, v13, v16
	v_max_f32_e32 v16, v5, v10
	v_min_f32_e32 v5, v5, v10
	v_max_f32_e32 v10, v7, v14
	v_min_f32_e32 v7, v7, v14
	v_max_f32_e32 v14, v15, v12
	v_min_f32_e32 v12, v15, v12
	v_max_f32_e32 v15, v8, v4
	v_min_f32_e32 v4, v8, v4
	v_max_f32_e32 v8, v6, v2
	v_min_f32_e32 v2, v6, v2
	v_max_f32_e32 v6, v0, v3
	v_min_f32_e32 v0, v0, v3
	v_max_f32_e32 v3, v9, v17
	v_min_f32_e32 v9, v9, v17
	v_max_f32_e32 v17, v11, v13
	v_min_f32_e32 v11, v11, v13
	v_max_f32_e32 v13, v16, v10
	v_min_f32_e32 v10, v16, v10
	v_max_f32_e32 v16, v5, v7
	v_min_f32_e32 v5, v5, v7
	v_max_f32_e32 v7, v14, v15
	v_min_f32_e32 v14, v14, v15
	v_max_f32_e32 v15, v12, v4
	v_min_f32_e32 v4, v12, v4
	v_max_f32_e32 v12, v8, v6
	v_min_f32_e32 v6, v8, v6
	v_max_f32_e32 v8, v2, v0
	v_min_f32_e32 v0, v2, v0
	v_mbcnt_hi_u32_b32 v2, -1, v215
	v_and_b32_e32 v19, 64, v2
	v_xor_b32_e32 v18, 16, v2
	v_add_u32_e32 v19, 64, v19
	v_cmp_lt_i32_e32 vcc, v18, v19
	s_add_u32 s14, s12, s14
	s_addc_u32 s15, s13, s15
	v_cndmask_b32_e32 v18, v2, v18, vcc
	v_lshlrev_b32_e32 v95, 2, v18
	ds_bpermute_b32 v18, v95, v0
	ds_bpermute_b32 v20, v95, v8
	ds_bpermute_b32 v21, v95, v6
	ds_bpermute_b32 v22, v95, v12
	ds_bpermute_b32 v23, v95, v4
	ds_bpermute_b32 v24, v95, v15
	s_waitcnt lgkmcnt(5)
	ds_bpermute_b32 v25, v95, v14
	ds_bpermute_b32 v39, v95, v3
	v_max_f32_e32 v3, v3, v18
	s_waitcnt lgkmcnt(6)
	ds_bpermute_b32 v26, v95, v7
	ds_bpermute_b32 v33, v95, v9
	v_max_f32_e32 v9, v9, v20
	s_waitcnt lgkmcnt(7)
	ds_bpermute_b32 v27, v95, v5
	ds_bpermute_b32 v32, v95, v17
	v_max_f32_e32 v17, v17, v21
	s_waitcnt lgkmcnt(8)
	ds_bpermute_b32 v28, v95, v16
	ds_bpermute_b32 v31, v95, v11
	v_max_f32_e32 v11, v11, v22
	s_waitcnt lgkmcnt(9)
	ds_bpermute_b32 v29, v95, v10
	ds_bpermute_b32 v30, v95, v13
	v_max_f32_e32 v13, v13, v23
	s_waitcnt lgkmcnt(10)
	v_max_f32_e32 v10, v10, v24
	s_waitcnt lgkmcnt(9)
	v_max_f32_e32 v16, v16, v25
	s_waitcnt lgkmcnt(7)
	v_max_f32_e32 v5, v5, v26
	s_waitcnt lgkmcnt(5)
	v_max_f32_e32 v7, v7, v27
	s_waitcnt lgkmcnt(3)
	v_max_f32_e32 v14, v14, v28
	s_waitcnt lgkmcnt(1)
	v_max_f32_e32 v15, v15, v29
	s_waitcnt lgkmcnt(0)
	v_max_f32_e32 v4, v4, v30
	v_max_f32_e32 v12, v12, v31
	v_max_f32_e32 v6, v6, v32
	v_max_f32_e32 v8, v8, v33
	v_max_f32_e32 v0, v0, v39
	v_max_f32_e32 v18, v3, v7
	v_min_f32_e32 v3, v3, v7
	v_max_f32_e32 v7, v9, v14
	v_min_f32_e32 v9, v9, v14
	v_max_f32_e32 v14, v17, v15
	v_min_f32_e32 v15, v17, v15
	v_max_f32_e32 v17, v11, v4
	v_min_f32_e32 v4, v11, v4
	v_max_f32_e32 v11, v13, v12
	v_min_f32_e32 v12, v13, v12
	v_max_f32_e32 v13, v10, v6
	v_min_f32_e32 v6, v10, v6
	v_max_f32_e32 v10, v16, v8
	v_min_f32_e32 v8, v16, v8
	v_max_f32_e32 v16, v5, v0
	v_min_f32_e32 v0, v5, v0
	v_max_f32_e32 v5, v18, v11
	v_min_f32_e32 v11, v18, v11
	v_max_f32_e32 v18, v7, v13
	v_min_f32_e32 v7, v7, v13
	v_max_f32_e32 v13, v14, v10
	v_min_f32_e32 v10, v14, v10
	v_max_f32_e32 v14, v17, v16
	v_min_f32_e32 v16, v17, v16
	v_max_f32_e32 v17, v3, v12
	v_min_f32_e32 v3, v3, v12
	v_max_f32_e32 v12, v9, v6
	v_min_f32_e32 v6, v9, v6
	v_max_f32_e32 v9, v15, v8
	v_min_f32_e32 v8, v15, v8
	v_max_f32_e32 v15, v4, v0
	v_min_f32_e32 v0, v4, v0
	v_max_f32_e32 v4, v5, v13
	v_min_f32_e32 v5, v5, v13
	v_max_f32_e32 v13, v18, v14
	v_min_f32_e32 v14, v18, v14
	v_max_f32_e32 v18, v11, v10
	v_min_f32_e32 v10, v11, v10
	v_max_f32_e32 v11, v7, v16
	v_min_f32_e32 v7, v7, v16
	v_max_f32_e32 v16, v17, v9
	v_min_f32_e32 v9, v17, v9
	v_max_f32_e32 v17, v12, v15
	v_min_f32_e32 v12, v12, v15
	v_max_f32_e32 v15, v3, v8
	v_min_f32_e32 v3, v3, v8
	v_max_f32_e32 v8, v6, v0
	v_min_f32_e32 v0, v6, v0
	v_max_f32_e32 v43, v3, v0
	v_min_f32_e32 v39, v3, v0
	v_xor_b32_e32 v0, 32, v2
	v_cmp_lt_i32_e32 vcc, v0, v19
	v_max_f32_e32 v109, v4, v13
	v_min_f32_e32 v107, v4, v13
	v_cndmask_b32_e32 v0, v2, v0, vcc
	v_max_f32_e32 v105, v5, v14
	v_min_f32_e32 v103, v5, v14
	v_max_f32_e32 v87, v18, v11
	v_min_f32_e32 v79, v18, v11
	v_max_f32_e32 v75, v10, v7
; DEV int tidx() { int t = threadIdx.x; asm volatile("" : "+v"(t)); return t; }
; DEV f32x4 mfma16(bf16x8 a, bf16x8 b, f32x4 c) { return __builtin_amdgcn_mfma_f32_16x16x32_bf16(a, b, c, 0, 0, 0); }
; DEV void merge_xor(float (&l)[16], int mask) {
;   float t[16];
; #pragma unroll
;   for (int i = 0; i < 16; i++) t[i] = __shfl_xor(l[15 - i], mask);
; #pragma unroll
;   for (int i = 0; i < 16; i++) l[i] = fmaxf(l[i], t[i]);
;   bitonic16(l);
; }
; DEV void peer_top16(const bf16_t* __restrict__ pq, const bf16_t* sk  , float (&l)[16]) {
;   const int lane = tidx() & 63, l15 = lane & 15, quad = lane >> 4;
;   f32x4 acc[8];
; #pragma unroll
;   for (int nt = 0; nt < 8; nt++) acc[nt] = (f32x4){0.f, 0.f, 0.f, 0.f};
; #pragma unroll 1
;   for (int ks = 0; ks < 4; ks++) {
;     const bf16x8 bqk = *(const bf16x8*)(pq + ks * 32 + quad * 8);
; #pragma unroll
;     for (int nt = 0; nt < 8; nt++) {
;       bf16x8 ak = *(const bf16x8*)(sk + (nt * 16 + l15) * 144 + ks * 32 + quad * 8);
;       acc[nt] = mfma16(ak, bqk, acc[nt]);
;     }
;   }
	v_min_f32_e32 v71, v10, v7
	v_max_f32_e32 v67, v16, v17
	v_min_f32_e32 v63, v16, v17
	v_max_f32_e32 v59, v9, v12
	v_min_f32_e32 v55, v9, v12
	v_max_f32_e32 v51, v15, v8
	v_min_f32_e32 v47, v15, v8
	v_lshlrev_b32_e32 v99, 2, v0
	v_mov_b32_e32 v0, v195
	ds_bpermute_b32 v121, v99, v39
	ds_bpermute_b32 v120, v99, v43
	ds_bpermute_b32 v119, v99, v47
	ds_bpermute_b32 v118, v99, v51
	ds_bpermute_b32 v116, v99, v55
	ds_bpermute_b32 v115, v99, v59
	ds_bpermute_b32 v114, v99, v63
	ds_bpermute_b32 v113, v99, v67
	ds_bpermute_b32 v112, v99, v71
	ds_bpermute_b32 v111, v99, v75
	ds_bpermute_b32 v110, v99, v79
	ds_bpermute_b32 v108, v99, v87
	ds_bpermute_b32 v106, v99, v103
	ds_bpermute_b32 v104, v99, v105
	ds_bpermute_b32 v91, v99, v107
	ds_bpermute_b32 v83, v99, v109
	s_mov_b32 s0, 0
	v_bfe_u32 v102, v0, 4, 2
	v_and_b32_e32 v2, 15, v0
	v_lshlrev_b32_e32 v0, 4, v102
	v_mad_u32_u24 v122, v2, s20, v0
	v_lshl_add_u64 v[2:3], v[100:101], 0, v[0:1]
	v_lshl_add_u64 v[100:101], s[14:15], 0, v[2:3]
	v_mov_b32_e32 v2, 0
	v_mov_b32_e32 v3, v2
	v_mov_b32_e32 v4, v2
	v_mov_b32_e32 v5, v2
	v_mov_b32_e32 v10, v2
	v_mov_b32_e32 v11, v2
	v_mov_b32_e32 v12, v2
	v_mov_b32_e32 v13, v2
	v_mov_b32_e32 v18, v2
	v_mov_b32_e32 v19, v2
	v_mov_b32_e32 v20, v2
	v_mov_b32_e32 v21, v2
	v_mov_b32_e32 v26, v2
	v_mov_b32_e32 v27, v2
	v_mov_b32_e32 v28, v2
	v_mov_b32_e32 v29, v2
	v_mov_b32_e32 v6, v2
	v_mov_b32_e32 v7, v2
	v_mov_b32_e32 v8, v2
	v_mov_b32_e32 v9, v2
	v_mov_b32_e32 v14, v2
	v_mov_b32_e32 v15, v2
	v_mov_b32_e32 v16, v2
	v_mov_b32_e32 v17, v2
	v_mov_b32_e32 v22, v2
	v_mov_b32_e32 v23, v2
	v_mov_b32_e32 v24, v2
	v_mov_b32_e32 v25, v2
	v_mov_b32_e32 v30, v2
	v_mov_b32_e32 v31, v2
	v_mov_b32_e32 v32, v2
	v_mov_b32_e32 v33, v2
.LBB0_170:
	v_add_u32_e32 v139, 0x10e00, v122
	ds_read_b128 v[164:167], v122 offset:36864
	ds_read_b128 v[168:171], v122 offset:41472
	ds_read_b128 v[172:175], v122 offset:46080
	ds_read_b128 v[176:179], v122 offset:50688
	ds_read_b128 v[180:183], v122 offset:55296
	ds_read_b128 v[184:187], v122 offset:59904
	ds_read_b128 v[188:191], v122 offset:64512
	ds_read_b128 v[128:131], v139
	s_waitcnt vmcnt(3) lgkmcnt(7)
	v_mfma_f32_16x16x32_bf16 v[30:33], v[164:167], v[148:151], v[30:33]
	ds_read_b128 v[164:167], v122 offset:36928
	s_waitcnt lgkmcnt(7)
	v_mfma_f32_16x16x32_bf16 v[22:25], v[168:171], v[148:151], v[22:25]
	ds_read_b128 v[168:171], v122 offset:41536
	s_waitcnt lgkmcnt(7)
	v_mfma_f32_16x16x32_bf16 v[14:17], v[172:175], v[148:151], v[14:17]
	ds_read_b128 v[172:175], v122 offset:46144
	s_waitcnt lgkmcnt(7)
	v_mfma_f32_16x16x32_bf16 v[6:9], v[176:179], v[148:151], v[6:9]
	ds_read_b128 v[176:179], v122 offset:50752
	s_waitcnt lgkmcnt(7)
	v_mfma_f32_16x16x32_bf16 v[26:29], v[180:183], v[148:151], v[26:29]
	ds_read_b128 v[180:183], v122 offset:55360
	s_waitcnt lgkmcnt(7)
	v_mfma_f32_16x16x32_bf16 v[18:21], v[184:187], v[148:151], v[18:21]
	ds_read_b128 v[184:187], v122 offset:59968
	s_waitcnt lgkmcnt(7)
	v_mfma_f32_16x16x32_bf16 v[10:13], v[188:191], v[148:151], v[10:13]
	ds_read_b128 v[188:191], v122 offset:64576
	s_waitcnt lgkmcnt(7)
	v_mfma_f32_16x16x32_bf16 v[2:5], v[128:131], v[148:151], v[2:5]
	ds_read_b128 v[128:131], v139 offset:64
	s_waitcnt vmcnt(2) lgkmcnt(7)
	v_mfma_f32_16x16x32_bf16 v[30:33], v[164:167], v[152:155], v[30:33]
	ds_read_b128 v[164:167], v122 offset:36992
	s_waitcnt lgkmcnt(7)
	v_mfma_f32_16x16x32_bf16 v[22:25], v[168:171], v[152:155], v[22:25]
	ds_read_b128 v[168:171], v122 offset:41600
	s_waitcnt lgkmcnt(7)
	v_mfma_f32_16x16x32_bf16 v[14:17], v[172:175], v[152:155], v[14:17]
	ds_read_b128 v[172:175], v122 offset:46208
	s_waitcnt lgkmcnt(7)
	v_mfma_f32_16x16x32_bf16 v[6:9], v[176:179], v[152:155], v[6:9]
	ds_read_b128 v[176:179], v122 offset:50816
	s_waitcnt lgkmcnt(7)
	v_mfma_f32_16x16x32_bf16 v[26:29], v[180:183], v[152:155], v[26:29]
	ds_read_b128 v[180:183], v122 offset:55424
	s_waitcnt lgkmcnt(7)
	v_mfma_f32_16x16x32_bf16 v[18:21], v[184:187], v[152:155], v[18:21]
	ds_read_b128 v[184:187], v122 offset:60032
	s_waitcnt lgkmcnt(7)
	v_mfma_f32_16x16x32_bf16 v[10:13], v[188:191], v[152:155], v[10:13]
	ds_read_b128 v[188:191], v122 offset:64640
	s_waitcnt lgkmcnt(7)
	v_mfma_f32_16x16x32_bf16 v[2:5], v[128:131], v[152:155], v[2:5]
	ds_read_b128 v[128:131], v139 offset:128
	s_waitcnt vmcnt(1) lgkmcnt(7)
	v_mfma_f32_16x16x32_bf16 v[30:33], v[164:167], v[156:159], v[30:33]
	ds_read_b128 v[164:167], v122 offset:37056
	s_waitcnt lgkmcnt(7)
	v_mfma_f32_16x16x32_bf16 v[22:25], v[168:171], v[156:159], v[22:25]
	ds_read_b128 v[168:171], v122 offset:41664
	s_waitcnt lgkmcnt(7)
	v_mfma_f32_16x16x32_bf16 v[14:17], v[172:175], v[156:159], v[14:17]
	ds_read_b128 v[172:175], v122 offset:46272
	s_waitcnt lgkmcnt(7)
	v_mfma_f32_16x16x32_bf16 v[6:9], v[176:179], v[156:159], v[6:9]
	ds_read_b128 v[176:179], v122 offset:50880
	s_waitcnt lgkmcnt(7)
	v_mfma_f32_16x16x32_bf16 v[26:29], v[180:183], v[156:159], v[26:29]
	ds_read_b128 v[180:183], v122 offset:55488
	s_waitcnt lgkmcnt(7)
	v_mfma_f32_16x16x32_bf16 v[18:21], v[184:187], v[156:159], v[18:21]
	ds_read_b128 v[184:187], v122 offset:60096
	s_waitcnt lgkmcnt(7)
	v_mfma_f32_16x16x32_bf16 v[10:13], v[188:191], v[156:159], v[10:13]
	ds_read_b128 v[188:191], v122 offset:64704
	s_waitcnt lgkmcnt(7)
	v_mfma_f32_16x16x32_bf16 v[2:5], v[128:131], v[156:159], v[2:5]
	ds_read_b128 v[128:131], v139 offset:192
	s_waitcnt vmcnt(0) lgkmcnt(7)
	v_mfma_f32_16x16x32_bf16 v[30:33], v[164:167], v[160:163], v[30:33]
	s_waitcnt lgkmcnt(6)
	v_mfma_f32_16x16x32_bf16 v[22:25], v[168:171], v[160:163], v[22:25]
	s_waitcnt lgkmcnt(5)
	v_mfma_f32_16x16x32_bf16 v[14:17], v[172:175], v[160:163], v[14:17]
	s_waitcnt lgkmcnt(4)
; DEV int tidx() { int t = threadIdx.x; asm volatile("" : "+v"(t)); return t; }
; DEV f32x4 mfma16(bf16x8 a, bf16x8 b, f32x4 c) { return __builtin_amdgcn_mfma_f32_16x16x32_bf16(a, b, c, 0, 0, 0); }
; DEV void merge_xor(float (&l)[16], int mask) {
;   float t[16];
; #pragma unroll
;   for (int i = 0; i < 16; i++) t[i] = __shfl_xor(l[15 - i], mask);
; #pragma unroll
;   for (int i = 0; i < 16; i++) l[i] = fmaxf(l[i], t[i]);
;   bitonic16(l);
; }
; DEV void peer_top16(const bf16_t* __restrict__ pq, const bf16_t* sk  , float (&l)[16]) {
;   const int lane = tidx() & 63, l15 = lane & 15, quad = lane >> 4;
;   f32x4 acc[8];
; #pragma unroll
;   for (int nt = 0; nt < 8; nt++) acc[nt] = (f32x4){0.f, 0.f, 0.f, 0.f};
; #pragma unroll 1
;   for (int ks = 0; ks < 4; ks++) {
;     const bf16x8 bqk = *(const bf16x8*)(pq + ks * 32 + quad * 8);
; #pragma unroll
;     for (int nt = 0; nt < 8; nt++) {
;       bf16x8 ak = *(const bf16x8*)(sk + (nt * 16 + l15) * 144 + ks * 32 + quad * 8);
;       acc[nt] = mfma16(ak, bqk, acc[nt]);
;     }
;   }
;   float hi[16];
; #pragma unroll
;   for (int nt = 0; nt < 4; nt++)
; #pragma unroll
;     for (int r = 0; r < 4; r++) {
;       l[nt * 4 + r] = __uint_as_float((__float_as_uint(acc[nt][r]) & ~127u) | (unsigned)(nt * 16 + quad * 4 + r));
;       hi[nt * 4 + r] = __uint_as_float((__float_as_uint(acc[nt + 4][r]) & ~127u) | (unsigned)((nt + 4) * 16 + quad * 4 + r));
;     }
;   sort16_desc(l);
	v_mfma_f32_16x16x32_bf16 v[6:9], v[176:179], v[160:163], v[6:9]
	s_waitcnt lgkmcnt(3)
	v_mfma_f32_16x16x32_bf16 v[26:29], v[180:183], v[160:163], v[26:29]
	s_waitcnt lgkmcnt(2)
	v_mfma_f32_16x16x32_bf16 v[18:21], v[184:187], v[160:163], v[18:21]
	s_waitcnt lgkmcnt(1)
	v_mfma_f32_16x16x32_bf16 v[10:13], v[188:191], v[160:163], v[10:13]
	s_waitcnt lgkmcnt(0)
	v_mfma_f32_16x16x32_bf16 v[2:5], v[128:131], v[160:163], v[2:5]
	s_movk_i32 s0, 0x100
	v_max_f32_e32 v0, v109, v121
	v_max_f32_e32 v100, v107, v120
	v_max_f32_e32 v101, v105, v119
	v_max_f32_e32 v103, v103, v118
	v_max_f32_e32 v87, v87, v116
	v_max_f32_e32 v79, v79, v115
	v_max_f32_e32 v75, v75, v114
	v_max_f32_e32 v71, v71, v113
	v_max_f32_e32 v67, v67, v112
	v_max_f32_e32 v63, v63, v111
	v_max_f32_e32 v59, v59, v110
	v_max_f32_e32 v55, v55, v108
	v_max_f32_e32 v51, v51, v106
	v_max_f32_e32 v47, v47, v104
	v_max_f32_e32 v43, v43, v91
	v_max_f32_e32 v39, v39, v83
	v_max_f32_e32 v83, v0, v67
	v_min_f32_e32 v0, v0, v67
	v_max_f32_e32 v67, v100, v63
	v_min_f32_e32 v63, v100, v63
	v_max_f32_e32 v91, v101, v59
	v_min_f32_e32 v59, v101, v59
	v_max_f32_e32 v100, v103, v55
	v_min_f32_e32 v55, v103, v55
	v_max_f32_e32 v101, v87, v51
	v_min_f32_e32 v51, v87, v51
	v_max_f32_e32 v87, v79, v47
	v_min_f32_e32 v47, v79, v47
	v_max_f32_e32 v79, v75, v43
	v_min_f32_e32 v43, v75, v43
	v_max_f32_e32 v75, v71, v39
	v_min_f32_e32 v39, v71, v39
	v_max_f32_e32 v71, v83, v101
	v_min_f32_e32 v101, v83, v101
	v_max_f32_e32 v103, v67, v87
	v_min_f32_e32 v67, v67, v87
	v_max_f32_e32 v87, v91, v79
	v_min_f32_e32 v79, v91, v79
	v_max_f32_e32 v91, v100, v75
	v_min_f32_e32 v75, v100, v75
	v_max_f32_e32 v100, v0, v51
	v_min_f32_e32 v0, v0, v51
	v_max_f32_e32 v51, v63, v47
	v_max_f32_e32 v105, v59, v43
	v_min_f32_e32 v43, v59, v43
	v_max_f32_e32 v59, v55, v39
	v_min_f32_e32 v107, v101, v79
	v_min_f32_e32 v108, v67, v75
	v_min_f32_e32 v110, v51, v59
	v_max_f32_e32 v79, v101, v79
	v_max_f32_e32 v67, v67, v75
	v_max_f32_e32 v101, v100, v105
	v_max_f32_e32 v51, v51, v59
	v_min_f32_e32 v75, v79, v67
	v_min_f32_e32 v59, v101, v51
	v_max_f32_e32 v79, v79, v67
	v_max_f32_e32 v67, v101, v51
	v_lshlrev_b32_e32 v101, 2, v102
	s_movk_i32 s0, 0xff80
	v_and_or_b32 v30, v30, s0, v101
	v_and_b32_e32 v27, 0xffffff80, v27
	s_movk_i32 s0, 0x41
	v_or3_b32 v27, v101, v27, s0
	v_and_b32_e32 v28, 0xffffff80, v28
	s_movk_i32 s0, 0x42
	v_or3_b32 v28, v101, v28, s0
	v_and_b32_e32 v29, 0xffffff80, v29
	s_movk_i32 s0, 0x43
	v_or3_b32 v29, v101, v29, s0
	v_and_b32_e32 v18, 0xffffff80, v18
	s_movk_i32 s0, 0x50
	v_or3_b32 v18, v101, v18, s0
	v_and_b32_e32 v19, 0xffffff80, v19
	s_movk_i32 s0, 0x51
	v_or3_b32 v19, v101, v19, s0
	v_and_b32_e32 v20, 0xffffff80, v20
	s_movk_i32 s0, 0x52
	v_or3_b32 v20, v101, v20, s0
	v_and_b32_e32 v21, 0xffffff80, v21
	s_movk_i32 s0, 0x53
	v_or3_b32 v21, v101, v21, s0
	v_and_b32_e32 v10, 0xffffff80, v10
	s_movk_i32 s0, 0x60
	v_or3_b32 v10, v101, v10, s0
	v_and_b32_e32 v11, 0xffffff80, v11
	s_movk_i32 s0, 0x61
	v_or3_b32 v11, v101, v11, s0
	v_and_b32_e32 v12, 0xffffff80, v12
	s_movk_i32 s0, 0x62
	v_or3_b32 v12, v101, v12, s0
	v_and_b32_e32 v13, 0xffffff80, v13
	s_movk_i32 s0, 0x63
	v_or3_b32 v13, v101, v13, s0
	v_and_b32_e32 v2, 0xffffff80, v2
	s_movk_i32 s0, 0x70
	v_and_b32_e32 v26, 0xffffff80, v26
	v_and_b32_e32 v31, 0xffffff80, v31
	v_or3_b32 v2, v101, v2, s0
	v_and_b32_e32 v3, 0xffffff80, v3
	s_movk_i32 s0, 0x71
	v_or3_b32 v26, v101, v26, 64
	v_or3_b32 v31, v101, v31, 1
	v_and_b32_e32 v32, 0xffffff80, v32
	v_and_b32_e32 v33, 0xffffff80, v33
	v_and_b32_e32 v22, 0xffffff80, v22
	v_and_b32_e32 v23, 0xffffff80, v23
	v_or3_b32 v3, v101, v3, s0
	v_and_b32_e32 v4, 0xffffff80, v4
	s_movk_i32 s0, 0x72
	v_min_f32_e32 v39, v55, v39
	v_min_f32_e32 v55, v71, v87
	v_min_f32_e32 v106, v103, v91
	v_min_f32_e32 v109, v100, v105
	v_max_f32_e32 v71, v71, v87
	v_max_f32_e32 v87, v103, v91
	v_or3_b32 v32, v101, v32, 2
	v_or3_b32 v33, v101, v33, 3
	v_or3_b32 v22, v101, v22, 16
	v_or3_b32 v23, v101, v23, 17
	v_and_b32_e32 v24, 0xffffff80, v24
	v_and_b32_e32 v25, 0xffffff80, v25
	v_and_b32_e32 v14, 0xffffff80, v14
	v_and_b32_e32 v15, 0xffffff80, v15
	v_and_b32_e32 v16, 0xffffff80, v16
	v_and_b32_e32 v17, 0xffffff80, v17
	v_and_b32_e32 v6, 0xffffff80, v6
	v_and_b32_e32 v7, 0xffffff80, v7
	v_and_b32_e32 v8, 0xffffff80, v8
	v_or3_b32 v4, v101, v4, s0
	v_and_b32_e32 v9, 0xffffff80, v9
	v_and_b32_e32 v5, 0xffffff80, v5
	s_movk_i32 s0, 0x73
	v_min_f32_e32 v104, v63, v47
	v_min_f32_e32 v83, v55, v106
	v_min_f32_e32 v47, v109, v110
	v_min_f32_e32 v91, v71, v87
	v_max_f32_e32 v100, v71, v87
	v_max_f32_e32 v87, v55, v106
	v_max_f32_e32 v55, v109, v110
	v_or3_b32 v24, v101, v24, 18
	v_or3_b32 v25, v101, v25, 19
	v_or3_b32 v14, v101, v14, 32
	v_or3_b32 v15, v101, v15, 33
	v_or3_b32 v16, v101, v16, 34
	v_or3_b32 v17, v101, v17, 35
	v_or3_b32 v6, v101, v6, 48
	v_or3_b32 v7, v101, v7, 49
	v_or3_b32 v8, v101, v8, 50
	v_or3_b32 v9, v101, v9, 51
	v_or3_b32 v5, v101, v5, s0
	v_max_f32_e32 v101, v30, v31
	v_min_f32_e32 v30, v30, v31
	v_max_f32_e32 v31, v32, v32
	v_max_f32_e32 v32, v33, v33
	v_max_f32_e32 v109, v26, v27
	v_min_f32_e32 v26, v26, v27
	v_max_f32_e32 v27, v28, v28
	v_max_f32_e32 v28, v29, v29
	v_max_f32_e32 v33, v32, v31
	v_min_f32_e32 v31, v32, v31
	v_max_f32_e32 v32, v22, v23
	v_min_f32_e32 v22, v22, v23
	v_max_f32_e32 v23, v24, v24
	v_max_f32_e32 v24, v25, v25
	v_max_f32_e32 v29, v28, v27
	v_min_f32_e32 v27, v28, v27
	v_max_f32_e32 v28, v18, v19
	v_min_f32_e32 v18, v18, v19
	v_max_f32_e32 v19, v20, v20
	v_max_f32_e32 v20, v21, v21
	v_max_f32_e32 v25, v24, v23
	v_min_f32_e32 v23, v24, v23
	v_max_f32_e32 v24, v14, v15
	v_min_f32_e32 v14, v14, v15
; DEV void ce(float& a, float& b) { float hi = fmaxf(a, b), lo = fminf(a, b); a = hi; b = lo; }
; DEV void sort16_desc(float (&a)[16]) {
; #pragma unroll
;   for (int k = 2; k <= 16; k <<= 1)
; #pragma unroll
;     for (int j = k >> 1; j > 0; j >>= 1)
; #pragma unroll
;       for (int i = 0; i < 16; i++) {
;         const int p = i ^ j;
;         if (p > i) { if ((i & k) == 0) ce(a[i], a[p]); else ce(a[p], a[i]); }
;       }
; }
	v_max_f32_e32 v15, v16, v16
	v_max_f32_e32 v16, v17, v17
	v_max_f32_e32 v21, v20, v19
	v_min_f32_e32 v19, v20, v19
	v_max_f32_e32 v20, v10, v11
	v_min_f32_e32 v10, v10, v11
	v_max_f32_e32 v11, v12, v12
	v_max_f32_e32 v12, v13, v13
	v_max_f32_e32 v17, v16, v15
	v_min_f32_e32 v15, v16, v15
	v_max_f32_e32 v16, v6, v7
	v_min_f32_e32 v6, v6, v7
	v_max_f32_e32 v7, v8, v8
	v_max_f32_e32 v8, v9, v9
	v_max_f32_e32 v13, v12, v11
	v_min_f32_e32 v11, v12, v11
	v_max_f32_e32 v12, v2, v3
	v_min_f32_e32 v2, v2, v3
	v_max_f32_e32 v3, v4, v4
	v_max_f32_e32 v4, v5, v5
	v_max_f32_e32 v9, v8, v7
	v_min_f32_e32 v7, v8, v7
	v_max_f32_e32 v5, v4, v3
	v_min_f32_e32 v3, v4, v3
	v_max_f32_e32 v8, v101, v31
	v_min_f32_e32 v31, v101, v31
	v_max_f32_e32 v101, v30, v33
	v_min_f32_e32 v30, v30, v33
	v_max_f32_e32 v33, v23, v32
	v_min_f32_e32 v23, v23, v32
	v_max_f32_e32 v32, v25, v22
	v_min_f32_e32 v22, v25, v22
	v_max_f32_e32 v25, v24, v15
	v_min_f32_e32 v15, v24, v15
	v_max_f32_e32 v24, v14, v17
	v_min_f32_e32 v14, v14, v17
	v_max_f32_e32 v17, v7, v16
	v_min_f32_e32 v7, v7, v16
	v_max_f32_e32 v16, v9, v6
	v_min_f32_e32 v6, v9, v6
	v_max_f32_e32 v4, v109, v27
	v_min_f32_e32 v27, v109, v27
	v_max_f32_e32 v109, v26, v29
	v_min_f32_e32 v26, v26, v29
	v_max_f32_e32 v29, v19, v28
	v_min_f32_e32 v19, v19, v28
	v_max_f32_e32 v28, v21, v18
	v_min_f32_e32 v18, v21, v18
	v_max_f32_e32 v21, v20, v11
	v_min_f32_e32 v11, v20, v11
	v_max_f32_e32 v20, v10, v13
	v_min_f32_e32 v10, v10, v13
	v_max_f32_e32 v13, v3, v12
	v_min_f32_e32 v3, v3, v12
	v_max_f32_e32 v12, v5, v2
	v_min_f32_e32 v2, v5, v2
	v_max_f32_e32 v9, v8, v101
	v_min_f32_e32 v8, v8, v101
	v_max_f32_e32 v101, v31, v30
	v_min_f32_e32 v30, v31, v30
	v_max_f32_e32 v31, v22, v23
	v_min_f32_e32 v22, v22, v23
	v_max_f32_e32 v23, v32, v33
	v_min_f32_e32 v32, v32, v33
	v_max_f32_e32 v33, v25, v24
	v_min_f32_e32 v24, v25, v24
	v_max_f32_e32 v25, v15, v14
	v_min_f32_e32 v14, v15, v14
	v_max_f32_e32 v15, v6, v7
	v_min_f32_e32 v6, v6, v7
	v_max_f32_e32 v7, v16, v17
	v_min_f32_e32 v16, v16, v17
	v_max_f32_e32 v5, v4, v109
	v_min_f32_e32 v4, v4, v109
	v_max_f32_e32 v109, v27, v26
	v_min_f32_e32 v26, v27, v26
	v_max_f32_e32 v27, v18, v19
	v_min_f32_e32 v18, v18, v19
	v_max_f32_e32 v19, v28, v29
	v_min_f32_e32 v28, v28, v29
	v_max_f32_e32 v29, v21, v20
	v_min_f32_e32 v20, v21, v20
	v_max_f32_e32 v21, v11, v10
	v_min_f32_e32 v10, v11, v10
	v_max_f32_e32 v11, v2, v3
	v_min_f32_e32 v2, v2, v3
	v_max_f32_e32 v3, v12, v13
	v_min_f32_e32 v12, v12, v13
	v_max_f32_e32 v17, v9, v22
	v_min_f32_e32 v9, v9, v22
	v_max_f32_e32 v22, v8, v31
	v_min_f32_e32 v8, v8, v31
	v_max_f32_e32 v31, v101, v32
	v_min_f32_e32 v32, v101, v32
	v_max_f32_e32 v101, v30, v23
	v_min_f32_e32 v23, v30, v23
	v_max_f32_e32 v30, v6, v33
	v_min_f32_e32 v6, v6, v33
	v_max_f32_e32 v33, v15, v24
	v_min_f32_e32 v15, v15, v24
	v_max_f32_e32 v24, v16, v25
	v_min_f32_e32 v16, v16, v25
	v_max_f32_e32 v25, v7, v14
	v_min_f32_e32 v7, v7, v14
	v_max_f32_e32 v13, v5, v18
	v_min_f32_e32 v5, v5, v18
	v_max_f32_e32 v18, v4, v27
	v_min_f32_e32 v4, v4, v27
	v_max_f32_e32 v27, v109, v28
	v_min_f32_e32 v28, v109, v28
	v_max_f32_e32 v109, v26, v19
	v_min_f32_e32 v19, v26, v19
	v_max_f32_e32 v26, v2, v29
	v_min_f32_e32 v2, v2, v29
	v_max_f32_e32 v29, v11, v20
	v_min_f32_e32 v11, v11, v20
	v_max_f32_e32 v20, v12, v21
	v_min_f32_e32 v12, v12, v21
	v_max_f32_e32 v21, v3, v10
	v_min_f32_e32 v3, v3, v10
	v_max_f32_e32 v14, v17, v31
	v_min_f32_e32 v17, v17, v31
	v_max_f32_e32 v31, v22, v101
	v_min_f32_e32 v22, v22, v101
	v_max_f32_e32 v101, v9, v32
	v_min_f32_e32 v9, v9, v32
	v_max_f32_e32 v32, v8, v23
	v_min_f32_e32 v8, v8, v23
	v_max_f32_e32 v23, v16, v6
	v_min_f32_e32 v6, v16, v6
	v_max_f32_e32 v16, v7, v15
	v_min_f32_e32 v7, v7, v15
	v_max_f32_e32 v15, v24, v30
	v_min_f32_e32 v24, v24, v30
	v_max_f32_e32 v30, v25, v33
	v_min_f32_e32 v25, v25, v33
	v_max_f32_e32 v10, v13, v27
	v_min_f32_e32 v13, v13, v27
	v_max_f32_e32 v27, v18, v109
	v_min_f32_e32 v18, v18, v109
	v_max_f32_e32 v109, v5, v28
	v_min_f32_e32 v5, v5, v28
	v_max_f32_e32 v28, v4, v19
	v_min_f32_e32 v4, v4, v19
	v_max_f32_e32 v19, v12, v2
	v_min_f32_e32 v2, v12, v2
	v_max_f32_e32 v12, v3, v11
	v_min_f32_e32 v3, v3, v11
	v_max_f32_e32 v11, v20, v26
	v_min_f32_e32 v20, v20, v26
	v_max_f32_e32 v26, v21, v29
	v_min_f32_e32 v21, v21, v29
	v_max_f32_e32 v33, v14, v31
	v_min_f32_e32 v14, v14, v31
	v_max_f32_e32 v31, v17, v22
	v_min_f32_e32 v17, v17, v22
	v_max_f32_e32 v22, v101, v32
	v_min_f32_e32 v32, v101, v32
	v_max_f32_e32 v101, v9, v8
	v_min_f32_e32 v8, v9, v8
	v_max_f32_e32 v9, v7, v6
	v_min_f32_e32 v6, v7, v6
	v_max_f32_e32 v7, v16, v23
	v_min_f32_e32 v16, v16, v23
	v_max_f32_e32 v23, v25, v24
	v_min_f32_e32 v24, v25, v24
	v_max_f32_e32 v25, v30, v15
	v_min_f32_e32 v15, v30, v15
	v_max_f32_e32 v29, v10, v27
	v_min_f32_e32 v10, v10, v27
	v_max_f32_e32 v27, v13, v18
	v_min_f32_e32 v13, v13, v18
	v_max_f32_e32 v18, v109, v28
	v_min_f32_e32 v28, v109, v28
	v_max_f32_e32 v109, v5, v4
	v_min_f32_e32 v4, v5, v4
	v_max_f32_e32 v5, v3, v2
	v_min_f32_e32 v2, v3, v2
	v_max_f32_e32 v3, v12, v19
	v_min_f32_e32 v12, v12, v19
	v_max_f32_e32 v19, v21, v20
	v_min_f32_e32 v20, v21, v20
	v_max_f32_e32 v21, v26, v11
	v_min_f32_e32 v11, v26, v11
	v_max_f32_e32 v30, v33, v6
	v_min_f32_e32 v6, v33, v6
	v_max_f32_e32 v33, v14, v9
	v_min_f32_e32 v9, v14, v9
	v_max_f32_e32 v14, v31, v16
	v_min_f32_e32 v16, v31, v16
	v_max_f32_e32 v31, v17, v7
	v_min_f32_e32 v7, v17, v7
	v_max_f32_e32 v17, v22, v24
	v_min_f32_e32 v22, v22, v24
	v_max_f32_e32 v24, v32, v23
	v_min_f32_e32 v23, v32, v23
	v_max_f32_e32 v32, v101, v15
	v_min_f32_e32 v15, v101, v15
	v_max_f32_e32 v101, v8, v25
; DEV void peer_top16(const bf16_t* __restrict__ pq, const bf16_t* sk  , float (&l)[16]) {
;     ...
;   sort16_desc(l);
;   sort16_desc(hi);
; #pragma unroll
;   for (int i = 0; i < 16; i++) l[i] = fmaxf(l[i], hi[15 - i]);
;   bitonic16(l);
;   merge_xor(l, 16);
;   merge_xor(l, 32);
	v_min_f32_e32 v8, v8, v25
	v_max_f32_e32 v26, v29, v2
	v_min_f32_e32 v2, v29, v2
	v_max_f32_e32 v29, v10, v5
	v_min_f32_e32 v5, v10, v5
	v_max_f32_e32 v10, v27, v12
	v_min_f32_e32 v12, v27, v12
	v_max_f32_e32 v27, v13, v3
	v_min_f32_e32 v3, v13, v3
	v_max_f32_e32 v13, v18, v20
	v_min_f32_e32 v18, v18, v20
	v_max_f32_e32 v20, v28, v19
	v_min_f32_e32 v19, v28, v19
	v_max_f32_e32 v28, v109, v11
	v_min_f32_e32 v11, v109, v11
	v_max_f32_e32 v109, v4, v21
	v_min_f32_e32 v4, v4, v21
	v_max_f32_e32 v25, v30, v17
	v_min_f32_e32 v17, v30, v17
	v_max_f32_e32 v30, v33, v24
	v_min_f32_e32 v24, v33, v24
	v_max_f32_e32 v33, v14, v32
	v_min_f32_e32 v14, v14, v32
	v_max_f32_e32 v32, v31, v101
	v_min_f32_e32 v31, v31, v101
	v_max_f32_e32 v101, v6, v22
	v_min_f32_e32 v6, v6, v22
	v_max_f32_e32 v22, v9, v23
	v_min_f32_e32 v9, v9, v23
	v_max_f32_e32 v23, v16, v15
	v_min_f32_e32 v15, v16, v15
	v_max_f32_e32 v16, v7, v8
	v_min_f32_e32 v7, v7, v8
	v_max_f32_e32 v21, v26, v13
	v_min_f32_e32 v13, v26, v13
	v_max_f32_e32 v26, v29, v20
	v_min_f32_e32 v20, v29, v20
	v_max_f32_e32 v29, v10, v28
	v_min_f32_e32 v10, v10, v28
	v_max_f32_e32 v28, v27, v109
	v_min_f32_e32 v27, v27, v109
	v_max_f32_e32 v109, v2, v18
	v_min_f32_e32 v2, v2, v18
	v_max_f32_e32 v18, v5, v19
	v_min_f32_e32 v5, v5, v19
	v_max_f32_e32 v19, v12, v11
	v_min_f32_e32 v11, v12, v11
	v_max_f32_e32 v12, v3, v4
	v_min_f32_e32 v3, v3, v4
	v_max_f32_e32 v111, v0, v43
	v_min_f32_e32 v112, v104, v39
	v_max_f32_e32 v103, v104, v39
	v_min_f32_e32 v0, v0, v43
	v_max_f32_e32 v8, v25, v33
	v_min_f32_e32 v25, v25, v33
	v_max_f32_e32 v33, v30, v32
	v_min_f32_e32 v30, v30, v32
	v_max_f32_e32 v32, v17, v14
	v_min_f32_e32 v14, v17, v14
	v_max_f32_e32 v17, v24, v31
	v_min_f32_e32 v24, v24, v31
	v_max_f32_e32 v31, v101, v23
	v_min_f32_e32 v23, v101, v23
	v_max_f32_e32 v101, v22, v16
	v_min_f32_e32 v16, v22, v16
	v_max_f32_e32 v22, v6, v15
	v_min_f32_e32 v6, v6, v15
	v_max_f32_e32 v15, v9, v7
	v_min_f32_e32 v7, v9, v7
	v_max_f32_e32 v4, v21, v29
	v_min_f32_e32 v21, v21, v29
	v_max_f32_e32 v29, v26, v28
	v_min_f32_e32 v26, v26, v28
	v_max_f32_e32 v28, v13, v10
	v_min_f32_e32 v10, v13, v10
	v_max_f32_e32 v13, v20, v27
	v_min_f32_e32 v20, v20, v27
	v_max_f32_e32 v27, v109, v19
	v_min_f32_e32 v19, v109, v19
	v_max_f32_e32 v109, v18, v12
	v_min_f32_e32 v12, v18, v12
	v_max_f32_e32 v18, v2, v11
	v_min_f32_e32 v2, v2, v11
	v_max_f32_e32 v11, v5, v3
	v_min_f32_e32 v3, v5, v3
	v_min_f32_e32 v63, v107, v108
	v_min_f32_e32 v39, v111, v103
	v_max_f32_e32 v71, v107, v108
	v_max_f32_e32 v51, v111, v103
	v_max_f32_e32 v43, v0, v112
	v_min_f32_e32 v0, v0, v112
	v_min_f32_e32 v9, v8, v33
	v_min_f32_e32 v102, v25, v30
	v_min_f32_e32 v103, v32, v17
	v_min_f32_e32 v104, v14, v24
	v_min_f32_e32 v105, v31, v101
	v_min_f32_e32 v106, v23, v16
	v_min_f32_e32 v107, v22, v15
	v_min_f32_e32 v108, v6, v7
	v_min_f32_e32 v5, v4, v29
	v_min_f32_e32 v110, v21, v26
	v_min_f32_e32 v111, v28, v13
	v_min_f32_e32 v112, v10, v20
	v_min_f32_e32 v113, v27, v109
	v_min_f32_e32 v114, v19, v12
	v_min_f32_e32 v115, v18, v11
	v_min_f32_e32 v116, v2, v3
	v_max3_f32 v8, v8, v33, v116
	v_max3_f32 v2, v9, v2, v3
	v_max3_f32 v3, v25, v30, v115
	v_max3_f32 v9, v102, v18, v11
	v_max3_f32 v11, v32, v17, v114
	v_max3_f32 v12, v103, v19, v12
	v_max3_f32 v14, v14, v24, v113
	v_max3_f32 v17, v104, v27, v109
	v_max3_f32 v18, v31, v101, v112
	v_max3_f32 v10, v105, v10, v20
	v_max3_f32 v16, v23, v16, v111
	v_max3_f32 v13, v106, v28, v13
	v_max3_f32 v15, v22, v15, v110
	v_max3_f32 v19, v107, v21, v26
	v_max3_f32 v5, v6, v7, v5
	v_max3_f32 v4, v108, v4, v29
	v_max_f32_e32 v6, v8, v18
	v_min_f32_e32 v7, v8, v18
	v_max_f32_e32 v8, v2, v10
	v_min_f32_e32 v2, v2, v10
	v_max_f32_e32 v10, v3, v16
	v_min_f32_e32 v3, v3, v16
	v_max_f32_e32 v16, v9, v13
	v_min_f32_e32 v9, v9, v13
	v_max_f32_e32 v13, v11, v15
	v_min_f32_e32 v11, v11, v15
	v_max_f32_e32 v15, v12, v19
	v_min_f32_e32 v12, v12, v19
	v_max_f32_e32 v18, v14, v5
	v_min_f32_e32 v5, v14, v5
	v_max_f32_e32 v14, v17, v4
	v_min_f32_e32 v4, v17, v4
	v_max_f32_e32 v17, v6, v13
	v_min_f32_e32 v6, v6, v13
	v_max_f32_e32 v13, v8, v15
	v_min_f32_e32 v8, v8, v15
	v_max_f32_e32 v15, v10, v18
	v_min_f32_e32 v10, v10, v18
	v_max_f32_e32 v18, v16, v14
	v_min_f32_e32 v14, v16, v14
	v_max_f32_e32 v16, v7, v11
	v_min_f32_e32 v7, v7, v11
	v_max_f32_e32 v11, v2, v12
	v_min_f32_e32 v2, v2, v12
	v_max_f32_e32 v12, v3, v5
	v_min_f32_e32 v3, v3, v5
	v_max_f32_e32 v5, v9, v4
	v_min_f32_e32 v4, v9, v4
	v_max_f32_e32 v9, v17, v15
	v_min_f32_e32 v15, v17, v15
	v_max_f32_e32 v17, v13, v18
	v_min_f32_e32 v13, v13, v18
	v_max_f32_e32 v18, v6, v10
	v_min_f32_e32 v6, v6, v10
	v_max_f32_e32 v10, v8, v14
	v_min_f32_e32 v8, v8, v14
	v_max_f32_e32 v14, v16, v12
	v_min_f32_e32 v12, v16, v12
	v_max_f32_e32 v16, v11, v5
	v_min_f32_e32 v5, v11, v5
	v_max_f32_e32 v11, v7, v3
	v_min_f32_e32 v3, v7, v3
	v_max_f32_e32 v7, v2, v4
	v_min_f32_e32 v2, v2, v4
	v_max_f32_e32 v4, v9, v17
	v_min_f32_e32 v9, v9, v17
	v_max_f32_e32 v17, v15, v13
	v_min_f32_e32 v13, v15, v13
	v_max_f32_e32 v15, v18, v10
	v_min_f32_e32 v10, v18, v10
	v_max_f32_e32 v18, v6, v8
	v_min_f32_e32 v6, v6, v8
	v_max_f32_e32 v8, v14, v16
	v_min_f32_e32 v14, v14, v16
	v_max_f32_e32 v16, v12, v5
	v_min_f32_e32 v5, v12, v5
	v_max_f32_e32 v12, v11, v7
	v_min_f32_e32 v7, v11, v7
	v_max_f32_e32 v11, v3, v2
	v_min_f32_e32 v2, v3, v2
	ds_bpermute_b32 v3, v95, v2
	ds_bpermute_b32 v19, v95, v11
	ds_bpermute_b32 v20, v95, v7
	ds_bpermute_b32 v21, v95, v12
	ds_bpermute_b32 v22, v95, v5
	ds_bpermute_b32 v23, v95, v16
	s_waitcnt lgkmcnt(5)
	ds_bpermute_b32 v24, v95, v14
	ds_bpermute_b32 v33, v95, v4
	v_max_f32_e32 v3, v4, v3
	s_waitcnt lgkmcnt(6)
; DEV void merge_xor(float (&l)[16], int mask) {
;   float t[16];
; #pragma unroll
;   for (int i = 0; i < 16; i++) t[i] = __shfl_xor(l[15 - i], mask);
; #pragma unroll
;   for (int i = 0; i < 16; i++) l[i] = fmaxf(l[i], t[i]);
;   bitonic16(l);
; }
; DEV void phase_peer_score(const Params& p, int layer, int M, char* smem) {
;     ...
;     unsigned char* tab = (unsigned char*)smem + 73728 + (w * 16 + l15) * 32;
; #pragma unroll
;     for (int i = 0; i < 16; i++) { tab[i] = (unsigned char)(__float_as_uint(L0[i]) & 127u); tab[16 + i] = (unsigned char)(__float_as_uint(L1[i]) & 127u); }
	ds_bpermute_b32 v25, v95, v8
	ds_bpermute_b32 v32, v95, v9
	v_max_f32_e32 v4, v9, v19
	s_waitcnt lgkmcnt(7)
	ds_bpermute_b32 v26, v95, v6
	ds_bpermute_b32 v31, v95, v17
	v_max_f32_e32 v9, v17, v20
	s_waitcnt lgkmcnt(8)
	ds_bpermute_b32 v27, v95, v18
	ds_bpermute_b32 v30, v95, v13
	v_max_f32_e32 v13, v13, v21
	s_waitcnt lgkmcnt(9)
	ds_bpermute_b32 v28, v95, v10
	ds_bpermute_b32 v29, v95, v15
	v_max_f32_e32 v15, v15, v22
	s_waitcnt lgkmcnt(10)
	v_max_f32_e32 v10, v10, v23
	s_waitcnt lgkmcnt(9)
	v_max_f32_e32 v17, v18, v24
	s_waitcnt lgkmcnt(7)
	v_max_f32_e32 v6, v6, v25
	s_waitcnt lgkmcnt(5)
	v_max_f32_e32 v8, v8, v26
	s_waitcnt lgkmcnt(3)
	v_max_f32_e32 v14, v14, v27
	s_waitcnt lgkmcnt(1)
	v_max_f32_e32 v16, v16, v28
	s_waitcnt lgkmcnt(0)
	v_max_f32_e32 v5, v5, v29
	v_max_f32_e32 v12, v12, v30
	v_max_f32_e32 v7, v7, v31
	v_max_f32_e32 v11, v11, v32
	v_max_f32_e32 v2, v2, v33
	v_max_f32_e32 v18, v3, v8
	v_min_f32_e32 v3, v3, v8
	v_max_f32_e32 v8, v4, v14
	v_min_f32_e32 v4, v4, v14
	v_max_f32_e32 v14, v9, v16
	v_min_f32_e32 v9, v9, v16
	v_max_f32_e32 v16, v13, v5
	v_min_f32_e32 v5, v13, v5
	v_max_f32_e32 v13, v15, v12
	v_min_f32_e32 v12, v15, v12
	v_max_f32_e32 v15, v10, v7
	v_min_f32_e32 v7, v10, v7
	v_max_f32_e32 v10, v17, v11
	v_min_f32_e32 v11, v17, v11
	v_max_f32_e32 v17, v6, v2
	v_min_f32_e32 v2, v6, v2
	v_max_f32_e32 v6, v18, v13
	v_min_f32_e32 v13, v18, v13
	v_max_f32_e32 v18, v8, v15
	v_min_f32_e32 v8, v8, v15
	v_max_f32_e32 v15, v14, v10
	v_min_f32_e32 v10, v14, v10
	v_max_f32_e32 v14, v16, v17
	v_min_f32_e32 v16, v16, v17
	v_max_f32_e32 v17, v3, v12
	v_min_f32_e32 v3, v3, v12
	v_max_f32_e32 v12, v4, v7
	v_min_f32_e32 v4, v4, v7
	v_max_f32_e32 v7, v9, v11
	v_min_f32_e32 v9, v9, v11
	v_max_f32_e32 v11, v5, v2
	v_min_f32_e32 v2, v5, v2
	v_max_f32_e32 v5, v6, v15
	v_min_f32_e32 v6, v6, v15
	v_max_f32_e32 v15, v18, v14
	v_min_f32_e32 v14, v18, v14
	v_max_f32_e32 v18, v13, v10
	v_min_f32_e32 v10, v13, v10
	v_max_f32_e32 v13, v8, v16
	v_min_f32_e32 v8, v8, v16
	v_max_f32_e32 v16, v17, v7
	v_min_f32_e32 v7, v17, v7
	v_max_f32_e32 v17, v12, v11
	v_min_f32_e32 v11, v12, v11
	v_max_f32_e32 v12, v3, v9
	v_min_f32_e32 v3, v3, v9
	v_max_f32_e32 v9, v4, v2
	v_min_f32_e32 v2, v4, v2
	v_max_f32_e32 v4, v5, v15
	v_min_f32_e32 v5, v5, v15
	v_max_f32_e32 v15, v6, v14
	v_min_f32_e32 v6, v6, v14
	v_max_f32_e32 v14, v18, v13
	v_min_f32_e32 v13, v18, v13
	v_max_f32_e32 v18, v10, v8
	v_min_f32_e32 v8, v10, v8
	v_max_f32_e32 v10, v16, v17
	v_min_f32_e32 v16, v16, v17
	v_max_f32_e32 v17, v7, v11
	v_min_f32_e32 v7, v7, v11
	v_max_f32_e32 v11, v12, v9
	v_min_f32_e32 v9, v12, v9
	v_max_f32_e32 v12, v3, v2
	v_min_f32_e32 v2, v3, v2
	ds_bpermute_b32 v3, v99, v2
	ds_bpermute_b32 v19, v99, v12
	ds_bpermute_b32 v20, v99, v9
	ds_bpermute_b32 v21, v99, v11
	ds_bpermute_b32 v22, v99, v7
	ds_bpermute_b32 v23, v99, v17
	s_waitcnt lgkmcnt(5)
	ds_bpermute_b32 v24, v99, v16
	ds_bpermute_b32 v33, v99, v4
	v_max_f32_e32 v3, v4, v3
	s_waitcnt lgkmcnt(6)
	ds_bpermute_b32 v25, v99, v10
	ds_bpermute_b32 v32, v99, v5
	v_max_f32_e32 v4, v5, v19
	s_waitcnt lgkmcnt(7)
	ds_bpermute_b32 v26, v99, v8
	ds_bpermute_b32 v31, v99, v15
	v_max_f32_e32 v5, v15, v20
	s_waitcnt lgkmcnt(8)
	ds_bpermute_b32 v27, v99, v18
	ds_bpermute_b32 v30, v99, v6
	v_max_f32_e32 v6, v6, v21
	s_waitcnt lgkmcnt(9)
	ds_bpermute_b32 v28, v99, v13
	ds_bpermute_b32 v29, v99, v14
	v_max_f32_e32 v14, v14, v22
	s_waitcnt lgkmcnt(10)
	v_max_f32_e32 v13, v13, v23
	s_waitcnt lgkmcnt(9)
	v_max_f32_e32 v15, v18, v24
	s_waitcnt lgkmcnt(7)
	v_max_f32_e32 v8, v8, v25
	s_waitcnt lgkmcnt(5)
	v_max_f32_e32 v10, v10, v26
	s_waitcnt lgkmcnt(3)
	v_max_f32_e32 v16, v16, v27
	s_waitcnt lgkmcnt(1)
	v_max_f32_e32 v17, v17, v28
	s_waitcnt lgkmcnt(0)
	v_max_f32_e32 v7, v7, v29
	v_max_f32_e32 v11, v11, v30
	v_max_f32_e32 v9, v9, v31
	v_max_f32_e32 v12, v12, v32
	v_max_f32_e32 v2, v2, v33
	v_max_f32_e32 v18, v3, v10
	v_min_f32_e32 v3, v3, v10
	v_max_f32_e32 v10, v4, v16
	v_min_f32_e32 v4, v4, v16
	v_max_f32_e32 v16, v5, v17
	v_min_f32_e32 v5, v5, v17
	v_max_f32_e32 v17, v6, v7
	v_min_f32_e32 v6, v6, v7
	v_max_f32_e32 v7, v14, v11
	v_min_f32_e32 v11, v14, v11
	v_max_f32_e32 v14, v13, v9
	v_min_f32_e32 v9, v13, v9
	v_max_f32_e32 v13, v15, v12
	v_min_f32_e32 v12, v15, v12
	v_max_f32_e32 v15, v8, v2
	v_min_f32_e32 v2, v8, v2
	v_max_f32_e32 v8, v18, v7
	v_min_f32_e32 v7, v18, v7
	v_max_f32_e32 v18, v10, v14
	v_min_f32_e32 v10, v10, v14
	v_max_f32_e32 v14, v16, v13
	v_min_f32_e32 v13, v16, v13
	v_max_f32_e32 v16, v17, v15
	v_min_f32_e32 v15, v17, v15
	v_max_f32_e32 v17, v3, v11
	v_min_f32_e32 v3, v3, v11
	v_max_f32_e32 v11, v4, v9
	v_min_f32_e32 v4, v4, v9
	v_max_f32_e32 v9, v5, v12
	v_min_f32_e32 v5, v5, v12
	v_max_f32_e32 v12, v6, v2
	v_min_f32_e32 v2, v6, v2
	v_max_f32_e32 v6, v8, v14
	v_min_f32_e32 v8, v8, v14
	v_max_f32_e32 v14, v18, v16
	v_min_f32_e32 v16, v18, v16
	v_max_f32_e32 v18, v7, v13
	v_max_f32_e32 v19, v10, v15
	s_movk_i32 s0, 0x7f
	v_min_f32_e32 v13, v7, v13
	v_min_f32_e32 v10, v10, v15
	v_max_f32_e32 v15, v17, v9
	v_min_f32_e32 v21, v17, v9
	v_max_f32_e32 v17, v11, v12
	v_min_f32_e32 v22, v11, v12
	v_max_f32_e32 v23, v3, v5
	v_min_f32_e32 v3, v3, v5
	v_max_f32_e32 v5, v4, v2
	v_min_f32_e32 v24, v4, v2
	v_max_f32_e32 v9, v18, v19
	v_min_f32_e32 v12, v18, v19
	v_and_b32_sdwa v18, v63, s0 dst_sel:BYTE_1 dst_unused:UNUSED_PAD src0_sel:DWORD src1_sel:DWORD
	v_max_f32_e32 v2, v6, v14
	v_min_f32_e32 v4, v6, v14
	v_max_f32_e32 v11, v13, v10
	v_min_f32_e32 v10, v13, v10
	v_max_f32_e32 v14, v23, v5
	v_min_f32_e32 v13, v23, v5
	v_max_f32_e32 v6, v3, v24
	v_min_f32_e32 v5, v3, v24
	v_and_b32_sdwa v3, v75, s0 dst_sel:BYTE_1 dst_unused:UNUSED_PAD src0_sel:DWORD src1_sel:DWORD
; DEV void ce(float& a, float& b) { float hi = fmaxf(a, b), lo = fminf(a, b); a = hi; b = lo; }
; DEV void phase_peer_score(const Params& p, int layer, int M, char* smem) {
;     ...
; #pragma unroll
;     for (int i = 0; i < 16; i++) R[i] = -3.0e38f;
; #pragma unroll
;     for (int i = 0; i < 16; i++)
; #pragma unroll
;       for (int j = 0; j < 16; j++)
;         if ((i + 1) * (j + 1) <= 16) {
;           float v = L0[i] + L1[j];
;           v = __uint_as_float((__float_as_uint(v) & ~255u) | (unsigned)(i * 16 + j));
; #pragma unroll
;           for (int t = 0; t < 16; t++)
;             if (t >= (i + 1) * (j + 1) - 1) ce(R[t], v);
;         }
;     unsigned char* tab = (unsigned char*)smem + 73728 + (w * 16 + l15) * 32;
; #pragma unroll
;     for (int i = 0; i < 16; i++) { tab[i] = (unsigned char)(__float_as_uint(L0[i]) & 127u); tab[16 + i] = (unsigned char)(__float_as_uint(L1[i]) & 127u); }
;     float ev[16]; float sum = 0.f;
; #pragma unroll
;     for (int t = 0; t < 16; t++) { ev[t] = __expf(R[t] - R[0]); sum += ev[t]; }
;     const float inv = 1.f / sum;
;     int eid[16];
; #pragma unroll
;     for (int t = 0; t < 16; t++) {
;       unsigned code = __float_as_uint(R[t]) & 255u;
;       eid[t] = (int)tab[code >> 4] * 128 + (int)tab[16 + (code & 15u)];
;     }
;     if (quad == 0) {
	v_bitop3_b16 v18, v71, v18, s0 bitop3:0xec
	v_bitop3_b16 v3, v79, v3, s0 bitop3:0xec
	v_lshlrev_b32_e32 v18, 16, v18
	v_or_b32_sdwa v23, v3, v18 dst_sel:DWORD dst_unused:UNUSED_PAD src0_sel:WORD_0 src1_sel:DWORD
	v_and_b32_sdwa v18, v83, s0 dst_sel:BYTE_1 dst_unused:UNUSED_PAD src0_sel:DWORD src1_sel:DWORD
	v_and_b32_sdwa v3, v91, s0 dst_sel:BYTE_1 dst_unused:UNUSED_PAD src0_sel:DWORD src1_sel:DWORD
	v_bitop3_b16 v18, v87, v18, s0 bitop3:0xec
	v_bitop3_b16 v3, v100, v3, s0 bitop3:0xec
	v_lshlrev_b32_e32 v18, 16, v18
	v_max_f32_e32 v7, v8, v16
	v_min_f32_e32 v8, v8, v16
	v_max_f32_e32 v20, v15, v17
	v_min_f32_e32 v17, v15, v17
	v_max_f32_e32 v16, v21, v22
	v_min_f32_e32 v15, v21, v22
	v_or_b32_sdwa v22, v3, v18 dst_sel:DWORD dst_unused:UNUSED_PAD src0_sel:WORD_0 src1_sel:DWORD
	v_and_b32_sdwa v18, v10, s0 dst_sel:BYTE_1 dst_unused:UNUSED_PAD src0_sel:DWORD src1_sel:DWORD
	v_and_b32_sdwa v3, v12, s0 dst_sel:BYTE_1 dst_unused:UNUSED_PAD src0_sel:DWORD src1_sel:DWORD
	v_bitop3_b16 v18, v11, v18, s0 bitop3:0xec
	v_bitop3_b16 v3, v9, v3, s0 bitop3:0xec
	v_lshlrev_b32_e32 v18, 16, v18
	v_or_b32_sdwa v27, v3, v18 dst_sel:DWORD dst_unused:UNUSED_PAD src0_sel:WORD_0 src1_sel:DWORD
	v_and_b32_sdwa v18, v8, s0 dst_sel:BYTE_1 dst_unused:UNUSED_PAD src0_sel:DWORD src1_sel:DWORD
	v_and_b32_sdwa v3, v4, s0 dst_sel:BYTE_1 dst_unused:UNUSED_PAD src0_sel:DWORD src1_sel:DWORD
	v_bitop3_b16 v18, v7, v18, s0 bitop3:0xec
	v_bitop3_b16 v3, v2, v3, s0 bitop3:0xec
	v_lshlrev_b32_e32 v18, 16, v18
	v_or_b32_sdwa v26, v3, v18 dst_sel:DWORD dst_unused:UNUSED_PAD src0_sel:WORD_0 src1_sel:DWORD
	v_and_b32_sdwa v18, v0, s0 dst_sel:BYTE_1 dst_unused:UNUSED_PAD src0_sel:DWORD src1_sel:DWORD
	v_and_b32_sdwa v3, v39, s0 dst_sel:BYTE_1 dst_unused:UNUSED_PAD src0_sel:DWORD src1_sel:DWORD
	v_bitop3_b16 v18, v43, v18, s0 bitop3:0xec
	v_bitop3_b16 v3, v51, v3, s0 bitop3:0xec
	v_lshlrev_b32_e32 v18, 16, v18
	v_or_b32_sdwa v25, v3, v18 dst_sel:DWORD dst_unused:UNUSED_PAD src0_sel:WORD_0 src1_sel:DWORD
	v_and_b32_sdwa v18, v47, s0 dst_sel:BYTE_1 dst_unused:UNUSED_PAD src0_sel:DWORD src1_sel:DWORD
	v_and_b32_sdwa v3, v59, s0 dst_sel:BYTE_1 dst_unused:UNUSED_PAD src0_sel:DWORD src1_sel:DWORD
	v_bitop3_b16 v18, v55, v18, s0 bitop3:0xec
	v_bitop3_b16 v3, v67, v3, s0 bitop3:0xec
	v_lshlrev_b32_e32 v18, 16, v18
	v_or_b32_sdwa v24, v3, v18 dst_sel:DWORD dst_unused:UNUSED_PAD src0_sel:WORD_0 src1_sel:DWORD
	v_and_b32_sdwa v18, v5, s0 dst_sel:BYTE_1 dst_unused:UNUSED_PAD src0_sel:DWORD src1_sel:DWORD
	v_and_b32_sdwa v3, v13, s0 dst_sel:BYTE_1 dst_unused:UNUSED_PAD src0_sel:DWORD src1_sel:DWORD
	v_bitop3_b16 v18, v6, v18, s0 bitop3:0xec
	v_bitop3_b16 v3, v14, v3, s0 bitop3:0xec
	v_lshlrev_b32_e32 v18, 16, v18
	v_or_b32_sdwa v29, v3, v18 dst_sel:DWORD dst_unused:UNUSED_PAD src0_sel:WORD_0 src1_sel:DWORD
	v_and_b32_sdwa v18, v15, s0 dst_sel:BYTE_1 dst_unused:UNUSED_PAD src0_sel:DWORD src1_sel:DWORD
	v_and_b32_sdwa v3, v17, s0 dst_sel:BYTE_1 dst_unused:UNUSED_PAD src0_sel:DWORD src1_sel:DWORD
	v_bitop3_b16 v18, v16, v18, s0 bitop3:0xec
	v_bitop3_b16 v3, v20, v3, s0 bitop3:0xec
	v_lshlrev_b32_e32 v18, 16, v18
	v_or_b32_sdwa v28, v3, v18 dst_sel:DWORD dst_unused:UNUSED_PAD src0_sel:WORD_0 src1_sel:DWORD
	ds_write_b128 v138, v[22:25]
	ds_write_b128 v138, v[26:29] offset:16
	s_and_saveexec_b64 s[14:15], s[38:39]
	s_cbranch_execz .LBB0_162
	s_lshl_b32 s0, s18, 3
	v_add_f32_e32 v3, v100, v2
	s_andn2_b32 s0, s0, 63
	v_and_b32_e32 v3, 0xffffff00, v3
	v_add_u32_e32 v18, s0, v117
	v_add_f32_e32 v22, v100, v4
	s_movk_i32 s0, 0xff00
	v_min_f32_e32 v21, 0xff61b1e6, v3
	v_and_or_b32 v22, v22, s0, 1
	v_max_f32_e32 v21, 0xff61b1e6, v21
	v_add_f32_e32 v24, v100, v7
	v_min_f32_e32 v23, v21, v22
	v_and_or_b32 v24, v24, s0, 2
	v_max_f32_e32 v23, v21, v23
	v_add_f32_e32 v26, v100, v8
	v_min_f32_e32 v25, v23, v24
	v_and_or_b32 v26, v26, s0, 3
	v_max_f32_e32 v25, v23, v25
	v_add_f32_e32 v28, v100, v9
	v_min_f32_e32 v27, v25, v26
	v_and_or_b32 v28, v28, s0, 4
	v_max_f32_e32 v27, v25, v27
	v_add_f32_e32 v30, v100, v12
	v_min_f32_e32 v29, v27, v28
	v_and_or_b32 v30, v30, s0, 5
	v_max_f32_e32 v29, v27, v29
	v_add_f32_e32 v32, v100, v11
	v_min_f32_e32 v31, v29, v30
	v_and_or_b32 v32, v32, s0, 6
	v_max_f32_e32 v31, v29, v31
	v_add_f32_e32 v95, v100, v10
	v_min_f32_e32 v33, v31, v32
	v_and_or_b32 v95, v95, s0, 7
	v_max_f32_e32 v33, v31, v33
	v_add_f32_e32 v20, v100, v20
	v_min_f32_e32 v99, v33, v95
	v_and_or_b32 v20, v20, s0, 8
	v_max_f32_e32 v99, v33, v99
	v_add_f32_e32 v17, v100, v17
	v_min_f32_e32 v101, v99, v20
	v_and_or_b32 v17, v17, s0, 9
	v_max_f32_e32 v101, v99, v101
	v_add_f32_e32 v16, v100, v16
	v_min_f32_e32 v102, v101, v17
	v_and_or_b32 v16, v16, s0, 10
	v_max_f32_e32 v102, v101, v102
	v_add_f32_e32 v15, v100, v15
	v_min_f32_e32 v103, v102, v16
	v_and_or_b32 v15, v15, s0, 11
	v_max_f32_e32 v103, v102, v103
	v_add_f32_e32 v14, v100, v14
	v_min_f32_e32 v104, v103, v15
	v_and_or_b32 v14, v14, s0, 12
	v_max_f32_e32 v104, v103, v104
	v_add_f32_e32 v13, v100, v13
	v_min_f32_e32 v105, v104, v14
	v_and_or_b32 v13, v13, s0, 13
	v_max_f32_e32 v105, v104, v105
	v_add_f32_e32 v6, v100, v6
	v_min_f32_e32 v106, v105, v13
	v_and_or_b32 v6, v6, s0, 14
	v_max_f32_e32 v106, v105, v106
	v_add_f32_e32 v5, v100, v5
	v_min_f32_e32 v107, v106, v6
	v_and_or_b32 v5, v5, s0, 15
	v_max3_f32 v100, v106, v107, v5
	v_max_f32_e32 v106, v106, v6
	v_add_f32_e32 v6, v91, v2
	v_and_or_b32 v6, v6, s0, 16
	v_max_f32_e32 v5, v21, v22
	v_max_f32_e32 v23, v23, v24
	v_min_f32_e32 v21, v5, v6
	v_max_f32_e32 v25, v25, v26
	v_min_f32_e32 v22, v23, v21
	v_min_f32_e32 v24, v25, v22
	v_max_f32_e32 v22, v25, v22
	v_add_f32_e32 v25, v91, v4
; DEV void ce(float& a, float& b) { float hi = fmaxf(a, b), lo = fminf(a, b); a = hi; b = lo; }
; DEV void phase_peer_score(const Params& p, int layer, int M, char* smem) {
;     ...
; #pragma unroll
;     for (int i = 0; i < 16; i++)
; #pragma unroll
;       for (int j = 0; j < 16; j++)
;         if ((i + 1) * (j + 1) <= 16) {
;           float v = L0[i] + L1[j];
;           v = __uint_as_float((__float_as_uint(v) & ~255u) | (unsigned)(i * 16 + j));
; #pragma unroll
;           for (int t = 0; t < 16; t++)
;             if (t >= (i + 1) * (j + 1) - 1) ce(R[t], v);
;         }
	v_and_or_b32 v25, v25, s0, 17
	v_max_f32_e32 v27, v27, v28
	v_max_f32_e32 v29, v29, v30
	v_min_f32_e32 v26, v27, v24
	v_max_f32_e32 v24, v27, v24
	v_min_f32_e32 v27, v22, v25
	v_max_f32_e32 v31, v31, v32
	v_min_f32_e32 v28, v29, v26
	v_max_f32_e32 v26, v29, v26
	v_min_f32_e32 v29, v24, v27
	v_min_f32_e32 v30, v31, v28
	v_max_f32_e32 v28, v31, v28
	v_min_f32_e32 v31, v26, v29
	v_max_f32_e32 v26, v26, v29
	v_add_f32_e32 v29, v91, v7
	v_max_f32_e32 v33, v33, v95
	v_and_or_b32 v29, v29, s0, 18
	v_max_f32_e32 v20, v99, v20
	v_min_f32_e32 v32, v33, v30
	v_min_f32_e32 v95, v20, v32
	v_max_f32_e32 v20, v20, v32
	v_max_f32_e32 v30, v33, v30
	v_min_f32_e32 v32, v28, v31
	v_max_f32_e32 v28, v28, v31
	v_min_f32_e32 v31, v26, v29
	v_max_f32_e32 v17, v101, v17
	v_min_f32_e32 v33, v30, v32
	v_max_f32_e32 v30, v30, v32
	v_min_f32_e32 v32, v28, v31
	v_min_f32_e32 v99, v17, v95
	v_max_f32_e32 v17, v17, v95
	v_min_f32_e32 v95, v20, v33
	v_max_f32_e32 v20, v20, v33
	v_min_f32_e32 v33, v30, v32
	v_max_f32_e32 v30, v30, v32
	v_add_f32_e32 v32, v91, v8
	v_and_or_b32 v32, v32, s0, 19
	v_max_f32_e32 v16, v102, v16
	v_max_f32_e32 v15, v103, v15
	v_min_f32_e32 v101, v16, v99
	v_max_f32_e32 v16, v16, v99
	v_min_f32_e32 v99, v17, v95
	v_max_f32_e32 v17, v17, v95
	v_min_f32_e32 v95, v20, v33
	v_max_f32_e32 v20, v20, v33
	v_min_f32_e32 v33, v30, v32
	v_max_f32_e32 v14, v104, v14
	v_min_f32_e32 v102, v15, v101
	v_max_f32_e32 v15, v15, v101
	v_min_f32_e32 v101, v16, v99
	v_max_f32_e32 v16, v16, v99
	v_min_f32_e32 v99, v17, v95
	v_max_f32_e32 v17, v17, v95
	v_min_f32_e32 v95, v20, v33
	v_min_f32_e32 v103, v14, v102
	v_max_f32_e32 v14, v14, v102
	v_min_f32_e32 v102, v15, v101
	v_max_f32_e32 v15, v15, v101
	v_min_f32_e32 v101, v16, v99
	v_max_f32_e32 v16, v16, v99
	v_min_f32_e32 v99, v17, v95
	v_max_f32_e32 v17, v17, v95
	v_add_f32_e32 v95, v91, v9
	v_max_f32_e32 v13, v105, v13
	v_and_or_b32 v95, v95, s0, 20
	v_min_f32_e32 v104, v13, v103
	v_max_f32_e32 v13, v13, v103
	v_min_f32_e32 v103, v14, v102
	v_min_f32_e32 v105, v106, v104
	v_max_f32_e32 v104, v106, v104
	v_min_f32_e32 v106, v13, v103
	v_max_f32_e32 v14, v14, v102
	v_min_f32_e32 v102, v15, v101
	v_max_f32_e32 v15, v15, v101
	v_min_f32_e32 v101, v16, v99
	v_max_f32_e32 v16, v16, v99
	v_min_f32_e32 v99, v17, v95
	v_add_f32_e32 v12, v91, v12
	v_min_f32_e32 v107, v104, v106
	v_max_f32_e32 v13, v13, v103
	v_min_f32_e32 v103, v14, v102
	v_max_f32_e32 v14, v14, v102
	v_min_f32_e32 v102, v15, v101
	v_max_f32_e32 v15, v15, v101
	v_min_f32_e32 v101, v16, v99
	v_and_or_b32 v12, v12, s0, 21
	v_max_f32_e32 v21, v23, v21
	v_add_f32_e32 v23, v87, v2
	v_max3_f32 v100, v100, v105, v107
	v_max_f32_e32 v104, v104, v106
	v_min_f32_e32 v105, v13, v103
	v_max_f32_e32 v13, v13, v103
	v_min_f32_e32 v103, v14, v102
	v_max_f32_e32 v14, v14, v102
	v_min_f32_e32 v102, v15, v101
	v_max_f32_e32 v15, v15, v101
	v_and_or_b32 v23, v23, s0, 32
	v_min_f32_e32 v106, v104, v105
	v_max_f32_e32 v104, v104, v105
	v_min_f32_e32 v105, v13, v103
	v_max_f32_e32 v13, v13, v103
	v_min_f32_e32 v103, v14, v102
	v_max_f32_e32 v14, v14, v102
	v_min_f32_e32 v101, v15, v12
	v_add_f32_e32 v11, v91, v11
	v_min_f32_e32 v107, v104, v105
	v_max_f32_e32 v104, v104, v105
	v_min_f32_e32 v105, v13, v103
	v_max_f32_e32 v13, v13, v103
	v_min_f32_e32 v102, v14, v101
	v_and_or_b32 v11, v11, s0, 22
	v_max_f32_e32 v22, v22, v25
	v_min_f32_e32 v25, v21, v23
	v_min_f32_e32 v103, v13, v102
	v_max_f32_e32 v13, v13, v102
	v_max_f32_e32 v24, v24, v27
	v_min_f32_e32 v27, v22, v25
	v_min_f32_e32 v102, v13, v11
	v_max_f32_e32 v11, v13, v11
	v_max_f32_e32 v13, v14, v101
	v_max_f32_e32 v14, v16, v99
	v_max_f32_e32 v16, v20, v33
	v_max_f32_e32 v20, v28, v31
	v_max_f32_e32 v26, v26, v29
	v_min_f32_e32 v28, v24, v27
	v_min_f32_e32 v29, v26, v28
	v_max_f32_e32 v26, v26, v28
	v_add_f32_e32 v28, v87, v4
	v_and_or_b32 v28, v28, s0, 33
	v_max_f32_e32 v12, v15, v12
	v_max_f32_e32 v15, v17, v95
	v_max_f32_e32 v17, v30, v32
	v_min_f32_e32 v30, v20, v29
	v_max_f32_e32 v20, v20, v29
	v_min_f32_e32 v29, v26, v28
	v_min_f32_e32 v31, v17, v30
	v_max_f32_e32 v17, v17, v30
	v_min_f32_e32 v30, v20, v29
	v_min_f32_e32 v32, v16, v31
	v_max_f32_e32 v16, v16, v31
	v_min_f32_e32 v31, v17, v30
	v_min_f32_e32 v33, v15, v32
	v_max_f32_e32 v15, v15, v32
	v_min_f32_e32 v32, v16, v31
	v_max_f32_e32 v16, v16, v31
	v_add_f32_e32 v31, v87, v7
	v_and_or_b32 v31, v31, s0, 34
	v_max3_f32 v100, v100, v106, v107
	v_min_f32_e32 v106, v104, v105
	v_max_f32_e32 v104, v104, v105
	v_min_f32_e32 v105, v104, v103
	v_max_f32_e32 v103, v104, v103
	v_add_f32_e32 v10, v91, v10
	v_min_f32_e32 v95, v14, v33
	v_max_f32_e32 v14, v14, v33
	v_min_f32_e32 v33, v15, v32
	v_max_f32_e32 v15, v15, v32
	v_min_f32_e32 v32, v16, v31
	v_max_f32_e32 v22, v22, v25
	v_add_f32_e32 v25, v83, v2
	v_max3_f32 v100, v100, v106, v105
	v_min_f32_e32 v104, v103, v102
	v_and_or_b32 v10, v10, s0, 23
	v_min_f32_e32 v99, v12, v95
	v_max_f32_e32 v12, v12, v95
	v_min_f32_e32 v95, v14, v33
	v_max_f32_e32 v14, v14, v33
	v_min_f32_e32 v33, v15, v32
	v_and_or_b32 v25, v25, s0, 48
	v_max3_f32 v10, v100, v104, v10
	v_min_f32_e32 v100, v13, v99
	v_max_f32_e32 v13, v13, v99
	v_min_f32_e32 v99, v12, v95
	v_max_f32_e32 v12, v12, v95
	v_min_f32_e32 v95, v14, v33
	v_min_f32_e32 v101, v11, v100
	v_max_f32_e32 v11, v11, v100
	v_min_f32_e32 v100, v13, v99
	v_max_f32_e32 v13, v13, v99
	v_min_f32_e32 v99, v12, v95
	v_max_f32_e32 v12, v12, v95
	v_add_f32_e32 v95, v87, v8
	v_max_f32_e32 v24, v24, v27
	v_min_f32_e32 v27, v22, v25
	v_and_or_b32 v95, v95, s0, 35
	v_max_f32_e32 v26, v26, v28
	v_min_f32_e32 v28, v24, v27
	v_max_f32_e32 v91, v103, v102
	v_max_f32_e32 v20, v20, v29
; DEV void ce(float& a, float& b) { float hi = fmaxf(a, b), lo = fminf(a, b); a = hi; b = lo; }
; DEV void phase_peer_score(const Params& p, int layer, int M, char* smem) {
;     ...
; #pragma unroll
;     for (int i = 0; i < 16; i++)
; #pragma unroll
;       for (int j = 0; j < 16; j++)
;         if ((i + 1) * (j + 1) <= 16) {
;           float v = L0[i] + L1[j];
;           v = __uint_as_float((__float_as_uint(v) & ~255u) | (unsigned)(i * 16 + j));
; #pragma unroll
;           for (int t = 0; t < 16; t++)
;             if (t >= (i + 1) * (j + 1) - 1) ce(R[t], v);
;         }
	v_min_f32_e32 v29, v26, v28
	v_min_f32_e32 v102, v91, v101
	v_max_f32_e32 v91, v91, v101
	v_min_f32_e32 v101, v11, v100
	v_max_f32_e32 v11, v11, v100
	v_min_f32_e32 v100, v13, v99
	v_max_f32_e32 v13, v13, v99
	v_min_f32_e32 v99, v12, v95
	v_max_f32_e32 v17, v17, v30
	v_min_f32_e32 v30, v20, v29
	v_min_f32_e32 v103, v91, v101
	v_max_f32_e32 v91, v91, v101
	v_min_f32_e32 v101, v11, v100
	v_max_f32_e32 v11, v11, v100
	v_min_f32_e32 v100, v13, v99
	v_add_f32_e32 v9, v87, v9
	v_max_f32_e32 v16, v16, v31
	v_min_f32_e32 v31, v17, v30
	v_max3_f32 v10, v10, v102, v103
	v_min_f32_e32 v102, v91, v101
	v_max_f32_e32 v91, v91, v101
	v_min_f32_e32 v101, v11, v100
	v_and_or_b32 v9, v9, s0, 36
	v_max_f32_e32 v15, v15, v32
	v_min_f32_e32 v32, v16, v31
	v_min_f32_e32 v103, v91, v101
	v_max_f32_e32 v91, v91, v101
	v_max_f32_e32 v14, v14, v33
	v_min_f32_e32 v33, v15, v32
	v_max_f32_e32 v17, v17, v30
	v_add_f32_e32 v30, v83, v4
	v_min_f32_e32 v87, v91, v9
	v_max_f32_e32 v9, v91, v9
	v_max_f32_e32 v12, v12, v95
	v_min_f32_e32 v91, v14, v33
	v_and_or_b32 v30, v30, s0, 49
	v_max_f32_e32 v24, v24, v27
	v_add_f32_e32 v27, v79, v2
	v_max_f32_e32 v13, v13, v99
	v_min_f32_e32 v95, v12, v91
	v_and_or_b32 v27, v27, s0, 64
	v_max_f32_e32 v11, v11, v100
	v_min_f32_e32 v99, v13, v95
	v_max_f32_e32 v16, v16, v31
	v_min_f32_e32 v31, v17, v30
	v_min_f32_e32 v100, v11, v99
	v_max_f32_e32 v15, v15, v32
	v_min_f32_e32 v32, v16, v31
	v_max_f32_e32 v26, v26, v28
	v_min_f32_e32 v28, v24, v27
	v_max3_f32 v10, v10, v102, v103
	v_min_f32_e32 v101, v9, v100
	v_max_f32_e32 v14, v14, v33
	v_min_f32_e32 v33, v15, v32
	v_max_f32_e32 v20, v20, v29
	v_min_f32_e32 v29, v26, v28
	v_max3_f32 v10, v10, v87, v101
	v_max_f32_e32 v12, v12, v91
	v_min_f32_e32 v87, v14, v33
	v_max_f32_e32 v17, v17, v30
	v_min_f32_e32 v30, v20, v29
	v_min_f32_e32 v91, v12, v87
	v_max_f32_e32 v12, v12, v87
	v_add_f32_e32 v87, v83, v7
	v_max_f32_e32 v16, v16, v31
	v_min_f32_e32 v31, v17, v30
	v_and_or_b32 v87, v87, s0, 50
	v_max_f32_e32 v15, v15, v32
	v_min_f32_e32 v32, v16, v31
	v_max_f32_e32 v13, v13, v95
	v_max_f32_e32 v14, v14, v33
	v_min_f32_e32 v33, v15, v32
	v_max_f32_e32 v11, v11, v99
	v_min_f32_e32 v95, v13, v91
	v_max_f32_e32 v13, v13, v91
	v_min_f32_e32 v91, v12, v87
	v_add_f32_e32 v8, v83, v8
	v_max_f32_e32 v12, v12, v87
	v_min_f32_e32 v83, v14, v33
	v_max_f32_e32 v9, v9, v100
	v_min_f32_e32 v99, v11, v95
	v_max_f32_e32 v11, v11, v95
	v_min_f32_e32 v95, v13, v91
	v_max_f32_e32 v13, v13, v91
	v_min_f32_e32 v87, v12, v83
	v_min_f32_e32 v100, v9, v99
	v_max_f32_e32 v9, v9, v99
	v_min_f32_e32 v99, v11, v95
	v_max_f32_e32 v11, v11, v95
	v_min_f32_e32 v91, v13, v87
	v_min_f32_e32 v101, v9, v99
	v_max_f32_e32 v9, v9, v99
	v_min_f32_e32 v95, v11, v91
	v_max3_f32 v10, v10, v100, v101
	v_and_or_b32 v8, v8, s0, 51
	v_min_f32_e32 v99, v9, v95
	v_max3_f32 v8, v10, v8, v99
	v_max_f32_e32 v10, v11, v91
	v_max_f32_e32 v11, v13, v87
	v_max_f32_e32 v13, v14, v33
	v_max_f32_e32 v14, v15, v32
	v_add_f32_e32 v15, v79, v4
	v_and_b32_e32 v15, 0xffffff00, v15
	v_or_b32_e32 v15, 0x41, v15
	v_min_f32_e32 v32, v14, v15
	v_max_f32_e32 v12, v12, v83
	v_min_f32_e32 v33, v13, v32
	v_min_f32_e32 v83, v12, v33
	v_add_f32_e32 v7, v79, v7
	v_min_f32_e32 v87, v11, v83
	v_and_b32_e32 v7, 0xffffff00, v7
	v_max_f32_e32 v9, v9, v95
	v_min_f32_e32 v91, v10, v87
	v_or_b32_e32 v7, 0x42, v7
	v_min_f32_e32 v95, v9, v91
	v_max_f32_e32 v9, v9, v91
	v_min_f32_e32 v79, v9, v7
	v_max_f32_e32 v7, v9, v7
	v_max_f32_e32 v9, v10, v87
	v_max_f32_e32 v10, v11, v83
	v_max_f32_e32 v11, v12, v33
	v_max_f32_e32 v12, v13, v32
	v_max_f32_e32 v13, v14, v15
	v_max_f32_e32 v14, v16, v31
	v_max_f32_e32 v16, v20, v29
	v_add_f32_e32 v20, v75, v2
	v_and_b32_e32 v20, 0xffffff00, v20
	v_or_b32_e32 v20, 0x50, v20
	v_max_f32_e32 v15, v17, v30
	v_max_f32_e32 v17, v26, v28
	v_min_f32_e32 v26, v17, v20
	v_min_f32_e32 v28, v16, v26
	v_max_f32_e32 v16, v16, v26
	v_add_f32_e32 v26, v71, v2
	v_and_b32_e32 v26, 0xffffff00, v26
	v_min_f32_e32 v29, v15, v28
	v_or_b32_e32 v26, 0x60, v26
	v_min_f32_e32 v30, v14, v29
	v_min_f32_e32 v31, v13, v30
	v_max_f32_e32 v15, v15, v28
	v_min_f32_e32 v28, v16, v26
	v_min_f32_e32 v32, v12, v31
	v_max_f32_e32 v14, v14, v29
	v_min_f32_e32 v29, v15, v28
	v_max_f32_e32 v15, v15, v28
	v_add_f32_e32 v28, v63, v2
	v_min_f32_e32 v33, v11, v32
	v_max_f32_e32 v11, v11, v32
	v_add_f32_e32 v32, v75, v4
	v_and_b32_e32 v28, 0xffffff00, v28
	v_and_b32_e32 v32, 0xffffff00, v32
	v_or_b32_e32 v28, 0x70, v28
	v_or_b32_e32 v32, 0x51, v32
	v_max_f32_e32 v13, v13, v30
	v_min_f32_e32 v30, v14, v29
	v_max_f32_e32 v12, v12, v31
	v_min_f32_e32 v31, v13, v30
	v_max_f32_e32 v14, v14, v29
	v_min_f32_e32 v29, v15, v28
	v_max3_f32 v8, v8, v95, v79
	v_min_f32_e32 v79, v10, v33
	v_max_f32_e32 v10, v10, v33
	v_min_f32_e32 v33, v11, v32
	v_max_f32_e32 v11, v11, v32
	v_min_f32_e32 v32, v12, v31
	v_add_f32_e32 v71, v71, v4
	v_max_f32_e32 v13, v13, v30
	v_min_f32_e32 v30, v14, v29
	v_min_f32_e32 v83, v9, v79
	v_max_f32_e32 v9, v9, v79
	v_min_f32_e32 v75, v10, v33
	v_max_f32_e32 v10, v10, v33
	v_min_f32_e32 v33, v11, v32
	v_and_b32_e32 v71, 0xffffff00, v71
	v_max_f32_e32 v12, v12, v31
	v_min_f32_e32 v31, v13, v30
	v_min_f32_e32 v87, v7, v83
	v_max_f32_e32 v7, v7, v83
	v_min_f32_e32 v79, v9, v75
	v_max_f32_e32 v9, v9, v75
	v_min_f32_e32 v75, v10, v33
	v_or_b32_e32 v71, 0x61, v71
	v_max_f32_e32 v11, v11, v32
	v_min_f32_e32 v32, v12, v31
	v_min_f32_e32 v83, v7, v79
	v_max_f32_e32 v7, v7, v79
	v_min_f32_e32 v79, v9, v75
	v_max_f32_e32 v9, v9, v75
	v_max_f32_e32 v10, v10, v33
	v_min_f32_e32 v33, v11, v32
	v_max3_f32 v8, v8, v87, v83
	v_min_f32_e32 v83, v7, v79
	v_max_f32_e32 v7, v7, v79
; DEV void phase_peer_score(const Params& p, int layer, int M, char* smem) {
;     ...
;     float ev[16]; float sum = 0.f;
; #pragma unroll
;     for (int t = 0; t < 16; t++) { ev[t] = __expf(R[t] - R[0]); sum += ev[t]; }
;     const float inv = 1.f / sum;
;     int eid[16];
; #pragma unroll
;     for (int t = 0; t < 16; t++) {
;       unsigned code = __float_as_uint(R[t]) & 255u;
;       eid[t] = (int)tab[code >> 4] * 128 + (int)tab[16 + (code & 15u)];
	v_min_f32_e32 v75, v9, v71
	v_max_f32_e32 v9, v9, v71
	v_min_f32_e32 v71, v10, v33
	v_add_f32_e32 v4, v63, v4
	v_min_f32_e32 v79, v7, v75
	v_max_f32_e32 v7, v7, v75
	v_min_f32_e32 v75, v9, v71
	v_and_b32_e32 v4, 0xffffff00, v4
	v_max3_f32 v8, v8, v83, v79
	v_min_f32_e32 v79, v7, v75
	v_or_b32_e32 v4, 0x71, v4
	v_max3_f32 v4, v8, v79, v4
	v_max_f32_e32 v8, v9, v71
	v_max_f32_e32 v9, v10, v33
	v_max_f32_e32 v10, v11, v32
	v_max_f32_e32 v11, v12, v31
	v_max_f32_e32 v12, v13, v30
	v_max_f32_e32 v13, v14, v29
	v_add_f32_e32 v14, v67, v2
	v_and_b32_e32 v14, 0xffffff00, v14
	v_or_b32_e32 v14, 0x80, v14
	v_min_f32_e32 v29, v13, v14
	v_min_f32_e32 v30, v12, v29
	v_max_f32_e32 v12, v12, v29
	v_add_f32_e32 v29, v59, v2
	v_and_b32_e32 v29, 0xffffff00, v29
	v_or_b32_e32 v29, 0x90, v29
	v_min_f32_e32 v31, v11, v30
	v_max_f32_e32 v11, v11, v30
	v_min_f32_e32 v30, v12, v29
	v_min_f32_e32 v32, v10, v31
	v_max_f32_e32 v10, v10, v31
	v_min_f32_e32 v31, v11, v30
	v_max_f32_e32 v11, v11, v30
	v_add_f32_e32 v30, v55, v2
	v_and_b32_e32 v30, 0xffffff00, v30
	v_or_b32_e32 v30, 0xa0, v30
	v_min_f32_e32 v33, v9, v32
	v_max_f32_e32 v9, v9, v32
	v_min_f32_e32 v32, v10, v31
	v_max_f32_e32 v10, v10, v31
	v_min_f32_e32 v31, v11, v30
	v_min_f32_e32 v63, v8, v33
	v_max_f32_e32 v8, v8, v33
	v_min_f32_e32 v33, v9, v32
	v_max_f32_e32 v9, v9, v32
	v_min_f32_e32 v32, v10, v31
	v_max_f32_e32 v10, v10, v31
	v_add_f32_e32 v31, v47, v2
	v_and_b32_e32 v31, 0xffffff00, v31
	v_or_b32_e32 v31, 0xb0, v31
	v_min_f32_e32 v59, v8, v33
	v_max_f32_e32 v8, v8, v33
	v_min_f32_e32 v33, v9, v32
	v_max_f32_e32 v9, v9, v32
	v_min_f32_e32 v32, v10, v31
	v_min_f32_e32 v55, v8, v33
	v_max_f32_e32 v8, v8, v33
	v_min_f32_e32 v33, v9, v32
	v_max_f32_e32 v9, v9, v32
	v_add_f32_e32 v32, v51, v2
	v_max_f32_e32 v7, v7, v75
	v_and_b32_e32 v32, 0xffffff00, v32
	v_min_f32_e32 v67, v7, v63
	v_max_f32_e32 v7, v7, v63
	v_or_b32_e32 v32, 0xc0, v32
	v_min_f32_e32 v63, v7, v59
	v_max_f32_e32 v7, v7, v59
	v_min_f32_e32 v59, v7, v55
	v_max_f32_e32 v7, v7, v55
	v_min_f32_e32 v47, v8, v33
	v_max_f32_e32 v8, v8, v33
	v_min_f32_e32 v33, v9, v32
	v_min_f32_e32 v55, v7, v47
	v_max_f32_e32 v7, v7, v47
	v_min_f32_e32 v47, v8, v33
	v_max_f32_e32 v8, v8, v33
	v_add_f32_e32 v33, v39, v2
	v_and_b32_e32 v33, 0xffffff00, v33
	v_or_b32_e32 v33, 0xd0, v33
	v_min_f32_e32 v51, v7, v47
	v_max_f32_e32 v7, v7, v47
	v_min_f32_e32 v39, v8, v33
	v_min_f32_e32 v47, v7, v39
	v_max_f32_e32 v7, v7, v39
	v_add_f32_e32 v39, v43, v2
	v_and_b32_e32 v39, 0xffffff00, v39
	v_max3_f32 v4, v4, v67, v63
	v_or_b32_e32 v39, 0xe0, v39
	v_add_f32_e32 v0, v0, v2
	v_max3_f32 v4, v4, v59, v55
	v_and_b32_e32 v0, 0xffffff00, v0
	v_max3_f32 v4, v4, v51, v47
	v_min_f32_e32 v43, v7, v39
	v_or_b32_e32 v0, 0xf0, v0
	v_max3_f32 v2, v4, v43, v0
	v_max_f32_e32 v13, v13, v14
	v_max_f32_e32 v14, v5, v6
	v_max_f32_e32 v0, 0xff61b1e6, v3
	v_sub_f32_e32 v5, v14, v0
	v_max_f32_e32 v28, v15, v28
	v_max_f32_e32 v15, v21, v23
	v_mul_f32_e32 v5, 0x3fb8aa3b, v5
	v_exp_f32_e32 v101, v5
	v_sub_f32_e32 v5, v15, v0
	v_max_f32_e32 v29, v12, v29
	v_max_f32_e32 v12, v16, v26
	v_max_f32_e32 v16, v22, v25
	v_mul_f32_e32 v5, 0x3fb8aa3b, v5
	v_exp_f32_e32 v104, v5
	v_sub_f32_e32 v5, v16, v0
	v_max_f32_e32 v4, v7, v39
	v_max_f32_e32 v7, v8, v33
	v_max_f32_e32 v8, v9, v32
	v_max_f32_e32 v9, v10, v31
	v_max_f32_e32 v10, v24, v27
	v_mul_f32_e32 v5, 0x3fb8aa3b, v5
	v_exp_f32_e32 v105, v5
	v_sub_f32_e32 v5, v10, v0
	v_max_f32_e32 v30, v11, v30
	v_max_f32_e32 v11, v17, v20
	v_mul_f32_e32 v5, 0x3fb8aa3b, v5
	v_exp_f32_e32 v102, v5
	v_sub_f32_e32 v5, v11, v0
	v_mul_f32_e32 v5, 0x3fb8aa3b, v5
	v_exp_f32_e32 v103, v5
	v_sub_f32_e32 v5, v12, v0
	v_mul_f32_e32 v5, 0x3fb8aa3b, v5
	v_exp_f32_e32 v110, v5
	v_sub_f32_e32 v5, v28, v0
	v_sub_f32_e32 v3, v0, v0
	v_mul_f32_e32 v5, 0x3fb8aa3b, v5
	v_mul_f32_e32 v3, 0x3fb8aa3b, v3
	v_exp_f32_e32 v111, v5
	v_sub_f32_e32 v5, v13, v0
	v_exp_f32_e32 v100, v3
	v_mul_f32_e32 v5, 0x3fb8aa3b, v5
	v_exp_f32_e32 v112, v5
	v_sub_f32_e32 v5, v29, v0
	v_mul_f32_e32 v5, 0x3fb8aa3b, v5
	v_exp_f32_e32 v113, v5
	v_sub_f32_e32 v5, v30, v0
	v_add_f32_e32 v3, 0, v100
	v_mul_f32_e32 v5, 0x3fb8aa3b, v5
	v_add_f32_e32 v3, v3, v101
	v_exp_f32_e32 v114, v5
	v_sub_f32_e32 v5, v9, v0
	v_add_f32_e32 v3, v3, v104
	v_mul_f32_e32 v5, 0x3fb8aa3b, v5
	v_add_f32_e32 v3, v3, v105
	v_exp_f32_e32 v115, v5
	v_sub_f32_e32 v5, v8, v0
	v_add_f32_e32 v3, v3, v102
	v_mul_f32_e32 v5, 0x3fb8aa3b, v5
	v_add_f32_e32 v3, v3, v103
	v_exp_f32_e32 v106, v5
	v_sub_f32_e32 v5, v7, v0
	v_add_f32_e32 v3, v3, v110
	v_mul_f32_e32 v5, 0x3fb8aa3b, v5
	v_add_f32_e32 v3, v3, v111
	v_exp_f32_e32 v107, v5
	v_sub_f32_e32 v5, v4, v0
	v_add_f32_e32 v3, v3, v112
	v_mul_f32_e32 v5, 0x3fb8aa3b, v5
	v_add_f32_e32 v3, v3, v113
	v_exp_f32_e32 v108, v5
	v_sub_f32_e32 v5, v2, v0
	v_add_f32_e32 v3, v3, v114
	v_mul_f32_e32 v5, 0x3fb8aa3b, v5
	v_add_f32_e32 v3, v3, v115
	v_exp_f32_e32 v109, v5
	v_add_f32_e32 v3, v3, v106
	v_add_f32_e32 v3, v3, v107
	v_add_f32_e32 v3, v3, v108
	v_add_f32_e32 v3, v3, v109
	v_div_scale_f32 v5, s[0:1], v3, v3, 1.0
	v_rcp_f32_e32 v6, v5
	v_ashrrev_i32_e32 v19, 31, v18
	s_mov_b32 s0, 0x10000
	v_lshlrev_b64 v[120:121], 9, v[18:19]
	v_fma_f32 v17, -v5, v6, 1.0
	v_fmac_f32_e32 v6, v17, v6
	v_div_scale_f32 v17, vcc, 1.0, v3, 1.0
	v_mul_f32_e32 v20, v17, v6
	v_fma_f32 v21, -v5, v20, v17
	v_fmac_f32_e32 v20, v21, v6
	v_fma_f32 v5, -v5, v20, v17
	v_div_fmas_f32 v5, v5, v6, v20
	v_div_fixup_f32 v116, v5, v3, 1.0
	v_bfe_u32 v3, v2, 4, 4
	v_and_b32_e32 v2, 15, v2
	v_and_b32_e32 v17, 15, v28
	v_add_u32_e32 v3, v138, v3
	v_add_u32_e32 v2, v138, v2
	v_add_u32_e32 v17, v138, v17
	ds_read_u8 v3, v3
	ds_read_u8 v17, v17 offset:16
	ds_read_u8 v2, v2 offset:16
	v_and_b32_e32 v6, 15, v8
	v_add_u32_e32 v6, v138, v6
	ds_read_u8 v6, v6 offset:16
	v_lshl_add_u64 v[18:19], s[8:9], 0, v[120:121]
	s_waitcnt lgkmcnt(1)
; DEV void phase_peer_score(const Params& p, int layer, int M, char* smem) {
;     ...
;     int eid[16];
; #pragma unroll
;     for (int t = 0; t < 16; t++) {
;       unsigned code = __float_as_uint(R[t]) & 255u;
;       eid[t] = (int)tab[code >> 4] * 128 + (int)tab[16 + (code & 15u)];
;     }
	v_lshl_add_u32 v5, v3, 7, v2
	v_bfe_u32 v2, v4, 4, 4
	v_and_b32_e32 v3, 15, v4
	v_add_u32_e32 v2, v138, v2
	v_add_u32_e32 v3, v138, v3
	ds_read_u8 v2, v2
	ds_read_u8 v3, v3 offset:16
	s_lshl_b32 s52, s19, 6
	v_lshl_add_u64 v[118:119], v[18:19], 0, s[52:53]
	v_lshl_add_u64 v[120:121], s[6:7], 0, v[120:121]
	v_lshl_add_u64 v[120:121], v[120:121], 0, s[52:53]
	s_waitcnt lgkmcnt(0)
	v_lshl_add_u32 v4, v2, 7, v3
	v_bfe_u32 v2, v7, 4, 4
	v_and_b32_e32 v3, 15, v7
	v_add_u32_e32 v2, v138, v2
	v_add_u32_e32 v3, v138, v3
	ds_read_u8 v2, v2
	ds_read_u8 v3, v3 offset:16
	v_and_b32_e32 v7, 15, v9
	v_add_u32_e32 v7, v138, v7
	ds_read_u8 v7, v7 offset:16
	s_waitcnt lgkmcnt(1)
	v_lshl_add_u32 v3, v2, 7, v3
	v_bfe_u32 v2, v8, 4, 4
	v_add_u32_e32 v2, v138, v2
	ds_read_u8 v2, v2
	s_waitcnt lgkmcnt(0)
	v_lshl_add_u32 v2, v2, 7, v6
	v_bfe_u32 v6, v9, 4, 4
	v_add_u32_e32 v6, v138, v6
	ds_read_u8 v6, v6
	s_waitcnt lgkmcnt(0)
	v_lshl_add_u32 v9, v6, 7, v7
	v_bfe_u32 v6, v30, 4, 4
	v_and_b32_e32 v7, 15, v30
	v_add_u32_e32 v6, v138, v6
	v_add_u32_e32 v7, v138, v7
	ds_read_u8 v6, v6
	ds_read_u8 v7, v7 offset:16
	s_waitcnt lgkmcnt(0)
	v_lshl_add_u32 v8, v6, 7, v7
	v_bfe_u32 v6, v29, 4, 4
	v_and_b32_e32 v7, 15, v29
	v_add_u32_e32 v6, v138, v6
	v_add_u32_e32 v7, v138, v7
	ds_read_u8 v6, v6
	ds_read_u8 v7, v7 offset:16
	s_waitcnt lgkmcnt(0)
	v_lshl_add_u32 v7, v6, 7, v7
	v_bfe_u32 v6, v13, 4, 4
	v_and_b32_e32 v13, 15, v13
	v_add_u32_e32 v6, v138, v6
	v_add_u32_e32 v13, v138, v13
	ds_read_u8 v6, v6
	ds_read_u8 v13, v13 offset:16
	s_waitcnt lgkmcnt(0)
	v_lshl_add_u32 v6, v6, 7, v13
	v_bfe_u32 v13, v28, 4, 4
	v_add_u32_e32 v13, v138, v13
	ds_read_u8 v13, v13
	s_waitcnt lgkmcnt(0)
	v_lshl_add_u32 v13, v13, 7, v17
	v_bfe_u32 v17, v12, 4, 4
	v_and_b32_e32 v12, 15, v12
	v_add_u32_e32 v17, v138, v17
	v_add_u32_e32 v12, v138, v12
	ds_read_u8 v17, v17
	ds_read_u8 v12, v12 offset:16
	s_waitcnt lgkmcnt(0)
	v_lshl_add_u32 v12, v17, 7, v12
	v_bfe_u32 v17, v11, 4, 4
	v_and_b32_e32 v11, 15, v11
	v_add_u32_e32 v17, v138, v17
	v_add_u32_e32 v11, v138, v11
	ds_read_u8 v17, v17
	ds_read_u8 v11, v11 offset:16
	s_waitcnt lgkmcnt(0)
	v_lshl_add_u32 v11, v17, 7, v11
	v_bfe_u32 v17, v10, 4, 4
	v_and_b32_e32 v10, 15, v10
	v_add_u32_e32 v17, v138, v17
	v_add_u32_e32 v10, v138, v10
	ds_read_u8 v17, v17
	ds_read_u8 v10, v10 offset:16
	s_waitcnt lgkmcnt(0)
	v_lshl_add_u32 v10, v17, 7, v10
	v_bfe_u32 v17, v16, 4, 4
	v_and_b32_e32 v16, 15, v16
	v_add_u32_e32 v17, v138, v17
	v_add_u32_e32 v16, v138, v16
	ds_read_u8 v17, v17
	ds_read_u8 v16, v16 offset:16
	s_waitcnt lgkmcnt(0)
	v_lshl_add_u32 v17, v17, 7, v16
	v_bfe_u32 v16, v15, 4, 4
	v_and_b32_e32 v15, 15, v15
	v_add_u32_e32 v16, v138, v16
	v_add_u32_e32 v15, v138, v15
	ds_read_u8 v16, v16
	ds_read_u8 v15, v15 offset:16
	s_waitcnt lgkmcnt(0)
	v_lshl_add_u32 v16, v16, 7, v15
	v_bfe_u32 v15, v14, 4, 4
	v_and_b32_e32 v14, 15, v14
	v_add_u32_e32 v15, v138, v15
	v_add_u32_e32 v14, v138, v14
	ds_read_u8 v15, v15
	ds_read_u8 v14, v14 offset:16
	s_waitcnt lgkmcnt(0)
	v_lshl_add_u32 v15, v15, 7, v14
	v_bfe_u32 v14, v0, 4, 4
	v_and_b32_e32 v0, 15, v0
	v_add_u32_e32 v14, v138, v14
	v_add_u32_e32 v0, v138, v0
	ds_read_u8 v14, v14
	ds_read_u8 v0, v0 offset:16
	s_waitcnt lgkmcnt(0)
; DEV void phase_peer_score(const Params& p, int layer, int M, char* smem) {
;     ...
;     if (quad == 0) {
;       int* eo = EIDX + (size_t)m * 128 + h * 16;
;       float* go = GATE + (size_t)m * 128 + h * 16;
;       float* uo = go + (size_t)MT * 128;
;       float us[16], vs[16];
; #pragma unroll
;       for (int t = 0; t < 16; t++) { us[t] = USC[eid[t]]; vs[t] = USC[16384 + eid[t]]; }
; #pragma unroll
;       for (int t = 0; t < 16; t += 4) {
;         *(int4*)(eo + t) = make_int4(eid[t], eid[t + 1], eid[t + 2], eid[t + 3]);
;         *(float4*)(go + t) = make_float4(ev[t] * inv * vs[t], ev[t + 1] * inv * vs[t + 1], ev[t + 2] * inv * vs[t + 2], ev[t + 3] * inv * vs[t + 3]);
;         *(float4*)(uo + t) = make_float4(us[t], us[t + 1], us[t + 2], us[t + 3]);
;       }
;     }
	v_lshl_add_u32 v14, v14, 7, v0
	v_lshlrev_b32_e32 v0, 2, v14
	v_lshl_add_u64 v[20:21], s[10:11], 0, v[0:1]
	v_add_co_u32_e32 v20, vcc, s0, v20
	global_load_dword v18, v0, s[10:11]
	s_nop 0
	v_addc_co_u32_e32 v21, vcc, 0, v21, vcc
	global_load_dword v122, v[20:21], off
	v_lshlrev_b32_e32 v0, 2, v15
	v_lshl_add_u64 v[20:21], s[10:11], 0, v[0:1]
	v_add_co_u32_e32 v20, vcc, s0, v20
	global_load_dword v19, v0, s[10:11]
	s_nop 0
	v_addc_co_u32_e32 v21, vcc, 0, v21, vcc
	global_load_dword v123, v[20:21], off
	v_lshlrev_b32_e32 v0, 2, v16
	v_lshl_add_u64 v[22:23], s[10:11], 0, v[0:1]
	v_add_co_u32_e32 v22, vcc, s0, v22
	global_load_dword v20, v0, s[10:11]
	s_nop 0
	v_addc_co_u32_e32 v23, vcc, 0, v23, vcc
	global_load_dword v126, v[22:23], off
	v_lshlrev_b32_e32 v0, 2, v17
	v_lshl_add_u64 v[22:23], s[10:11], 0, v[0:1]
	v_add_co_u32_e32 v22, vcc, s0, v22
	global_load_dword v21, v0, s[10:11]
	s_nop 0
	v_addc_co_u32_e32 v23, vcc, 0, v23, vcc
	global_load_dword v127, v[22:23], off
	v_lshlrev_b32_e32 v0, 2, v10
	v_lshl_add_u64 v[24:25], s[10:11], 0, v[0:1]
	v_add_co_u32_e32 v24, vcc, s0, v24
	global_load_dword v22, v0, s[10:11]
	s_nop 0
	v_addc_co_u32_e32 v25, vcc, 0, v25, vcc
	global_load_dword v124, v[24:25], off
	v_lshlrev_b32_e32 v0, 2, v11
	v_lshl_add_u64 v[24:25], s[10:11], 0, v[0:1]
	v_add_co_u32_e32 v24, vcc, s0, v24
	global_load_dword v23, v0, s[10:11]
	s_nop 0
	v_addc_co_u32_e32 v25, vcc, 0, v25, vcc
	global_load_dword v125, v[24:25], off
	v_lshlrev_b32_e32 v0, 2, v12
	v_lshl_add_u64 v[26:27], s[10:11], 0, v[0:1]
	v_add_co_u32_e32 v26, vcc, s0, v26
	global_load_dword v24, v0, s[10:11]
	s_nop 0
	v_addc_co_u32_e32 v27, vcc, 0, v27, vcc
	global_load_dword v128, v[26:27], off
	v_lshlrev_b32_e32 v0, 2, v13
	v_lshl_add_u64 v[26:27], s[10:11], 0, v[0:1]
	v_add_co_u32_e32 v26, vcc, s0, v26
	global_load_dword v25, v0, s[10:11]
	s_nop 0
	v_addc_co_u32_e32 v27, vcc, 0, v27, vcc
	global_load_dword v129, v[26:27], off
	v_lshlrev_b32_e32 v0, 2, v6
	v_lshl_add_u64 v[28:29], s[10:11], 0, v[0:1]
	v_add_co_u32_e32 v28, vcc, s0, v28
	global_load_dword v26, v0, s[10:11]
	s_nop 0
	v_addc_co_u32_e32 v29, vcc, 0, v29, vcc
	global_load_dword v130, v[28:29], off
	v_lshlrev_b32_e32 v0, 2, v7
	v_lshl_add_u64 v[28:29], s[10:11], 0, v[0:1]
	v_add_co_u32_e32 v28, vcc, s0, v28
	global_load_dword v27, v0, s[10:11]
	s_nop 0
	v_addc_co_u32_e32 v29, vcc, 0, v29, vcc
	global_load_dword v131, v[28:29], off
	v_lshlrev_b32_e32 v0, 2, v8
	v_lshl_add_u64 v[30:31], s[10:11], 0, v[0:1]
	v_add_co_u32_e32 v30, vcc, s0, v30
	global_load_dword v28, v0, s[10:11]
	s_nop 0
	v_addc_co_u32_e32 v31, vcc, 0, v31, vcc
	global_load_dword v132, v[30:31], off
	v_lshlrev_b32_e32 v0, 2, v9
	v_lshl_add_u64 v[30:31], s[10:11], 0, v[0:1]
	v_add_co_u32_e32 v30, vcc, s0, v30
	global_load_dword v29, v0, s[10:11]
	s_nop 0
	v_addc_co_u32_e32 v31, vcc, 0, v31, vcc
	global_load_dword v133, v[30:31], off
	v_lshlrev_b32_e32 v0, 2, v2
	v_lshl_add_u64 v[32:33], s[10:11], 0, v[0:1]
	v_add_co_u32_e32 v32, vcc, s0, v32
	global_load_dword v30, v0, s[10:11]
	s_nop 0
	v_addc_co_u32_e32 v33, vcc, 0, v33, vcc
	global_load_dword v134, v[32:33], off
	v_lshlrev_b32_e32 v0, 2, v3
	v_lshl_add_u64 v[32:33], s[10:11], 0, v[0:1]
	v_add_co_u32_e32 v32, vcc, s0, v32
	global_load_dword v31, v0, s[10:11]
	s_nop 0
	v_addc_co_u32_e32 v33, vcc, 0, v33, vcc
	global_load_dword v135, v[32:33], off
	v_lshlrev_b32_e32 v0, 2, v4
	v_lshl_add_u64 v[136:137], s[10:11], 0, v[0:1]
	v_add_co_u32_e32 v136, vcc, s0, v136
	global_load_dword v32, v0, s[10:11]
	s_nop 0
	v_addc_co_u32_e32 v137, vcc, 0, v137, vcc
	global_load_dword v136, v[136:137], off
	v_lshlrev_b32_e32 v0, 2, v5
	v_lshl_add_u64 v[140:141], s[10:11], 0, v[0:1]
	v_add_co_u32_e32 v140, vcc, s0, v140
	global_load_dword v33, v0, s[10:11]
	s_nop 0
	v_addc_co_u32_e32 v141, vcc, 0, v141, vcc
	global_load_dword v137, v[140:141], off
	s_mov_b32 s0, 0x840000
	global_store_dwordx4 v[120:121], v[14:17], off
	s_nop 1
	v_pk_mul_f32 v[14:15], v[100:101], v[116:117] op_sel_hi:[1,0]
	v_pk_mul_f32 v[16:17], v[104:105], v[116:117] op_sel_hi:[1,0]
	s_waitcnt vmcnt(29)
	v_pk_mul_f32 v[14:15], v[14:15], v[122:123]
	s_waitcnt vmcnt(25)
	v_pk_mul_f32 v[16:17], v[16:17], v[126:127]
	global_store_dwordx4 v[118:119], v[14:17], off
	s_nop 1
	v_add_co_u32_e32 v14, vcc, s0, v118
	s_nop 1
	v_addc_co_u32_e32 v15, vcc, 0, v119, vcc
	global_store_dwordx4 v[14:15], v[18:21], off
	global_store_dwordx4 v[120:121], v[10:13], off offset:16
	s_nop 1
	v_pk_mul_f32 v[10:11], v[102:103], v[116:117] op_sel_hi:[1,0]
	v_pk_mul_f32 v[12:13], v[110:111], v[116:117] op_sel_hi:[1,0]
	s_waitcnt vmcnt(24)
	v_pk_mul_f32 v[10:11], v[10:11], v[124:125]
	s_waitcnt vmcnt(20)
	v_pk_mul_f32 v[12:13], v[12:13], v[128:129]
	global_store_dwordx4 v[118:119], v[10:13], off offset:16
	global_store_dwordx4 v[14:15], v[22:25], off offset:16
	global_store_dwordx4 v[120:121], v[6:9], off offset:32
	s_nop 1
	v_pk_mul_f32 v[6:7], v[112:113], v[116:117] op_sel_hi:[1,0]
	v_pk_mul_f32 v[8:9], v[114:115], v[116:117] op_sel_hi:[1,0]
	s_waitcnt vmcnt(19)
	v_pk_mul_f32 v[6:7], v[6:7], v[130:131]
	s_waitcnt vmcnt(15)
	v_pk_mul_f32 v[8:9], v[8:9], v[132:133]
	global_store_dwordx4 v[118:119], v[6:9], off offset:32
	global_store_dwordx4 v[14:15], v[26:29], off offset:32
	global_store_dwordx4 v[120:121], v[2:5], off offset:48
	s_nop 1
	v_pk_mul_f32 v[2:3], v[106:107], v[116:117] op_sel_hi:[1,0]
	v_pk_mul_f32 v[4:5], v[108:109], v[116:117] op_sel_hi:[1,0]
	s_waitcnt vmcnt(14)
	v_pk_mul_f32 v[2:3], v[2:3], v[134:135]
	s_waitcnt vmcnt(10)
	v_pk_mul_f32 v[4:5], v[4:5], v[136:137]
	global_store_dwordx4 v[118:119], v[2:5], off offset:48
	global_store_dwordx4 v[14:15], v[30:33], off offset:48
	s_branch .LBB0_162

; DEV void phase_peer_score(const Params& p, int layer, int M, char* smem) {
;     ...
;     if (h != hcur) {
;       hcur = h;
;       __syncthreads();
; #pragma unroll
;       for (int i = 0; i < 16; i++) {
;         int id = tid + i * 256; int row = id >> 4, cc = id & 15;
;         *(uint4*)(SKs + row * 144 + cc * 8) = *(const uint4*)(SK + ((size_t)h * 256 + row) * 128 + cc * 8);
;       }
;       __syncthreads();
;     }
.LBB0_628:
	s_and_b32 s17, s16, 7
	s_cmp_lg_u32 s17, s15
	s_mov_b64 s[8:9], -1
	s_cbranch_scc0 .LBB0_630
	s_lshl_b32 s52, s17, 8
	s_waitcnt lgkmcnt(0)
	s_barrier
	s_mov_b64 s[8:9], 0
	v_lshl_add_u64 v[2:3], s[52:53], 0, v[36:37]
	v_lshlrev_b64 v[2:3], 8, v[2:3]
	v_lshl_add_u64 v[2:3], v[34:35], 0, v[2:3]
	global_load_dwordx4 v[148:151], v[2:3], off
	v_lshl_add_u64 v[2:3], s[52:53], 0, v[40:41]
	v_lshlrev_b64 v[2:3], 8, v[2:3]
	v_lshl_add_u64 v[2:3], v[34:35], 0, v[2:3]
	global_load_dwordx4 v[152:155], v[2:3], off
	v_lshl_add_u64 v[2:3], s[52:53], 0, v[44:45]
	v_lshlrev_b64 v[2:3], 8, v[2:3]
	v_lshl_add_u64 v[2:3], v[34:35], 0, v[2:3]
	global_load_dwordx4 v[156:159], v[2:3], off
	v_lshl_add_u64 v[2:3], s[52:53], 0, v[48:49]
	v_lshlrev_b64 v[2:3], 8, v[2:3]
	v_lshl_add_u64 v[2:3], v[34:35], 0, v[2:3]
	global_load_dwordx4 v[160:163], v[2:3], off
	v_lshl_add_u64 v[2:3], s[52:53], 0, v[52:53]
	v_lshlrev_b64 v[2:3], 8, v[2:3]
	v_lshl_add_u64 v[2:3], v[34:35], 0, v[2:3]
	global_load_dwordx4 v[164:167], v[2:3], off
	v_lshl_add_u64 v[2:3], s[52:53], 0, v[56:57]
	v_lshlrev_b64 v[2:3], 8, v[2:3]
	v_lshl_add_u64 v[2:3], v[34:35], 0, v[2:3]
	global_load_dwordx4 v[168:171], v[2:3], off
	v_lshl_add_u64 v[2:3], s[52:53], 0, v[60:61]
	v_lshlrev_b64 v[2:3], 8, v[2:3]
	v_lshl_add_u64 v[2:3], v[34:35], 0, v[2:3]
	global_load_dwordx4 v[172:175], v[2:3], off
	v_lshl_add_u64 v[2:3], s[52:53], 0, v[64:65]
	v_lshlrev_b64 v[2:3], 8, v[2:3]
	v_lshl_add_u64 v[2:3], v[34:35], 0, v[2:3]
	global_load_dwordx4 v[176:179], v[2:3], off
	s_waitcnt vmcnt(7)
	ds_write_b128 v38, v[148:151]
	v_lshl_add_u64 v[2:3], s[52:53], 0, v[68:69]
	v_lshlrev_b64 v[2:3], 8, v[2:3]
	v_lshl_add_u64 v[2:3], v[34:35], 0, v[2:3]
	global_load_dwordx4 v[148:151], v[2:3], off
	s_waitcnt vmcnt(7)
	ds_write_b128 v42, v[152:155]
	v_lshl_add_u64 v[2:3], s[52:53], 0, v[72:73]
	v_lshlrev_b64 v[2:3], 8, v[2:3]
	v_lshl_add_u64 v[2:3], v[34:35], 0, v[2:3]
	global_load_dwordx4 v[152:155], v[2:3], off
	s_waitcnt vmcnt(7)
	ds_write_b128 v46, v[156:159]
	v_lshl_add_u64 v[2:3], s[52:53], 0, v[76:77]
	v_lshlrev_b64 v[2:3], 8, v[2:3]
	v_lshl_add_u64 v[2:3], v[34:35], 0, v[2:3]
	global_load_dwordx4 v[156:159], v[2:3], off
	s_waitcnt vmcnt(7)
	ds_write_b128 v50, v[160:163]
	v_lshl_add_u64 v[2:3], s[52:53], 0, v[80:81]
	v_lshlrev_b64 v[2:3], 8, v[2:3]
	v_lshl_add_u64 v[2:3], v[34:35], 0, v[2:3]
	global_load_dwordx4 v[160:163], v[2:3], off
	s_waitcnt vmcnt(7)
	ds_write_b128 v54, v[164:167]
	v_lshl_add_u64 v[2:3], s[52:53], 0, v[84:85]
	v_lshlrev_b64 v[2:3], 8, v[2:3]
	v_lshl_add_u64 v[2:3], v[34:35], 0, v[2:3]
	global_load_dwordx4 v[164:167], v[2:3], off
	s_waitcnt vmcnt(7)
	ds_write_b128 v58, v[168:171]
	v_lshl_add_u64 v[2:3], s[52:53], 0, v[88:89]
	v_lshlrev_b64 v[2:3], 8, v[2:3]
	v_lshl_add_u64 v[2:3], v[34:35], 0, v[2:3]
	global_load_dwordx4 v[168:171], v[2:3], off
	s_waitcnt vmcnt(7)
	ds_write_b128 v62, v[172:175]
	v_lshl_add_u64 v[2:3], s[52:53], 0, v[92:93]
	v_lshlrev_b64 v[2:3], 8, v[2:3]
	v_lshl_add_u64 v[2:3], v[34:35], 0, v[2:3]
	global_load_dwordx4 v[172:175], v[2:3], off
	s_waitcnt vmcnt(7)
	ds_write_b128 v66, v[176:179]
	v_lshl_add_u64 v[2:3], s[52:53], 0, v[96:97]
	v_lshlrev_b64 v[2:3], 8, v[2:3]
	v_lshl_add_u64 v[2:3], v[34:35], 0, v[2:3]
	global_load_dwordx4 v[176:179], v[2:3], off
	s_waitcnt vmcnt(7)
	ds_write_b128 v70, v[148:151]
	s_waitcnt vmcnt(6)
	ds_write_b128 v74, v[152:155]
	s_waitcnt vmcnt(5)
	ds_write_b128 v78, v[156:159]
	s_waitcnt vmcnt(4)
	ds_write_b128 v82, v[160:163]
	s_waitcnt vmcnt(3)
	ds_write_b128 v86, v[164:167]
	s_waitcnt vmcnt(2)
	ds_write_b128 v90, v[168:171]
	s_waitcnt vmcnt(1)
	ds_write_b128 v94, v[172:175]
	s_waitcnt vmcnt(0)
	ds_write_b128 v98, v[176:179]
	s_waitcnt lgkmcnt(0)
	s_barrier

; DEV f32x4 mfma16(bf16x8 a, bf16x8 b, f32x4 c) { return __builtin_amdgcn_mfma_f32_16x16x32_bf16(a, b, c, 0, 0, 0); }
; DEV void peer_top16(const bf16_t* __restrict__ pq, const bf16_t* sk  , float (&l)[16]) {
;     ...
; #pragma unroll 1
;   for (int ks = 0; ks < 4; ks++) {
;     const bf16x8 bqk = *(const bf16x8*)(pq + ks * 32 + quad * 8);
; #pragma unroll
;     for (int nt = 0; nt < 8; nt++) {
;       bf16x8 ak = *(const bf16x8*)(sk + (nt * 16 + l15) * 144 + ks * 32 + quad * 8);
;       acc[nt] = mfma16(ak, bqk, acc[nt]);
;     }
;   }
.LBB0_633:
	global_load_dwordx4 v[148:151], v[102:103], off
	global_load_dwordx4 v[152:155], v[102:103], off offset:64
	global_load_dwordx4 v[156:159], v[102:103], off offset:128
	global_load_dwordx4 v[160:163], v[102:103], off offset:192
	ds_read_b128 v[164:167], v39
	ds_read_b128 v[168:171], v39 offset:4608
	ds_read_b128 v[172:175], v39 offset:9216
	ds_read_b128 v[176:179], v39 offset:13824
	ds_read_b128 v[180:183], v39 offset:18432
	ds_read_b128 v[184:187], v39 offset:23040
	ds_read_b128 v[188:191], v39 offset:27648
	ds_read_b128 v[108:111], v39 offset:32256
	s_waitcnt vmcnt(3) lgkmcnt(7)
	v_mfma_f32_16x16x32_bf16 v[30:33], v[164:167], v[148:151], v[30:33]
	ds_read_b128 v[164:167], v39 offset:64
	s_waitcnt lgkmcnt(7)
	v_mfma_f32_16x16x32_bf16 v[22:25], v[168:171], v[148:151], v[22:25]
	ds_read_b128 v[168:171], v39 offset:4672
	s_waitcnt lgkmcnt(7)
	v_mfma_f32_16x16x32_bf16 v[14:17], v[172:175], v[148:151], v[14:17]
	ds_read_b128 v[172:175], v39 offset:9280
	s_waitcnt lgkmcnt(7)
	v_mfma_f32_16x16x32_bf16 v[6:9], v[176:179], v[148:151], v[6:9]
	ds_read_b128 v[176:179], v39 offset:13888
	s_waitcnt lgkmcnt(7)
	v_mfma_f32_16x16x32_bf16 v[26:29], v[180:183], v[148:151], v[26:29]
	ds_read_b128 v[180:183], v39 offset:18496
	s_waitcnt lgkmcnt(7)
	v_mfma_f32_16x16x32_bf16 v[18:21], v[184:187], v[148:151], v[18:21]
	ds_read_b128 v[184:187], v39 offset:23104
	s_waitcnt lgkmcnt(7)
	v_mfma_f32_16x16x32_bf16 v[10:13], v[188:191], v[148:151], v[10:13]
	ds_read_b128 v[188:191], v39 offset:27712
	s_waitcnt lgkmcnt(7)
	v_mfma_f32_16x16x32_bf16 v[2:5], v[108:111], v[148:151], v[2:5]
	ds_read_b128 v[108:111], v39 offset:32320
	global_load_dwordx4 v[148:151], v[102:103], off offset:256
	s_waitcnt vmcnt(3) lgkmcnt(7)
	v_mfma_f32_16x16x32_bf16 v[30:33], v[164:167], v[152:155], v[30:33]
	ds_read_b128 v[164:167], v39 offset:128
	s_waitcnt lgkmcnt(7)
	v_mfma_f32_16x16x32_bf16 v[22:25], v[168:171], v[152:155], v[22:25]
	ds_read_b128 v[168:171], v39 offset:4736
	s_waitcnt lgkmcnt(7)
	v_mfma_f32_16x16x32_bf16 v[14:17], v[172:175], v[152:155], v[14:17]
	ds_read_b128 v[172:175], v39 offset:9344
	s_waitcnt lgkmcnt(7)
	v_mfma_f32_16x16x32_bf16 v[6:9], v[176:179], v[152:155], v[6:9]
	ds_read_b128 v[176:179], v39 offset:13952
	s_waitcnt lgkmcnt(7)
	v_mfma_f32_16x16x32_bf16 v[26:29], v[180:183], v[152:155], v[26:29]
	ds_read_b128 v[180:183], v39 offset:18560
	s_waitcnt lgkmcnt(7)
	v_mfma_f32_16x16x32_bf16 v[18:21], v[184:187], v[152:155], v[18:21]
	ds_read_b128 v[184:187], v39 offset:23168
	s_waitcnt lgkmcnt(7)
	v_mfma_f32_16x16x32_bf16 v[10:13], v[188:191], v[152:155], v[10:13]
	ds_read_b128 v[188:191], v39 offset:27776
	s_waitcnt lgkmcnt(7)
	v_mfma_f32_16x16x32_bf16 v[2:5], v[108:111], v[152:155], v[2:5]
	ds_read_b128 v[108:111], v39 offset:32384
	global_load_dwordx4 v[152:155], v[102:103], off offset:320
	s_waitcnt vmcnt(3) lgkmcnt(7)
	v_mfma_f32_16x16x32_bf16 v[30:33], v[164:167], v[156:159], v[30:33]
	ds_read_b128 v[164:167], v39 offset:192
	s_waitcnt lgkmcnt(7)
	v_mfma_f32_16x16x32_bf16 v[22:25], v[168:171], v[156:159], v[22:25]
	ds_read_b128 v[168:171], v39 offset:4800
	s_waitcnt lgkmcnt(7)
	v_mfma_f32_16x16x32_bf16 v[14:17], v[172:175], v[156:159], v[14:17]
	ds_read_b128 v[172:175], v39 offset:9408
	s_waitcnt lgkmcnt(7)
	v_mfma_f32_16x16x32_bf16 v[6:9], v[176:179], v[156:159], v[6:9]
	ds_read_b128 v[176:179], v39 offset:14016
	s_waitcnt lgkmcnt(7)
	v_mfma_f32_16x16x32_bf16 v[26:29], v[180:183], v[156:159], v[26:29]
	ds_read_b128 v[180:183], v39 offset:18624
	s_waitcnt lgkmcnt(7)
	v_mfma_f32_16x16x32_bf16 v[18:21], v[184:187], v[156:159], v[18:21]
	ds_read_b128 v[184:187], v39 offset:23232
	s_waitcnt lgkmcnt(7)
	v_mfma_f32_16x16x32_bf16 v[10:13], v[188:191], v[156:159], v[10:13]
	ds_read_b128 v[188:191], v39 offset:27840
	s_waitcnt lgkmcnt(7)
	v_mfma_f32_16x16x32_bf16 v[2:5], v[108:111], v[156:159], v[2:5]
	ds_read_b128 v[108:111], v39 offset:32448
	global_load_dwordx4 v[156:159], v[102:103], off offset:384
	s_waitcnt vmcnt(3) lgkmcnt(7)
	v_mfma_f32_16x16x32_bf16 v[30:33], v[164:167], v[160:163], v[30:33]
	s_waitcnt lgkmcnt(6)
	v_mfma_f32_16x16x32_bf16 v[22:25], v[168:171], v[160:163], v[22:25]
	s_waitcnt lgkmcnt(5)
	v_mfma_f32_16x16x32_bf16 v[14:17], v[172:175], v[160:163], v[14:17]
	s_waitcnt lgkmcnt(4)
	v_mfma_f32_16x16x32_bf16 v[6:9], v[176:179], v[160:163], v[6:9]
	s_waitcnt lgkmcnt(3)
	v_mfma_f32_16x16x32_bf16 v[26:29], v[180:183], v[160:163], v[26:29]
	s_waitcnt lgkmcnt(2)
	v_mfma_f32_16x16x32_bf16 v[18:21], v[184:187], v[160:163], v[18:21]
	s_waitcnt lgkmcnt(1)
	v_mfma_f32_16x16x32_bf16 v[10:13], v[188:191], v[160:163], v[10:13]
	s_waitcnt lgkmcnt(0)
; DEV f32x4 mfma16(bf16x8 a, bf16x8 b, f32x4 c) { return __builtin_amdgcn_mfma_f32_16x16x32_bf16(a, b, c, 0, 0, 0); }
; DEV void peer_top16(const bf16_t* __restrict__ pq, const bf16_t* sk  , float (&l)[16]) {
;     ...
;     const bf16x8 bqk = *(const bf16x8*)(pq + ks * 32 + quad * 8);
; #pragma unroll
;     for (int nt = 0; nt < 8; nt++) {
;       bf16x8 ak = *(const bf16x8*)(sk + (nt * 16 + l15) * 144 + ks * 32 + quad * 8);
;       acc[nt] = mfma16(ak, bqk, acc[nt]);
;     }
;   }
;   float hi[16];
; #pragma unroll
;   for (int nt = 0; nt < 4; nt++)
; #pragma unroll
;     for (int r = 0; r < 4; r++) {
;       l[nt * 4 + r] = __uint_as_float((__float_as_uint(acc[nt][r]) & ~127u) | (unsigned)(nt * 16 + quad * 4 + r));
;       hi[nt * 4 + r] = __uint_as_float((__float_as_uint(acc[nt + 4][r]) & ~127u) | (unsigned)((nt + 4) * 16 + quad * 4 + r));
;     }
;   sort16_desc(l);
	v_mfma_f32_16x16x32_bf16 v[2:5], v[108:111], v[160:163], v[2:5]
	global_load_dwordx4 v[160:163], v[102:103], off offset:448
	s_movk_i32 s18, 0x100
	v_lshlrev_b32_e32 v0, 2, v0
	s_movk_i32 s18, 0xff80
	v_and_or_b32 v30, v30, s18, v0
	v_and_b32_e32 v27, 0xffffff80, v27
	s_movk_i32 s18, 0x41
	v_or3_b32 v27, v0, v27, s18
	v_and_b32_e32 v28, 0xffffff80, v28
	s_movk_i32 s18, 0x42
	v_or3_b32 v28, v0, v28, s18
	v_and_b32_e32 v29, 0xffffff80, v29
	s_movk_i32 s18, 0x43
	v_or3_b32 v29, v0, v29, s18
	v_and_b32_e32 v18, 0xffffff80, v18
	s_movk_i32 s18, 0x50
	v_or3_b32 v18, v0, v18, s18
	v_and_b32_e32 v19, 0xffffff80, v19
	s_movk_i32 s18, 0x51
	v_or3_b32 v19, v0, v19, s18
	v_and_b32_e32 v20, 0xffffff80, v20
	s_movk_i32 s18, 0x52
	v_or3_b32 v20, v0, v20, s18
	v_and_b32_e32 v21, 0xffffff80, v21
	s_movk_i32 s18, 0x53
	v_or3_b32 v21, v0, v21, s18
	v_and_b32_e32 v10, 0xffffff80, v10
	s_movk_i32 s18, 0x60
	v_or3_b32 v10, v0, v10, s18
	v_and_b32_e32 v11, 0xffffff80, v11
	s_movk_i32 s18, 0x61
	v_or3_b32 v11, v0, v11, s18
	v_and_b32_e32 v12, 0xffffff80, v12
	s_movk_i32 s18, 0x62
	v_or3_b32 v12, v0, v12, s18
	v_and_b32_e32 v13, 0xffffff80, v13
	s_movk_i32 s18, 0x63
	v_or3_b32 v13, v0, v13, s18
	v_and_b32_e32 v2, 0xffffff80, v2
	s_movk_i32 s18, 0x70
	v_or3_b32 v2, v0, v2, s18
	v_and_b32_e32 v3, 0xffffff80, v3
	s_movk_i32 s18, 0x71
	v_and_b32_e32 v26, 0xffffff80, v26
	v_and_b32_e32 v31, 0xffffff80, v31
	v_or3_b32 v3, v0, v3, s18
	v_and_b32_e32 v4, 0xffffff80, v4
	s_movk_i32 s18, 0x72
	v_or3_b32 v26, v0, v26, 64
	v_or3_b32 v31, v0, v31, 1
	v_and_b32_e32 v32, 0xffffff80, v32
	v_and_b32_e32 v33, 0xffffff80, v33
	v_and_b32_e32 v22, 0xffffff80, v22
	v_and_b32_e32 v23, 0xffffff80, v23
	v_and_b32_e32 v24, 0xffffff80, v24
	v_and_b32_e32 v25, 0xffffff80, v25
	v_and_b32_e32 v14, 0xffffff80, v14
	v_and_b32_e32 v15, 0xffffff80, v15
	v_and_b32_e32 v16, 0xffffff80, v16
	v_and_b32_e32 v17, 0xffffff80, v17
	v_and_b32_e32 v6, 0xffffff80, v6
	v_and_b32_e32 v7, 0xffffff80, v7
	v_and_b32_e32 v8, 0xffffff80, v8
	v_or3_b32 v4, v0, v4, s18
	v_and_b32_e32 v9, 0xffffff80, v9
	v_and_b32_e32 v5, 0xffffff80, v5
	s_movk_i32 s18, 0x73
	v_or3_b32 v32, v0, v32, 2
	v_or3_b32 v33, v0, v33, 3
	v_or3_b32 v22, v0, v22, 16
	v_or3_b32 v23, v0, v23, 17
	v_or3_b32 v24, v0, v24, 18
	v_or3_b32 v25, v0, v25, 19
	v_or3_b32 v14, v0, v14, 32
	v_or3_b32 v15, v0, v15, 33
	v_or3_b32 v16, v0, v16, 34
	v_or3_b32 v17, v0, v17, 35
	v_or3_b32 v6, v0, v6, 48
	v_or3_b32 v7, v0, v7, 49
	v_or3_b32 v8, v0, v8, 50
	v_or3_b32 v9, v0, v9, 51
	v_or3_b32 v0, v0, v5, s18
	v_max_f32_e32 v5, v31, v31
	v_max_f32_e32 v31, v30, v5
	v_min_f32_e32 v5, v30, v5
	v_max_f32_e32 v30, v32, v32
	v_max_f32_e32 v32, v33, v33
	v_max_f32_e32 v67, v26, v27
	v_min_f32_e32 v26, v26, v27
	v_max_f32_e32 v27, v28, v28
	v_max_f32_e32 v28, v29, v29
	v_max_f32_e32 v33, v32, v30
	v_min_f32_e32 v30, v32, v30
	v_max_f32_e32 v32, v22, v23
	v_min_f32_e32 v22, v22, v23
	v_max_f32_e32 v23, v24, v24
	v_max_f32_e32 v24, v25, v25
	v_max_f32_e32 v29, v28, v27
	v_min_f32_e32 v27, v28, v27
	v_max_f32_e32 v28, v18, v19
	v_min_f32_e32 v18, v18, v19
	v_max_f32_e32 v19, v20, v20
	v_max_f32_e32 v20, v21, v21
	v_max_f32_e32 v25, v24, v23
	v_min_f32_e32 v23, v24, v23
	v_max_f32_e32 v24, v14, v15
	v_min_f32_e32 v14, v14, v15
	v_max_f32_e32 v15, v16, v16
	v_max_f32_e32 v16, v17, v17
	v_max_f32_e32 v21, v20, v19
	v_min_f32_e32 v19, v20, v19
	v_max_f32_e32 v20, v10, v11
	v_min_f32_e32 v10, v10, v11
	v_max_f32_e32 v11, v12, v12
	v_max_f32_e32 v12, v13, v13
	v_max_f32_e32 v17, v16, v15
	v_min_f32_e32 v15, v16, v15
	v_max_f32_e32 v16, v6, v7
	v_min_f32_e32 v6, v6, v7
	v_max_f32_e32 v7, v8, v8
	v_max_f32_e32 v8, v9, v9
	v_max_f32_e32 v13, v12, v11
	v_min_f32_e32 v11, v12, v11
	v_max_f32_e32 v12, v2, v3
	v_min_f32_e32 v2, v2, v3
	v_max_f32_e32 v3, v4, v4
	v_max_f32_e32 v9, v8, v7
	v_min_f32_e32 v7, v8, v7
	v_max_f32_e32 v4, v0, v3
	v_min_f32_e32 v0, v0, v3
	v_max_f32_e32 v8, v31, v30
	v_min_f32_e32 v30, v31, v30
	v_max_f32_e32 v31, v5, v33
	v_min_f32_e32 v5, v5, v33
	v_max_f32_e32 v33, v23, v32
	v_min_f32_e32 v23, v23, v32
	v_max_f32_e32 v32, v25, v22
	v_min_f32_e32 v22, v25, v22
	v_max_f32_e32 v25, v24, v15
	v_min_f32_e32 v15, v24, v15
	v_max_f32_e32 v24, v14, v17
	v_min_f32_e32 v14, v14, v17
	v_max_f32_e32 v17, v7, v16
	v_min_f32_e32 v7, v7, v16
	v_max_f32_e32 v16, v9, v6
	v_min_f32_e32 v6, v9, v6
	v_max_f32_e32 v3, v67, v27
	v_min_f32_e32 v27, v67, v27
	v_max_f32_e32 v67, v26, v29
	v_min_f32_e32 v26, v26, v29
	v_max_f32_e32 v29, v19, v28
	v_min_f32_e32 v19, v19, v28
	v_max_f32_e32 v28, v21, v18
	v_min_f32_e32 v18, v21, v18
	v_max_f32_e32 v21, v20, v11
	v_min_f32_e32 v11, v20, v11
	v_max_f32_e32 v20, v10, v13
	v_min_f32_e32 v10, v10, v13
	v_max_f32_e32 v13, v0, v12
	v_min_f32_e32 v0, v0, v12
	v_max_f32_e32 v12, v4, v2
	v_min_f32_e32 v2, v4, v2
	v_max_f32_e32 v9, v8, v31
	v_min_f32_e32 v8, v8, v31
	v_max_f32_e32 v31, v30, v5
	v_min_f32_e32 v5, v30, v5
	v_max_f32_e32 v30, v22, v23
	v_min_f32_e32 v22, v22, v23
	v_max_f32_e32 v23, v32, v33
	v_min_f32_e32 v32, v32, v33
	v_max_f32_e32 v33, v25, v24
	v_min_f32_e32 v24, v25, v24
	v_max_f32_e32 v25, v15, v14
	v_min_f32_e32 v14, v15, v14
	v_max_f32_e32 v15, v6, v7
	v_min_f32_e32 v6, v6, v7
	v_max_f32_e32 v7, v16, v17
	v_min_f32_e32 v16, v16, v17
	v_max_f32_e32 v4, v3, v67
	v_min_f32_e32 v3, v3, v67
	v_max_f32_e32 v67, v27, v26
	v_min_f32_e32 v26, v27, v26
	v_max_f32_e32 v27, v18, v19
	v_min_f32_e32 v18, v18, v19
	v_max_f32_e32 v19, v28, v29
	v_min_f32_e32 v28, v28, v29
	v_max_f32_e32 v29, v21, v20
	v_min_f32_e32 v20, v21, v20
	v_max_f32_e32 v21, v11, v10
	v_min_f32_e32 v10, v11, v10
	v_max_f32_e32 v11, v2, v0
	v_min_f32_e32 v0, v2, v0
; DEV void ce(float& a, float& b) { float hi = fmaxf(a, b), lo = fminf(a, b); a = hi; b = lo; }
; DEV void sort16_desc(float (&a)[16]) {
; #pragma unroll
;   for (int k = 2; k <= 16; k <<= 1)
; #pragma unroll
;     for (int j = k >> 1; j > 0; j >>= 1)
; #pragma unroll
;       for (int i = 0; i < 16; i++) {
;         const int p = i ^ j;
;         if (p > i) { if ((i & k) == 0) ce(a[i], a[p]); else ce(a[p], a[i]); }
;       }
; }
	v_max_f32_e32 v2, v12, v13
	v_min_f32_e32 v12, v12, v13
	v_max_f32_e32 v17, v9, v22
	v_min_f32_e32 v9, v9, v22
	v_max_f32_e32 v22, v8, v30
	v_min_f32_e32 v8, v8, v30
	v_max_f32_e32 v30, v31, v32
	v_min_f32_e32 v31, v31, v32
	v_max_f32_e32 v32, v5, v23
	v_min_f32_e32 v5, v5, v23
	v_max_f32_e32 v23, v6, v33
	v_min_f32_e32 v6, v6, v33
	v_max_f32_e32 v33, v15, v24
	v_min_f32_e32 v15, v15, v24
	v_max_f32_e32 v24, v16, v25
	v_min_f32_e32 v16, v16, v25
	v_max_f32_e32 v25, v7, v14
	v_min_f32_e32 v7, v7, v14
	v_max_f32_e32 v13, v4, v18
	v_min_f32_e32 v4, v4, v18
	v_max_f32_e32 v18, v3, v27
	v_min_f32_e32 v3, v3, v27
	v_max_f32_e32 v27, v67, v28
	v_min_f32_e32 v28, v67, v28
	v_max_f32_e32 v67, v26, v19
	v_min_f32_e32 v19, v26, v19
	v_max_f32_e32 v26, v0, v29
	v_min_f32_e32 v0, v0, v29
	v_max_f32_e32 v29, v11, v20
	v_min_f32_e32 v11, v11, v20
	v_max_f32_e32 v20, v12, v21
	v_min_f32_e32 v12, v12, v21
	v_max_f32_e32 v21, v2, v10
	v_min_f32_e32 v2, v2, v10
	v_max_f32_e32 v14, v17, v30
	v_min_f32_e32 v17, v17, v30
	v_max_f32_e32 v30, v22, v32
	v_min_f32_e32 v22, v22, v32
	v_max_f32_e32 v32, v9, v31
	v_min_f32_e32 v9, v9, v31
	v_max_f32_e32 v31, v8, v5
	v_min_f32_e32 v5, v8, v5
	v_max_f32_e32 v8, v16, v6
	v_min_f32_e32 v6, v16, v6
	v_max_f32_e32 v16, v7, v15
	v_min_f32_e32 v7, v7, v15
	v_max_f32_e32 v15, v24, v23
	v_min_f32_e32 v23, v24, v23
	v_max_f32_e32 v24, v25, v33
	v_min_f32_e32 v25, v25, v33
	v_max_f32_e32 v10, v13, v27
	v_min_f32_e32 v13, v13, v27
	v_max_f32_e32 v27, v18, v67
	v_min_f32_e32 v18, v18, v67
	v_max_f32_e32 v67, v4, v28
	v_min_f32_e32 v4, v4, v28
	v_max_f32_e32 v28, v3, v19
	v_min_f32_e32 v3, v3, v19
	v_max_f32_e32 v19, v12, v0
	v_min_f32_e32 v0, v12, v0
	v_max_f32_e32 v12, v2, v11
	v_min_f32_e32 v2, v2, v11
	v_max_f32_e32 v11, v20, v26
	v_min_f32_e32 v20, v20, v26
	v_max_f32_e32 v26, v21, v29
	v_min_f32_e32 v21, v21, v29
	v_max_f32_e32 v33, v14, v30
	v_min_f32_e32 v14, v14, v30
	v_max_f32_e32 v30, v17, v22
	v_min_f32_e32 v17, v17, v22
	v_max_f32_e32 v22, v32, v31
	v_min_f32_e32 v31, v32, v31
	v_max_f32_e32 v32, v9, v5
	v_min_f32_e32 v5, v9, v5
	v_max_f32_e32 v9, v7, v6
	v_min_f32_e32 v6, v7, v6
	v_max_f32_e32 v7, v16, v8
	v_min_f32_e32 v8, v16, v8
	v_max_f32_e32 v16, v25, v23
	v_min_f32_e32 v23, v25, v23
	v_max_f32_e32 v25, v24, v15
	v_min_f32_e32 v15, v24, v15
	v_max_f32_e32 v29, v10, v27
	v_min_f32_e32 v10, v10, v27
	v_max_f32_e32 v27, v13, v18
	v_min_f32_e32 v13, v13, v18
	v_max_f32_e32 v18, v67, v28
	v_min_f32_e32 v28, v67, v28
	v_max_f32_e32 v67, v4, v3
	v_min_f32_e32 v3, v4, v3
	v_max_f32_e32 v4, v2, v0
	v_min_f32_e32 v0, v2, v0
	v_max_f32_e32 v2, v12, v19
	v_min_f32_e32 v12, v12, v19
	v_max_f32_e32 v19, v21, v20
	v_min_f32_e32 v20, v21, v20
	v_max_f32_e32 v21, v26, v11
	v_min_f32_e32 v11, v26, v11
	v_max_f32_e32 v24, v33, v6
	v_min_f32_e32 v6, v33, v6
	v_max_f32_e32 v33, v14, v9
	v_min_f32_e32 v9, v14, v9
	v_max_f32_e32 v14, v30, v8
	v_min_f32_e32 v8, v30, v8
	v_max_f32_e32 v30, v17, v7
	v_min_f32_e32 v7, v17, v7
	v_max_f32_e32 v17, v22, v23
	v_min_f32_e32 v22, v22, v23
	v_max_f32_e32 v23, v31, v16
	v_min_f32_e32 v16, v31, v16
	v_max_f32_e32 v31, v32, v15
	v_min_f32_e32 v15, v32, v15
	v_max_f32_e32 v32, v5, v25
	v_min_f32_e32 v5, v5, v25
	v_max_f32_e32 v26, v29, v0
	v_min_f32_e32 v0, v29, v0
	v_max_f32_e32 v29, v10, v4
	v_min_f32_e32 v4, v10, v4
	v_max_f32_e32 v10, v27, v12
	v_min_f32_e32 v12, v27, v12
	v_max_f32_e32 v27, v13, v2
	v_min_f32_e32 v2, v13, v2
	v_max_f32_e32 v13, v18, v20
	v_min_f32_e32 v18, v18, v20
	v_max_f32_e32 v20, v28, v19
	v_min_f32_e32 v19, v28, v19
	v_max_f32_e32 v28, v67, v11
	v_min_f32_e32 v11, v67, v11
	v_max_f32_e32 v67, v3, v21
	v_min_f32_e32 v3, v3, v21
	v_max_f32_e32 v25, v24, v17
	v_min_f32_e32 v17, v24, v17
	v_max_f32_e32 v24, v33, v23
	v_min_f32_e32 v23, v33, v23
	v_max_f32_e32 v33, v14, v31
	v_min_f32_e32 v14, v14, v31
	v_max_f32_e32 v31, v30, v32
	v_min_f32_e32 v30, v30, v32
	v_max_f32_e32 v32, v6, v22
	v_min_f32_e32 v6, v6, v22
	v_max_f32_e32 v22, v9, v16
	v_min_f32_e32 v9, v9, v16
	v_max_f32_e32 v16, v8, v15
	v_min_f32_e32 v8, v8, v15
	v_max_f32_e32 v15, v7, v5
	v_min_f32_e32 v5, v7, v5
	v_max_f32_e32 v21, v26, v13
	v_min_f32_e32 v13, v26, v13
	v_max_f32_e32 v26, v29, v20
	v_min_f32_e32 v20, v29, v20
	v_max_f32_e32 v29, v10, v28
	v_min_f32_e32 v10, v10, v28
	v_max_f32_e32 v28, v27, v67
	v_min_f32_e32 v27, v27, v67
	v_max_f32_e32 v67, v0, v18
	v_min_f32_e32 v0, v0, v18
	v_max_f32_e32 v18, v4, v19
	v_min_f32_e32 v4, v4, v19
	v_max_f32_e32 v19, v12, v11
	v_min_f32_e32 v11, v12, v11
	v_max_f32_e32 v12, v2, v3
	v_min_f32_e32 v2, v2, v3
	v_max_f32_e32 v7, v25, v33
	v_min_f32_e32 v25, v25, v33
	v_max_f32_e32 v33, v24, v31
	v_min_f32_e32 v24, v24, v31
	v_max_f32_e32 v31, v17, v14
	v_min_f32_e32 v14, v17, v14
	v_max_f32_e32 v17, v23, v30
	v_min_f32_e32 v23, v23, v30
	v_max_f32_e32 v30, v32, v16
	v_min_f32_e32 v16, v32, v16
	v_max_f32_e32 v32, v22, v15
	v_min_f32_e32 v15, v22, v15
	v_max_f32_e32 v22, v6, v8
	v_min_f32_e32 v6, v6, v8
	v_max_f32_e32 v8, v9, v5
	v_min_f32_e32 v5, v9, v5
	v_max_f32_e32 v3, v21, v29
	v_min_f32_e32 v21, v21, v29
	v_max_f32_e32 v29, v26, v28
	v_min_f32_e32 v26, v26, v28
	v_max_f32_e32 v28, v13, v10
	v_min_f32_e32 v10, v13, v10
	v_max_f32_e32 v13, v20, v27
	v_min_f32_e32 v20, v20, v27
	v_max_f32_e32 v27, v67, v19
	v_min_f32_e32 v19, v67, v19
	v_max_f32_e32 v67, v18, v12
	v_min_f32_e32 v12, v18, v12
	v_max_f32_e32 v18, v0, v11
	v_min_f32_e32 v0, v0, v11
	v_max_f32_e32 v11, v4, v2
	v_min_f32_e32 v2, v4, v2
	v_min_f32_e32 v9, v7, v33
	v_min_f32_e32 v39, v25, v24
	v_min_f32_e32 v43, v31, v17
	v_min_f32_e32 v47, v14, v23
	v_min_f32_e32 v51, v30, v32
	v_min_f32_e32 v55, v16, v15
; DEV void ce(float& a, float& b) { float hi = fmaxf(a, b), lo = fminf(a, b); a = hi; b = lo; }
; DEV void bitonic16(float (&l)[16]) {
; #pragma unroll
;   for (int s = 8; s > 0; s >>= 1)
; #pragma unroll
;     for (int i = 0; i < 16; i++)
;       if (!(i & s)) ce(l[i], l[i + s]);
; }
; DEV void sort16_desc(float (&a)[16]) {
; #pragma unroll
;   for (int k = 2; k <= 16; k <<= 1)
; #pragma unroll
;     for (int j = k >> 1; j > 0; j >>= 1)
; #pragma unroll
;       for (int i = 0; i < 16; i++) {
;         const int p = i ^ j;
;         if (p > i) { if ((i & k) == 0) ce(a[i], a[p]); else ce(a[p], a[i]); }
;       }
; }
; DEV void merge_xor(float (&l)[16], int mask) {
;   float t[16];
; #pragma unroll
;   for (int i = 0; i < 16; i++) t[i] = __shfl_xor(l[15 - i], mask);
; #pragma unroll
;   for (int i = 0; i < 16; i++) l[i] = fmaxf(l[i], t[i]);
;   bitonic16(l);
; }
; DEV void peer_top16(const bf16_t* __restrict__ pq, const bf16_t* sk  , float (&l)[16]) {
;     ...
;   sort16_desc(l);
;   sort16_desc(hi);
; #pragma unroll
;   for (int i = 0; i < 16; i++) l[i] = fmaxf(l[i], hi[15 - i]);
;   bitonic16(l);
;   merge_xor(l, 16);
;   merge_xor(l, 32);
	v_min_f32_e32 v59, v22, v8
	v_min_f32_e32 v63, v6, v5
	v_min_f32_e32 v4, v3, v29
	v_min_f32_e32 v71, v21, v26
	v_min_f32_e32 v75, v28, v13
	v_min_f32_e32 v79, v10, v20
	v_min_f32_e32 v83, v27, v67
	v_min_f32_e32 v87, v19, v12
	v_min_f32_e32 v91, v18, v11
	v_min_f32_e32 v95, v0, v2
	v_max3_f32 v7, v7, v33, v95
	v_max3_f32 v0, v9, v0, v2
	v_max3_f32 v2, v25, v24, v91
	v_max3_f32 v9, v39, v18, v11
	v_max3_f32 v11, v31, v17, v87
	v_max3_f32 v12, v43, v19, v12
	v_max3_f32 v14, v14, v23, v83
	v_max3_f32 v17, v47, v27, v67
	v_max3_f32 v18, v30, v32, v79
	v_max3_f32 v10, v51, v10, v20
	v_max3_f32 v15, v16, v15, v75
	v_max3_f32 v13, v55, v28, v13
	v_max3_f32 v8, v22, v8, v71
	v_max3_f32 v16, v59, v21, v26
	v_max3_f32 v4, v6, v5, v4
	v_max3_f32 v3, v63, v3, v29
	v_max_f32_e32 v5, v7, v18
	v_min_f32_e32 v6, v7, v18
	v_max_f32_e32 v7, v0, v10
	v_min_f32_e32 v0, v0, v10
	v_max_f32_e32 v10, v2, v15
	v_min_f32_e32 v2, v2, v15
	v_max_f32_e32 v15, v9, v13
	v_min_f32_e32 v9, v9, v13
	v_max_f32_e32 v13, v11, v8
	v_min_f32_e32 v8, v11, v8
	v_max_f32_e32 v11, v12, v16
	v_min_f32_e32 v12, v12, v16
	v_max_f32_e32 v16, v14, v4
	v_min_f32_e32 v4, v14, v4
	v_max_f32_e32 v14, v17, v3
	v_min_f32_e32 v3, v17, v3
	v_max_f32_e32 v17, v5, v13
	v_min_f32_e32 v5, v5, v13
	v_max_f32_e32 v13, v7, v11
	v_min_f32_e32 v7, v7, v11
	v_max_f32_e32 v11, v10, v16
	v_min_f32_e32 v10, v10, v16
	v_max_f32_e32 v16, v15, v14
	v_min_f32_e32 v14, v15, v14
	v_max_f32_e32 v15, v6, v8
	v_min_f32_e32 v6, v6, v8
	v_max_f32_e32 v8, v0, v12
	v_min_f32_e32 v0, v0, v12
	v_max_f32_e32 v12, v2, v4
	v_min_f32_e32 v2, v2, v4
	v_max_f32_e32 v4, v9, v3
	v_min_f32_e32 v3, v9, v3
	v_max_f32_e32 v9, v17, v11
	v_min_f32_e32 v11, v17, v11
	v_max_f32_e32 v17, v13, v16
	v_min_f32_e32 v13, v13, v16
	v_max_f32_e32 v16, v5, v10
	v_min_f32_e32 v5, v5, v10
	v_max_f32_e32 v10, v7, v14
	v_min_f32_e32 v7, v7, v14
	v_max_f32_e32 v14, v15, v12
	v_min_f32_e32 v12, v15, v12
	v_max_f32_e32 v15, v8, v4
	v_min_f32_e32 v4, v8, v4
	v_max_f32_e32 v8, v6, v2
	v_min_f32_e32 v2, v6, v2
	v_max_f32_e32 v6, v0, v3
	v_min_f32_e32 v0, v0, v3
	v_max_f32_e32 v3, v9, v17
	v_min_f32_e32 v9, v9, v17
	v_max_f32_e32 v17, v11, v13
	v_min_f32_e32 v11, v11, v13
	v_max_f32_e32 v13, v16, v10
	v_min_f32_e32 v10, v16, v10
	v_max_f32_e32 v16, v5, v7
	v_min_f32_e32 v5, v5, v7
	v_max_f32_e32 v7, v14, v15
	v_min_f32_e32 v14, v14, v15
	v_max_f32_e32 v15, v12, v4
	v_min_f32_e32 v4, v12, v4
	v_max_f32_e32 v12, v8, v6
	v_min_f32_e32 v6, v8, v6
	v_max_f32_e32 v8, v2, v0
	v_min_f32_e32 v0, v2, v0
	v_mbcnt_hi_u32_b32 v2, -1, v215
	v_and_b32_e32 v19, 64, v2
	v_xor_b32_e32 v18, 16, v2
	v_add_u32_e32 v19, 64, v19
	v_cmp_lt_i32_e32 vcc, v18, v19
	s_add_u32 s8, s12, s8
	s_addc_u32 s9, s13, s9
	v_cndmask_b32_e32 v18, v2, v18, vcc
	v_lshlrev_b32_e32 v95, 2, v18
	ds_bpermute_b32 v18, v95, v0
	ds_bpermute_b32 v20, v95, v8
	ds_bpermute_b32 v21, v95, v6
	ds_bpermute_b32 v22, v95, v12
	ds_bpermute_b32 v23, v95, v4
	ds_bpermute_b32 v24, v95, v15
	s_waitcnt lgkmcnt(5)
	ds_bpermute_b32 v25, v95, v14
	ds_bpermute_b32 v39, v95, v3
	v_max_f32_e32 v3, v3, v18
	s_waitcnt lgkmcnt(6)
	ds_bpermute_b32 v26, v95, v7
	ds_bpermute_b32 v33, v95, v9
	v_max_f32_e32 v9, v9, v20
	s_waitcnt lgkmcnt(7)
	ds_bpermute_b32 v27, v95, v5
	ds_bpermute_b32 v32, v95, v17
	v_max_f32_e32 v17, v17, v21
	s_waitcnt lgkmcnt(8)
	ds_bpermute_b32 v28, v95, v16
	ds_bpermute_b32 v31, v95, v11
	v_max_f32_e32 v11, v11, v22
	s_waitcnt lgkmcnt(9)
	ds_bpermute_b32 v29, v95, v10
	ds_bpermute_b32 v30, v95, v13
	v_max_f32_e32 v13, v13, v23
	s_waitcnt lgkmcnt(10)
	v_max_f32_e32 v10, v10, v24
	s_waitcnt lgkmcnt(9)
	v_max_f32_e32 v16, v16, v25
	s_waitcnt lgkmcnt(7)
	v_max_f32_e32 v5, v5, v26
	s_waitcnt lgkmcnt(5)
	v_max_f32_e32 v7, v7, v27
	s_waitcnt lgkmcnt(3)
	v_max_f32_e32 v14, v14, v28
	s_waitcnt lgkmcnt(1)
	v_max_f32_e32 v15, v15, v29
	s_waitcnt lgkmcnt(0)
	v_max_f32_e32 v4, v4, v30
	v_max_f32_e32 v12, v12, v31
	v_max_f32_e32 v6, v6, v32
	v_max_f32_e32 v8, v8, v33
	v_max_f32_e32 v0, v0, v39
	v_max_f32_e32 v18, v3, v7
	v_min_f32_e32 v3, v3, v7
	v_max_f32_e32 v7, v9, v14
	v_min_f32_e32 v9, v9, v14
	v_max_f32_e32 v14, v17, v15
	v_min_f32_e32 v15, v17, v15
	v_max_f32_e32 v17, v11, v4
	v_min_f32_e32 v4, v11, v4
	v_max_f32_e32 v11, v13, v12
	v_min_f32_e32 v12, v13, v12
	v_max_f32_e32 v13, v10, v6
	v_min_f32_e32 v6, v10, v6
	v_max_f32_e32 v10, v16, v8
	v_min_f32_e32 v8, v16, v8
	v_max_f32_e32 v16, v5, v0
	v_min_f32_e32 v0, v5, v0
	v_max_f32_e32 v5, v18, v11
	v_min_f32_e32 v11, v18, v11
	v_max_f32_e32 v18, v7, v13
	v_min_f32_e32 v7, v7, v13
	v_max_f32_e32 v13, v14, v10
	v_min_f32_e32 v10, v14, v10
	v_max_f32_e32 v14, v17, v16
	v_min_f32_e32 v16, v17, v16
	v_max_f32_e32 v17, v3, v12
	v_min_f32_e32 v3, v3, v12
	v_max_f32_e32 v12, v9, v6
	v_min_f32_e32 v6, v9, v6
	v_max_f32_e32 v9, v15, v8
	v_min_f32_e32 v8, v15, v8
	v_max_f32_e32 v15, v4, v0
	v_min_f32_e32 v0, v4, v0
	v_max_f32_e32 v4, v5, v13
	v_min_f32_e32 v5, v5, v13
	v_max_f32_e32 v13, v18, v14
	v_min_f32_e32 v14, v18, v14
	v_max_f32_e32 v18, v11, v10
	v_min_f32_e32 v10, v11, v10
	v_max_f32_e32 v11, v7, v16
	v_min_f32_e32 v7, v7, v16
	v_max_f32_e32 v16, v17, v9
	v_min_f32_e32 v9, v17, v9
	v_max_f32_e32 v17, v12, v15
	v_min_f32_e32 v12, v12, v15
	v_max_f32_e32 v15, v3, v8
	v_min_f32_e32 v3, v3, v8
	v_max_f32_e32 v8, v6, v0
	v_min_f32_e32 v0, v6, v0
	v_max_f32_e32 v43, v3, v0
	v_min_f32_e32 v39, v3, v0
	v_xor_b32_e32 v0, 32, v2
	v_cmp_lt_i32_e32 vcc, v0, v19
	v_max_f32_e32 v109, v4, v13
	v_min_f32_e32 v107, v4, v13
	v_cndmask_b32_e32 v0, v2, v0, vcc
	v_max_f32_e32 v105, v5, v14
	v_min_f32_e32 v103, v5, v14
	v_max_f32_e32 v87, v18, v11
	v_min_f32_e32 v79, v18, v11
; DEV int tidx() { int t = threadIdx.x; asm volatile("" : "+v"(t)); return t; }
; DEV f32x4 mfma16(bf16x8 a, bf16x8 b, f32x4 c) { return __builtin_amdgcn_mfma_f32_16x16x32_bf16(a, b, c, 0, 0, 0); }
; DEV void merge_xor(float (&l)[16], int mask) {
;   float t[16];
; #pragma unroll
;   for (int i = 0; i < 16; i++) t[i] = __shfl_xor(l[15 - i], mask);
; #pragma unroll
;   for (int i = 0; i < 16; i++) l[i] = fmaxf(l[i], t[i]);
;   bitonic16(l);
; }
; DEV void peer_top16(const bf16_t* __restrict__ pq, const bf16_t* sk  , float (&l)[16]) {
;   const int lane = tidx() & 63, l15 = lane & 15, quad = lane >> 4;
;   f32x4 acc[8];
; #pragma unroll
;   for (int nt = 0; nt < 8; nt++) acc[nt] = (f32x4){0.f, 0.f, 0.f, 0.f};
; #pragma unroll 1
;   for (int ks = 0; ks < 4; ks++) {
;     const bf16x8 bqk = *(const bf16x8*)(pq + ks * 32 + quad * 8);
; #pragma unroll
;     for (int nt = 0; nt < 8; nt++) {
;       bf16x8 ak = *(const bf16x8*)(sk + (nt * 16 + l15) * 144 + ks * 32 + quad * 8);
;       acc[nt] = mfma16(ak, bqk, acc[nt]);
;     }
;   }
	v_max_f32_e32 v75, v10, v7
	v_min_f32_e32 v71, v10, v7
	v_max_f32_e32 v67, v16, v17
	v_min_f32_e32 v63, v16, v17
	v_max_f32_e32 v59, v9, v12
	v_min_f32_e32 v55, v9, v12
	v_max_f32_e32 v51, v15, v8
	v_min_f32_e32 v47, v15, v8
	v_lshlrev_b32_e32 v99, 2, v0
	v_mov_b32_e32 v0, v195
	ds_bpermute_b32 v121, v99, v39
	ds_bpermute_b32 v120, v99, v43
	ds_bpermute_b32 v119, v99, v47
	ds_bpermute_b32 v118, v99, v51
	ds_bpermute_b32 v116, v99, v55
	ds_bpermute_b32 v115, v99, v59
	ds_bpermute_b32 v114, v99, v63
	ds_bpermute_b32 v113, v99, v67
	ds_bpermute_b32 v112, v99, v71
	ds_bpermute_b32 v111, v99, v75
	ds_bpermute_b32 v110, v99, v79
	ds_bpermute_b32 v108, v99, v87
	ds_bpermute_b32 v106, v99, v103
	ds_bpermute_b32 v104, v99, v105
	ds_bpermute_b32 v91, v99, v107
	ds_bpermute_b32 v83, v99, v109
	s_mov_b32 s18, 0
	v_bfe_u32 v102, v0, 4, 2
	v_and_b32_e32 v2, 15, v0
	v_lshlrev_b32_e32 v0, 4, v102
	v_mad_u32_u24 v122, v2, s20, v0
	v_lshl_add_u64 v[2:3], v[100:101], 0, v[0:1]
	v_lshl_add_u64 v[100:101], s[8:9], 0, v[2:3]
	v_mov_b32_e32 v2, 0
	v_mov_b32_e32 v3, v2
	v_mov_b32_e32 v4, v2
	v_mov_b32_e32 v5, v2
	v_mov_b32_e32 v10, v2
	v_mov_b32_e32 v11, v2
	v_mov_b32_e32 v12, v2
	v_mov_b32_e32 v13, v2
	v_mov_b32_e32 v18, v2
	v_mov_b32_e32 v19, v2
	v_mov_b32_e32 v20, v2
	v_mov_b32_e32 v21, v2
	v_mov_b32_e32 v26, v2
	v_mov_b32_e32 v27, v2
	v_mov_b32_e32 v28, v2
	v_mov_b32_e32 v29, v2
	v_mov_b32_e32 v6, v2
	v_mov_b32_e32 v7, v2
	v_mov_b32_e32 v8, v2
	v_mov_b32_e32 v9, v2
	v_mov_b32_e32 v14, v2
	v_mov_b32_e32 v15, v2
	v_mov_b32_e32 v16, v2
	v_mov_b32_e32 v17, v2
	v_mov_b32_e32 v22, v2
	v_mov_b32_e32 v23, v2
	v_mov_b32_e32 v24, v2
	v_mov_b32_e32 v25, v2
	v_mov_b32_e32 v30, v2
	v_mov_b32_e32 v31, v2
	v_mov_b32_e32 v32, v2
	v_mov_b32_e32 v33, v2
.LBB0_635:
	v_add_u32_e32 v139, 0x10e00, v122
	ds_read_b128 v[164:167], v122 offset:36864
	ds_read_b128 v[168:171], v122 offset:41472
	ds_read_b128 v[172:175], v122 offset:46080
	ds_read_b128 v[176:179], v122 offset:50688
	ds_read_b128 v[180:183], v122 offset:55296
	ds_read_b128 v[184:187], v122 offset:59904
	ds_read_b128 v[188:191], v122 offset:64512
	ds_read_b128 v[128:131], v139
	s_waitcnt vmcnt(3) lgkmcnt(7)
	v_mfma_f32_16x16x32_bf16 v[30:33], v[164:167], v[148:151], v[30:33]
	ds_read_b128 v[164:167], v122 offset:36928
	s_waitcnt lgkmcnt(7)
	v_mfma_f32_16x16x32_bf16 v[22:25], v[168:171], v[148:151], v[22:25]
	ds_read_b128 v[168:171], v122 offset:41536
	s_waitcnt lgkmcnt(7)
	v_mfma_f32_16x16x32_bf16 v[14:17], v[172:175], v[148:151], v[14:17]
	ds_read_b128 v[172:175], v122 offset:46144
	s_waitcnt lgkmcnt(7)
	v_mfma_f32_16x16x32_bf16 v[6:9], v[176:179], v[148:151], v[6:9]
	ds_read_b128 v[176:179], v122 offset:50752
	s_waitcnt lgkmcnt(7)
	v_mfma_f32_16x16x32_bf16 v[26:29], v[180:183], v[148:151], v[26:29]
	ds_read_b128 v[180:183], v122 offset:55360
	s_waitcnt lgkmcnt(7)
	v_mfma_f32_16x16x32_bf16 v[18:21], v[184:187], v[148:151], v[18:21]
	ds_read_b128 v[184:187], v122 offset:59968
	s_waitcnt lgkmcnt(7)
	v_mfma_f32_16x16x32_bf16 v[10:13], v[188:191], v[148:151], v[10:13]
	ds_read_b128 v[188:191], v122 offset:64576
	s_waitcnt lgkmcnt(7)
	v_mfma_f32_16x16x32_bf16 v[2:5], v[128:131], v[148:151], v[2:5]
	ds_read_b128 v[128:131], v139 offset:64
	s_waitcnt vmcnt(2) lgkmcnt(7)
	v_mfma_f32_16x16x32_bf16 v[30:33], v[164:167], v[152:155], v[30:33]
	ds_read_b128 v[164:167], v122 offset:36992
	s_waitcnt lgkmcnt(7)
	v_mfma_f32_16x16x32_bf16 v[22:25], v[168:171], v[152:155], v[22:25]
	ds_read_b128 v[168:171], v122 offset:41600
	s_waitcnt lgkmcnt(7)
	v_mfma_f32_16x16x32_bf16 v[14:17], v[172:175], v[152:155], v[14:17]
	ds_read_b128 v[172:175], v122 offset:46208
	s_waitcnt lgkmcnt(7)
	v_mfma_f32_16x16x32_bf16 v[6:9], v[176:179], v[152:155], v[6:9]
	ds_read_b128 v[176:179], v122 offset:50816
	s_waitcnt lgkmcnt(7)
	v_mfma_f32_16x16x32_bf16 v[26:29], v[180:183], v[152:155], v[26:29]
	ds_read_b128 v[180:183], v122 offset:55424
	s_waitcnt lgkmcnt(7)
	v_mfma_f32_16x16x32_bf16 v[18:21], v[184:187], v[152:155], v[18:21]
	ds_read_b128 v[184:187], v122 offset:60032
	s_waitcnt lgkmcnt(7)
	v_mfma_f32_16x16x32_bf16 v[10:13], v[188:191], v[152:155], v[10:13]
	ds_read_b128 v[188:191], v122 offset:64640
	s_waitcnt lgkmcnt(7)
	v_mfma_f32_16x16x32_bf16 v[2:5], v[128:131], v[152:155], v[2:5]
	ds_read_b128 v[128:131], v139 offset:128
	s_waitcnt vmcnt(1) lgkmcnt(7)
	v_mfma_f32_16x16x32_bf16 v[30:33], v[164:167], v[156:159], v[30:33]
	ds_read_b128 v[164:167], v122 offset:37056
	s_waitcnt lgkmcnt(7)
	v_mfma_f32_16x16x32_bf16 v[22:25], v[168:171], v[156:159], v[22:25]
	ds_read_b128 v[168:171], v122 offset:41664
	s_waitcnt lgkmcnt(7)
	v_mfma_f32_16x16x32_bf16 v[14:17], v[172:175], v[156:159], v[14:17]
	ds_read_b128 v[172:175], v122 offset:46272
	s_waitcnt lgkmcnt(7)
	v_mfma_f32_16x16x32_bf16 v[6:9], v[176:179], v[156:159], v[6:9]
	ds_read_b128 v[176:179], v122 offset:50880
	s_waitcnt lgkmcnt(7)
	v_mfma_f32_16x16x32_bf16 v[26:29], v[180:183], v[156:159], v[26:29]
	ds_read_b128 v[180:183], v122 offset:55488
	s_waitcnt lgkmcnt(7)
	v_mfma_f32_16x16x32_bf16 v[18:21], v[184:187], v[156:159], v[18:21]
	ds_read_b128 v[184:187], v122 offset:60096
	s_waitcnt lgkmcnt(7)
	v_mfma_f32_16x16x32_bf16 v[10:13], v[188:191], v[156:159], v[10:13]
	ds_read_b128 v[188:191], v122 offset:64704
	s_waitcnt lgkmcnt(7)
	v_mfma_f32_16x16x32_bf16 v[2:5], v[128:131], v[156:159], v[2:5]
	ds_read_b128 v[128:131], v139 offset:192
	s_waitcnt vmcnt(0) lgkmcnt(7)
	v_mfma_f32_16x16x32_bf16 v[30:33], v[164:167], v[160:163], v[30:33]
	s_waitcnt lgkmcnt(6)
	v_mfma_f32_16x16x32_bf16 v[22:25], v[168:171], v[160:163], v[22:25]
	s_waitcnt lgkmcnt(5)
	v_mfma_f32_16x16x32_bf16 v[14:17], v[172:175], v[160:163], v[14:17]
	s_waitcnt lgkmcnt(4)
; DEV int tidx() { int t = threadIdx.x; asm volatile("" : "+v"(t)); return t; }
; DEV f32x4 mfma16(bf16x8 a, bf16x8 b, f32x4 c) { return __builtin_amdgcn_mfma_f32_16x16x32_bf16(a, b, c, 0, 0, 0); }
; DEV void peer_top16(const bf16_t* __restrict__ pq, const bf16_t* sk  , float (&l)[16]) {
;   const int lane = tidx() & 63, l15 = lane & 15, quad = lane >> 4;
;   f32x4 acc[8];
; #pragma unroll
;   for (int nt = 0; nt < 8; nt++) acc[nt] = (f32x4){0.f, 0.f, 0.f, 0.f};
; #pragma unroll 1
;   for (int ks = 0; ks < 4; ks++) {
;     const bf16x8 bqk = *(const bf16x8*)(pq + ks * 32 + quad * 8);
; #pragma unroll
;     for (int nt = 0; nt < 8; nt++) {
;       bf16x8 ak = *(const bf16x8*)(sk + (nt * 16 + l15) * 144 + ks * 32 + quad * 8);
;       acc[nt] = mfma16(ak, bqk, acc[nt]);
;     }
;   }
;   float hi[16];
; #pragma unroll
;   for (int nt = 0; nt < 4; nt++)
; #pragma unroll
;     for (int r = 0; r < 4; r++) {
;       l[nt * 4 + r] = __uint_as_float((__float_as_uint(acc[nt][r]) & ~127u) | (unsigned)(nt * 16 + quad * 4 + r));
;       hi[nt * 4 + r] = __uint_as_float((__float_as_uint(acc[nt + 4][r]) & ~127u) | (unsigned)((nt + 4) * 16 + quad * 4 + r));
;     }
;     ...
;   merge_xor(l, 16);
;   merge_xor(l, 32);
	v_mfma_f32_16x16x32_bf16 v[6:9], v[176:179], v[160:163], v[6:9]
	s_waitcnt lgkmcnt(3)
	v_mfma_f32_16x16x32_bf16 v[26:29], v[180:183], v[160:163], v[26:29]
	s_waitcnt lgkmcnt(2)
	v_mfma_f32_16x16x32_bf16 v[18:21], v[184:187], v[160:163], v[18:21]
	s_waitcnt lgkmcnt(1)
	v_mfma_f32_16x16x32_bf16 v[10:13], v[188:191], v[160:163], v[10:13]
	s_waitcnt lgkmcnt(0)
	v_mfma_f32_16x16x32_bf16 v[2:5], v[128:131], v[160:163], v[2:5]
	s_movk_i32 s18, 0x100
	v_max_f32_e32 v0, v109, v121
	v_max_f32_e32 v100, v107, v120
	v_max_f32_e32 v101, v105, v119
	v_max_f32_e32 v103, v103, v118
	v_max_f32_e32 v87, v87, v116
	v_max_f32_e32 v79, v79, v115
	v_max_f32_e32 v75, v75, v114
	v_max_f32_e32 v71, v71, v113
	v_max_f32_e32 v67, v67, v112
	v_max_f32_e32 v63, v63, v111
	v_max_f32_e32 v59, v59, v110
	v_max_f32_e32 v55, v55, v108
	v_max_f32_e32 v51, v51, v106
	v_max_f32_e32 v47, v47, v104
	v_max_f32_e32 v43, v43, v91
	v_max_f32_e32 v39, v39, v83
	v_max_f32_e32 v83, v0, v67
	v_min_f32_e32 v0, v0, v67
	v_max_f32_e32 v67, v100, v63
	v_min_f32_e32 v63, v100, v63
	v_max_f32_e32 v91, v101, v59
	v_min_f32_e32 v59, v101, v59
	v_max_f32_e32 v100, v103, v55
	v_min_f32_e32 v55, v103, v55
	v_max_f32_e32 v101, v87, v51
	v_min_f32_e32 v51, v87, v51
	v_max_f32_e32 v87, v79, v47
	v_min_f32_e32 v47, v79, v47
	v_max_f32_e32 v79, v75, v43
	v_min_f32_e32 v43, v75, v43
	v_max_f32_e32 v75, v71, v39
	v_min_f32_e32 v39, v71, v39
	v_max_f32_e32 v71, v83, v101
	v_min_f32_e32 v101, v83, v101
	v_max_f32_e32 v103, v67, v87
	v_min_f32_e32 v67, v67, v87
	v_max_f32_e32 v87, v91, v79
	v_min_f32_e32 v79, v91, v79
	v_max_f32_e32 v91, v100, v75
	v_min_f32_e32 v75, v100, v75
	v_max_f32_e32 v100, v0, v51
	v_min_f32_e32 v0, v0, v51
	v_max_f32_e32 v51, v63, v47
	v_max_f32_e32 v105, v59, v43
	v_min_f32_e32 v43, v59, v43
	v_max_f32_e32 v59, v55, v39
	v_min_f32_e32 v107, v101, v79
	v_min_f32_e32 v108, v67, v75
	v_min_f32_e32 v110, v51, v59
	v_max_f32_e32 v79, v101, v79
	v_max_f32_e32 v67, v67, v75
	v_max_f32_e32 v101, v100, v105
	v_max_f32_e32 v51, v51, v59
	v_min_f32_e32 v75, v79, v67
	v_min_f32_e32 v59, v101, v51
	v_max_f32_e32 v79, v79, v67
	v_max_f32_e32 v67, v101, v51
	v_lshlrev_b32_e32 v101, 2, v102
	s_movk_i32 s8, 0xff80
	v_and_or_b32 v30, v30, s8, v101
	v_and_b32_e32 v27, 0xffffff80, v27
	s_movk_i32 s8, 0x41
	v_or3_b32 v27, v101, v27, s8
	v_and_b32_e32 v28, 0xffffff80, v28
	s_movk_i32 s8, 0x42
	v_or3_b32 v28, v101, v28, s8
	v_and_b32_e32 v29, 0xffffff80, v29
	s_movk_i32 s8, 0x43
	v_or3_b32 v29, v101, v29, s8
	v_and_b32_e32 v18, 0xffffff80, v18
	s_movk_i32 s8, 0x50
	v_or3_b32 v18, v101, v18, s8
	v_and_b32_e32 v19, 0xffffff80, v19
	s_movk_i32 s8, 0x51
	v_or3_b32 v19, v101, v19, s8
	v_and_b32_e32 v20, 0xffffff80, v20
	s_movk_i32 s8, 0x52
	v_or3_b32 v20, v101, v20, s8
	v_and_b32_e32 v21, 0xffffff80, v21
	s_movk_i32 s8, 0x53
	v_or3_b32 v21, v101, v21, s8
	v_and_b32_e32 v10, 0xffffff80, v10
	s_movk_i32 s8, 0x60
	v_or3_b32 v10, v101, v10, s8
	v_and_b32_e32 v11, 0xffffff80, v11
	s_movk_i32 s8, 0x61
	v_or3_b32 v11, v101, v11, s8
	v_and_b32_e32 v12, 0xffffff80, v12
	s_movk_i32 s8, 0x62
	v_or3_b32 v12, v101, v12, s8
	v_and_b32_e32 v13, 0xffffff80, v13
	s_movk_i32 s8, 0x63
	v_or3_b32 v13, v101, v13, s8
	v_and_b32_e32 v2, 0xffffff80, v2
	s_movk_i32 s8, 0x70
	v_and_b32_e32 v26, 0xffffff80, v26
	v_and_b32_e32 v31, 0xffffff80, v31
	v_or3_b32 v2, v101, v2, s8
	v_and_b32_e32 v3, 0xffffff80, v3
	s_movk_i32 s8, 0x71
	v_or3_b32 v26, v101, v26, 64
	v_or3_b32 v31, v101, v31, 1
	v_and_b32_e32 v32, 0xffffff80, v32
	v_and_b32_e32 v33, 0xffffff80, v33
	v_and_b32_e32 v22, 0xffffff80, v22
	v_and_b32_e32 v23, 0xffffff80, v23
	v_or3_b32 v3, v101, v3, s8
	v_and_b32_e32 v4, 0xffffff80, v4
	s_movk_i32 s8, 0x72
	v_min_f32_e32 v39, v55, v39
	v_min_f32_e32 v55, v71, v87
	v_min_f32_e32 v106, v103, v91
	v_min_f32_e32 v109, v100, v105
	v_max_f32_e32 v71, v71, v87
	v_max_f32_e32 v87, v103, v91
	v_or3_b32 v32, v101, v32, 2
	v_or3_b32 v33, v101, v33, 3
	v_or3_b32 v22, v101, v22, 16
	v_or3_b32 v23, v101, v23, 17
	v_and_b32_e32 v24, 0xffffff80, v24
	v_and_b32_e32 v25, 0xffffff80, v25
	v_and_b32_e32 v14, 0xffffff80, v14
	v_and_b32_e32 v15, 0xffffff80, v15
	v_and_b32_e32 v16, 0xffffff80, v16
	v_and_b32_e32 v17, 0xffffff80, v17
	v_and_b32_e32 v6, 0xffffff80, v6
	v_and_b32_e32 v7, 0xffffff80, v7
	v_and_b32_e32 v8, 0xffffff80, v8
	v_or3_b32 v4, v101, v4, s8
	v_and_b32_e32 v9, 0xffffff80, v9
	v_and_b32_e32 v5, 0xffffff80, v5
	s_movk_i32 s8, 0x73
	v_min_f32_e32 v104, v63, v47
	v_min_f32_e32 v83, v55, v106
	v_min_f32_e32 v47, v109, v110
	v_min_f32_e32 v91, v71, v87
	v_max_f32_e32 v100, v71, v87
	v_max_f32_e32 v87, v55, v106
	v_max_f32_e32 v55, v109, v110
	v_or3_b32 v24, v101, v24, 18
	v_or3_b32 v25, v101, v25, 19
	v_or3_b32 v14, v101, v14, 32
	v_or3_b32 v15, v101, v15, 33
	v_or3_b32 v16, v101, v16, 34
	v_or3_b32 v17, v101, v17, 35
	v_or3_b32 v6, v101, v6, 48
	v_or3_b32 v7, v101, v7, 49
	v_or3_b32 v8, v101, v8, 50
	v_or3_b32 v9, v101, v9, 51
	v_or3_b32 v5, v101, v5, s8
	v_max_f32_e32 v101, v30, v31
	v_min_f32_e32 v30, v30, v31
	v_max_f32_e32 v31, v32, v32
	v_max_f32_e32 v32, v33, v33
	v_max_f32_e32 v109, v26, v27
	v_min_f32_e32 v26, v26, v27
	v_max_f32_e32 v27, v28, v28
	v_max_f32_e32 v28, v29, v29
	v_max_f32_e32 v33, v32, v31
	v_min_f32_e32 v31, v32, v31
	v_max_f32_e32 v32, v22, v23
	v_min_f32_e32 v22, v22, v23
	v_max_f32_e32 v23, v24, v24
	v_max_f32_e32 v24, v25, v25
	v_max_f32_e32 v29, v28, v27
	v_min_f32_e32 v27, v28, v27
	v_max_f32_e32 v28, v18, v19
	v_min_f32_e32 v18, v18, v19
	v_max_f32_e32 v19, v20, v20
	v_max_f32_e32 v20, v21, v21
	v_max_f32_e32 v25, v24, v23
	v_min_f32_e32 v23, v24, v23
	v_max_f32_e32 v24, v14, v15
	v_min_f32_e32 v14, v14, v15
; DEV void ce(float& a, float& b) { float hi = fmaxf(a, b), lo = fminf(a, b); a = hi; b = lo; }
; DEV void sort16_desc(float (&a)[16]) {
; #pragma unroll
;   for (int k = 2; k <= 16; k <<= 1)
; #pragma unroll
;     for (int j = k >> 1; j > 0; j >>= 1)
; #pragma unroll
;       for (int i = 0; i < 16; i++) {
;         const int p = i ^ j;
;         if (p > i) { if ((i & k) == 0) ce(a[i], a[p]); else ce(a[p], a[i]); }
;       }
; }
	v_max_f32_e32 v15, v16, v16
	v_max_f32_e32 v16, v17, v17
	v_max_f32_e32 v21, v20, v19
	v_min_f32_e32 v19, v20, v19
	v_max_f32_e32 v20, v10, v11
	v_min_f32_e32 v10, v10, v11
	v_max_f32_e32 v11, v12, v12
	v_max_f32_e32 v12, v13, v13
	v_max_f32_e32 v17, v16, v15
	v_min_f32_e32 v15, v16, v15
	v_max_f32_e32 v16, v6, v7
	v_min_f32_e32 v6, v6, v7
	v_max_f32_e32 v7, v8, v8
	v_max_f32_e32 v8, v9, v9
	v_max_f32_e32 v13, v12, v11
	v_min_f32_e32 v11, v12, v11
	v_max_f32_e32 v12, v2, v3
	v_min_f32_e32 v2, v2, v3
	v_max_f32_e32 v3, v4, v4
	v_max_f32_e32 v4, v5, v5
	v_max_f32_e32 v9, v8, v7
	v_min_f32_e32 v7, v8, v7
	v_max_f32_e32 v5, v4, v3
	v_min_f32_e32 v3, v4, v3
	v_max_f32_e32 v8, v101, v31
	v_min_f32_e32 v31, v101, v31
	v_max_f32_e32 v101, v30, v33
	v_min_f32_e32 v30, v30, v33
	v_max_f32_e32 v33, v23, v32
	v_min_f32_e32 v23, v23, v32
	v_max_f32_e32 v32, v25, v22
	v_min_f32_e32 v22, v25, v22
	v_max_f32_e32 v25, v24, v15
	v_min_f32_e32 v15, v24, v15
	v_max_f32_e32 v24, v14, v17
	v_min_f32_e32 v14, v14, v17
	v_max_f32_e32 v17, v7, v16
	v_min_f32_e32 v7, v7, v16
	v_max_f32_e32 v16, v9, v6
	v_min_f32_e32 v6, v9, v6
	v_max_f32_e32 v4, v109, v27
	v_min_f32_e32 v27, v109, v27
	v_max_f32_e32 v109, v26, v29
	v_min_f32_e32 v26, v26, v29
	v_max_f32_e32 v29, v19, v28
	v_min_f32_e32 v19, v19, v28
	v_max_f32_e32 v28, v21, v18
	v_min_f32_e32 v18, v21, v18
	v_max_f32_e32 v21, v20, v11
	v_min_f32_e32 v11, v20, v11
	v_max_f32_e32 v20, v10, v13
	v_min_f32_e32 v10, v10, v13
	v_max_f32_e32 v13, v3, v12
	v_min_f32_e32 v3, v3, v12
	v_max_f32_e32 v12, v5, v2
	v_min_f32_e32 v2, v5, v2
	v_max_f32_e32 v9, v8, v101
	v_min_f32_e32 v8, v8, v101
	v_max_f32_e32 v101, v31, v30
	v_min_f32_e32 v30, v31, v30
	v_max_f32_e32 v31, v22, v23
	v_min_f32_e32 v22, v22, v23
	v_max_f32_e32 v23, v32, v33
	v_min_f32_e32 v32, v32, v33
	v_max_f32_e32 v33, v25, v24
	v_min_f32_e32 v24, v25, v24
	v_max_f32_e32 v25, v15, v14
	v_min_f32_e32 v14, v15, v14
	v_max_f32_e32 v15, v6, v7
	v_min_f32_e32 v6, v6, v7
	v_max_f32_e32 v7, v16, v17
	v_min_f32_e32 v16, v16, v17
	v_max_f32_e32 v5, v4, v109
	v_min_f32_e32 v4, v4, v109
	v_max_f32_e32 v109, v27, v26
	v_min_f32_e32 v26, v27, v26
	v_max_f32_e32 v27, v18, v19
	v_min_f32_e32 v18, v18, v19
	v_max_f32_e32 v19, v28, v29
	v_min_f32_e32 v28, v28, v29
	v_max_f32_e32 v29, v21, v20
	v_min_f32_e32 v20, v21, v20
	v_max_f32_e32 v21, v11, v10
	v_min_f32_e32 v10, v11, v10
	v_max_f32_e32 v11, v2, v3
	v_min_f32_e32 v2, v2, v3
	v_max_f32_e32 v3, v12, v13
	v_min_f32_e32 v12, v12, v13
	v_max_f32_e32 v17, v9, v22
	v_min_f32_e32 v9, v9, v22
	v_max_f32_e32 v22, v8, v31
	v_min_f32_e32 v8, v8, v31
	v_max_f32_e32 v31, v101, v32
	v_min_f32_e32 v32, v101, v32
	v_max_f32_e32 v101, v30, v23
	v_min_f32_e32 v23, v30, v23
	v_max_f32_e32 v30, v6, v33
	v_min_f32_e32 v6, v6, v33
	v_max_f32_e32 v33, v15, v24
	v_min_f32_e32 v15, v15, v24
	v_max_f32_e32 v24, v16, v25
	v_min_f32_e32 v16, v16, v25
	v_max_f32_e32 v25, v7, v14
	v_min_f32_e32 v7, v7, v14
	v_max_f32_e32 v13, v5, v18
	v_min_f32_e32 v5, v5, v18
	v_max_f32_e32 v18, v4, v27
	v_min_f32_e32 v4, v4, v27
	v_max_f32_e32 v27, v109, v28
	v_min_f32_e32 v28, v109, v28
	v_max_f32_e32 v109, v26, v19
	v_min_f32_e32 v19, v26, v19
	v_max_f32_e32 v26, v2, v29
	v_min_f32_e32 v2, v2, v29
	v_max_f32_e32 v29, v11, v20
	v_min_f32_e32 v11, v11, v20
	v_max_f32_e32 v20, v12, v21
	v_min_f32_e32 v12, v12, v21
	v_max_f32_e32 v21, v3, v10
	v_min_f32_e32 v3, v3, v10
	v_max_f32_e32 v14, v17, v31
	v_min_f32_e32 v17, v17, v31
	v_max_f32_e32 v31, v22, v101
	v_min_f32_e32 v22, v22, v101
	v_max_f32_e32 v101, v9, v32
	v_min_f32_e32 v9, v9, v32
	v_max_f32_e32 v32, v8, v23
	v_min_f32_e32 v8, v8, v23
	v_max_f32_e32 v23, v16, v6
	v_min_f32_e32 v6, v16, v6
	v_max_f32_e32 v16, v7, v15
	v_min_f32_e32 v7, v7, v15
	v_max_f32_e32 v15, v24, v30
	v_min_f32_e32 v24, v24, v30
	v_max_f32_e32 v30, v25, v33
	v_min_f32_e32 v25, v25, v33
	v_max_f32_e32 v10, v13, v27
	v_min_f32_e32 v13, v13, v27
	v_max_f32_e32 v27, v18, v109
	v_min_f32_e32 v18, v18, v109
	v_max_f32_e32 v109, v5, v28
	v_min_f32_e32 v5, v5, v28
	v_max_f32_e32 v28, v4, v19
	v_min_f32_e32 v4, v4, v19
	v_max_f32_e32 v19, v12, v2
	v_min_f32_e32 v2, v12, v2
	v_max_f32_e32 v12, v3, v11
	v_min_f32_e32 v3, v3, v11
	v_max_f32_e32 v11, v20, v26
	v_min_f32_e32 v20, v20, v26
	v_max_f32_e32 v26, v21, v29
	v_min_f32_e32 v21, v21, v29
	v_max_f32_e32 v33, v14, v31
	v_min_f32_e32 v14, v14, v31
	v_max_f32_e32 v31, v17, v22
	v_min_f32_e32 v17, v17, v22
	v_max_f32_e32 v22, v101, v32
	v_min_f32_e32 v32, v101, v32
	v_max_f32_e32 v101, v9, v8
	v_min_f32_e32 v8, v9, v8
	v_max_f32_e32 v9, v7, v6
	v_min_f32_e32 v6, v7, v6
	v_max_f32_e32 v7, v16, v23
	v_min_f32_e32 v16, v16, v23
	v_max_f32_e32 v23, v25, v24
	v_min_f32_e32 v24, v25, v24
	v_max_f32_e32 v25, v30, v15
	v_min_f32_e32 v15, v30, v15
	v_max_f32_e32 v29, v10, v27
	v_min_f32_e32 v10, v10, v27
	v_max_f32_e32 v27, v13, v18
	v_min_f32_e32 v13, v13, v18
	v_max_f32_e32 v18, v109, v28
	v_min_f32_e32 v28, v109, v28
	v_max_f32_e32 v109, v5, v4
	v_min_f32_e32 v4, v5, v4
	v_max_f32_e32 v5, v3, v2
	v_min_f32_e32 v2, v3, v2
	v_max_f32_e32 v3, v12, v19
	v_min_f32_e32 v12, v12, v19
	v_max_f32_e32 v19, v21, v20
	v_min_f32_e32 v20, v21, v20
	v_max_f32_e32 v21, v26, v11
	v_min_f32_e32 v11, v26, v11
	v_max_f32_e32 v30, v33, v6
	v_min_f32_e32 v6, v33, v6
	v_max_f32_e32 v33, v14, v9
	v_min_f32_e32 v9, v14, v9
	v_max_f32_e32 v14, v31, v16
	v_min_f32_e32 v16, v31, v16
	v_max_f32_e32 v31, v17, v7
	v_min_f32_e32 v7, v17, v7
	v_max_f32_e32 v17, v22, v24
	v_min_f32_e32 v22, v22, v24
	v_max_f32_e32 v24, v32, v23
	v_min_f32_e32 v23, v32, v23
	v_max_f32_e32 v32, v101, v15
	v_min_f32_e32 v15, v101, v15
	v_max_f32_e32 v101, v8, v25
; DEV void ce(float& a, float& b) { float hi = fmaxf(a, b), lo = fminf(a, b); a = hi; b = lo; }
; DEV void sort16_desc(float (&a)[16]) {
; #pragma unroll
;   for (int k = 2; k <= 16; k <<= 1)
; #pragma unroll
;     for (int j = k >> 1; j > 0; j >>= 1)
; #pragma unroll
;       for (int i = 0; i < 16; i++) {
;         const int p = i ^ j;
;         if (p > i) { if ((i & k) == 0) ce(a[i], a[p]); else ce(a[p], a[i]); }
;       }
; }
; DEV void merge_xor(float (&l)[16], int mask) {
;   float t[16];
; #pragma unroll
;   for (int i = 0; i < 16; i++) t[i] = __shfl_xor(l[15 - i], mask);
; #pragma unroll
;   for (int i = 0; i < 16; i++) l[i] = fmaxf(l[i], t[i]);
;   bitonic16(l);
; }
; DEV void peer_top16(const bf16_t* __restrict__ pq, const bf16_t* sk  , float (&l)[16]) {
;     ...
;   sort16_desc(l);
;   sort16_desc(hi);
; #pragma unroll
;   for (int i = 0; i < 16; i++) l[i] = fmaxf(l[i], hi[15 - i]);
;   bitonic16(l);
;   merge_xor(l, 16);
	v_min_f32_e32 v8, v8, v25
	v_max_f32_e32 v26, v29, v2
	v_min_f32_e32 v2, v29, v2
	v_max_f32_e32 v29, v10, v5
	v_min_f32_e32 v5, v10, v5
	v_max_f32_e32 v10, v27, v12
	v_min_f32_e32 v12, v27, v12
	v_max_f32_e32 v27, v13, v3
	v_min_f32_e32 v3, v13, v3
	v_max_f32_e32 v13, v18, v20
	v_min_f32_e32 v18, v18, v20
	v_max_f32_e32 v20, v28, v19
	v_min_f32_e32 v19, v28, v19
	v_max_f32_e32 v28, v109, v11
	v_min_f32_e32 v11, v109, v11
	v_max_f32_e32 v109, v4, v21
	v_min_f32_e32 v4, v4, v21
	v_max_f32_e32 v25, v30, v17
	v_min_f32_e32 v17, v30, v17
	v_max_f32_e32 v30, v33, v24
	v_min_f32_e32 v24, v33, v24
	v_max_f32_e32 v33, v14, v32
	v_min_f32_e32 v14, v14, v32
	v_max_f32_e32 v32, v31, v101
	v_min_f32_e32 v31, v31, v101
	v_max_f32_e32 v101, v6, v22
	v_min_f32_e32 v6, v6, v22
	v_max_f32_e32 v22, v9, v23
	v_min_f32_e32 v9, v9, v23
	v_max_f32_e32 v23, v16, v15
	v_min_f32_e32 v15, v16, v15
	v_max_f32_e32 v16, v7, v8
	v_min_f32_e32 v7, v7, v8
	v_max_f32_e32 v21, v26, v13
	v_min_f32_e32 v13, v26, v13
	v_max_f32_e32 v26, v29, v20
	v_min_f32_e32 v20, v29, v20
	v_max_f32_e32 v29, v10, v28
	v_min_f32_e32 v10, v10, v28
	v_max_f32_e32 v28, v27, v109
	v_min_f32_e32 v27, v27, v109
	v_max_f32_e32 v109, v2, v18
	v_min_f32_e32 v2, v2, v18
	v_max_f32_e32 v18, v5, v19
	v_min_f32_e32 v5, v5, v19
	v_max_f32_e32 v19, v12, v11
	v_min_f32_e32 v11, v12, v11
	v_max_f32_e32 v12, v3, v4
	v_min_f32_e32 v3, v3, v4
	v_max_f32_e32 v111, v0, v43
	v_min_f32_e32 v112, v104, v39
	v_max_f32_e32 v103, v104, v39
	v_min_f32_e32 v0, v0, v43
	v_max_f32_e32 v8, v25, v33
	v_min_f32_e32 v25, v25, v33
	v_max_f32_e32 v33, v30, v32
	v_min_f32_e32 v30, v30, v32
	v_max_f32_e32 v32, v17, v14
	v_min_f32_e32 v14, v17, v14
	v_max_f32_e32 v17, v24, v31
	v_min_f32_e32 v24, v24, v31
	v_max_f32_e32 v31, v101, v23
	v_min_f32_e32 v23, v101, v23
	v_max_f32_e32 v101, v22, v16
	v_min_f32_e32 v16, v22, v16
	v_max_f32_e32 v22, v6, v15
	v_min_f32_e32 v6, v6, v15
	v_max_f32_e32 v15, v9, v7
	v_min_f32_e32 v7, v9, v7
	v_max_f32_e32 v4, v21, v29
	v_min_f32_e32 v21, v21, v29
	v_max_f32_e32 v29, v26, v28
	v_min_f32_e32 v26, v26, v28
	v_max_f32_e32 v28, v13, v10
	v_min_f32_e32 v10, v13, v10
	v_max_f32_e32 v13, v20, v27
	v_min_f32_e32 v20, v20, v27
	v_max_f32_e32 v27, v109, v19
	v_min_f32_e32 v19, v109, v19
	v_max_f32_e32 v109, v18, v12
	v_min_f32_e32 v12, v18, v12
	v_max_f32_e32 v18, v2, v11
	v_min_f32_e32 v2, v2, v11
	v_max_f32_e32 v11, v5, v3
	v_min_f32_e32 v3, v5, v3
	v_min_f32_e32 v63, v107, v108
	v_min_f32_e32 v39, v111, v103
	v_max_f32_e32 v71, v107, v108
	v_max_f32_e32 v51, v111, v103
	v_max_f32_e32 v43, v0, v112
	v_min_f32_e32 v0, v0, v112
	v_min_f32_e32 v9, v8, v33
	v_min_f32_e32 v102, v25, v30
	v_min_f32_e32 v103, v32, v17
	v_min_f32_e32 v104, v14, v24
	v_min_f32_e32 v105, v31, v101
	v_min_f32_e32 v106, v23, v16
	v_min_f32_e32 v107, v22, v15
	v_min_f32_e32 v108, v6, v7
	v_min_f32_e32 v5, v4, v29
	v_min_f32_e32 v110, v21, v26
	v_min_f32_e32 v111, v28, v13
	v_min_f32_e32 v112, v10, v20
	v_min_f32_e32 v113, v27, v109
	v_min_f32_e32 v114, v19, v12
	v_min_f32_e32 v115, v18, v11
	v_min_f32_e32 v116, v2, v3
	v_max3_f32 v8, v8, v33, v116
	v_max3_f32 v2, v9, v2, v3
	v_max3_f32 v3, v25, v30, v115
	v_max3_f32 v9, v102, v18, v11
	v_max3_f32 v11, v32, v17, v114
	v_max3_f32 v12, v103, v19, v12
	v_max3_f32 v14, v14, v24, v113
	v_max3_f32 v17, v104, v27, v109
	v_max3_f32 v18, v31, v101, v112
	v_max3_f32 v10, v105, v10, v20
	v_max3_f32 v16, v23, v16, v111
	v_max3_f32 v13, v106, v28, v13
	v_max3_f32 v15, v22, v15, v110
	v_max3_f32 v19, v107, v21, v26
	v_max3_f32 v5, v6, v7, v5
	v_max3_f32 v4, v108, v4, v29
	v_max_f32_e32 v6, v8, v18
	v_min_f32_e32 v7, v8, v18
	v_max_f32_e32 v8, v2, v10
	v_min_f32_e32 v2, v2, v10
	v_max_f32_e32 v10, v3, v16
	v_min_f32_e32 v3, v3, v16
	v_max_f32_e32 v16, v9, v13
	v_min_f32_e32 v9, v9, v13
	v_max_f32_e32 v13, v11, v15
	v_min_f32_e32 v11, v11, v15
	v_max_f32_e32 v15, v12, v19
	v_min_f32_e32 v12, v12, v19
	v_max_f32_e32 v18, v14, v5
	v_min_f32_e32 v5, v14, v5
	v_max_f32_e32 v14, v17, v4
	v_min_f32_e32 v4, v17, v4
	v_max_f32_e32 v17, v6, v13
	v_min_f32_e32 v6, v6, v13
	v_max_f32_e32 v13, v8, v15
	v_min_f32_e32 v8, v8, v15
	v_max_f32_e32 v15, v10, v18
	v_min_f32_e32 v10, v10, v18
	v_max_f32_e32 v18, v16, v14
	v_min_f32_e32 v14, v16, v14
	v_max_f32_e32 v16, v7, v11
	v_min_f32_e32 v7, v7, v11
	v_max_f32_e32 v11, v2, v12
	v_min_f32_e32 v2, v2, v12
	v_max_f32_e32 v12, v3, v5
	v_min_f32_e32 v3, v3, v5
	v_max_f32_e32 v5, v9, v4
	v_min_f32_e32 v4, v9, v4
	v_max_f32_e32 v9, v17, v15
	v_min_f32_e32 v15, v17, v15
	v_max_f32_e32 v17, v13, v18
	v_min_f32_e32 v13, v13, v18
	v_max_f32_e32 v18, v6, v10
	v_min_f32_e32 v6, v6, v10
	v_max_f32_e32 v10, v8, v14
	v_min_f32_e32 v8, v8, v14
	v_max_f32_e32 v14, v16, v12
	v_min_f32_e32 v12, v16, v12
	v_max_f32_e32 v16, v11, v5
	v_min_f32_e32 v5, v11, v5
	v_max_f32_e32 v11, v7, v3
	v_min_f32_e32 v3, v7, v3
	v_max_f32_e32 v7, v2, v4
	v_min_f32_e32 v2, v2, v4
	v_max_f32_e32 v4, v9, v17
	v_min_f32_e32 v9, v9, v17
	v_max_f32_e32 v17, v15, v13
	v_min_f32_e32 v13, v15, v13
	v_max_f32_e32 v15, v18, v10
	v_min_f32_e32 v10, v18, v10
	v_max_f32_e32 v18, v6, v8
	v_min_f32_e32 v6, v6, v8
	v_max_f32_e32 v8, v14, v16
	v_min_f32_e32 v14, v14, v16
	v_max_f32_e32 v16, v12, v5
	v_min_f32_e32 v5, v12, v5
	v_max_f32_e32 v12, v11, v7
	v_min_f32_e32 v7, v11, v7
	v_max_f32_e32 v11, v3, v2
	v_min_f32_e32 v2, v3, v2
	ds_bpermute_b32 v3, v95, v2
	ds_bpermute_b32 v19, v95, v11
	ds_bpermute_b32 v20, v95, v7
	ds_bpermute_b32 v21, v95, v12
	ds_bpermute_b32 v22, v95, v5
	ds_bpermute_b32 v23, v95, v16
	s_waitcnt lgkmcnt(5)
	ds_bpermute_b32 v24, v95, v14
	ds_bpermute_b32 v33, v95, v4
	v_max_f32_e32 v3, v4, v3
	s_waitcnt lgkmcnt(6)
; DEV void merge_xor(float (&l)[16], int mask) {
;   float t[16];
; #pragma unroll
;   for (int i = 0; i < 16; i++) t[i] = __shfl_xor(l[15 - i], mask);
; #pragma unroll
;   for (int i = 0; i < 16; i++) l[i] = fmaxf(l[i], t[i]);
;   bitonic16(l);
; }
; DEV void phase_peer_score(const Params& p, int layer, int M, char* smem) {
;     ...
;     unsigned char* tab = (unsigned char*)smem + 73728 + (w * 16 + l15) * 32;
; #pragma unroll
;     for (int i = 0; i < 16; i++) { tab[i] = (unsigned char)(__float_as_uint(L0[i]) & 127u); tab[16 + i] = (unsigned char)(__float_as_uint(L1[i]) & 127u); }
	ds_bpermute_b32 v25, v95, v8
	ds_bpermute_b32 v32, v95, v9
	v_max_f32_e32 v4, v9, v19
	s_waitcnt lgkmcnt(7)
	ds_bpermute_b32 v26, v95, v6
	ds_bpermute_b32 v31, v95, v17
	v_max_f32_e32 v9, v17, v20
	s_waitcnt lgkmcnt(8)
	ds_bpermute_b32 v27, v95, v18
	ds_bpermute_b32 v30, v95, v13
	v_max_f32_e32 v13, v13, v21
	s_waitcnt lgkmcnt(9)
	ds_bpermute_b32 v28, v95, v10
	ds_bpermute_b32 v29, v95, v15
	v_max_f32_e32 v15, v15, v22
	s_waitcnt lgkmcnt(10)
	v_max_f32_e32 v10, v10, v23
	s_waitcnt lgkmcnt(9)
	v_max_f32_e32 v17, v18, v24
	s_waitcnt lgkmcnt(7)
	v_max_f32_e32 v6, v6, v25
	s_waitcnt lgkmcnt(5)
	v_max_f32_e32 v8, v8, v26
	s_waitcnt lgkmcnt(3)
	v_max_f32_e32 v14, v14, v27
	s_waitcnt lgkmcnt(1)
	v_max_f32_e32 v16, v16, v28
	s_waitcnt lgkmcnt(0)
	v_max_f32_e32 v5, v5, v29
	v_max_f32_e32 v12, v12, v30
	v_max_f32_e32 v7, v7, v31
	v_max_f32_e32 v11, v11, v32
	v_max_f32_e32 v2, v2, v33
	v_max_f32_e32 v18, v3, v8
	v_min_f32_e32 v3, v3, v8
	v_max_f32_e32 v8, v4, v14
	v_min_f32_e32 v4, v4, v14
	v_max_f32_e32 v14, v9, v16
	v_min_f32_e32 v9, v9, v16
	v_max_f32_e32 v16, v13, v5
	v_min_f32_e32 v5, v13, v5
	v_max_f32_e32 v13, v15, v12
	v_min_f32_e32 v12, v15, v12
	v_max_f32_e32 v15, v10, v7
	v_min_f32_e32 v7, v10, v7
	v_max_f32_e32 v10, v17, v11
	v_min_f32_e32 v11, v17, v11
	v_max_f32_e32 v17, v6, v2
	v_min_f32_e32 v2, v6, v2
	v_max_f32_e32 v6, v18, v13
	v_min_f32_e32 v13, v18, v13
	v_max_f32_e32 v18, v8, v15
	v_min_f32_e32 v8, v8, v15
	v_max_f32_e32 v15, v14, v10
	v_min_f32_e32 v10, v14, v10
	v_max_f32_e32 v14, v16, v17
	v_min_f32_e32 v16, v16, v17
	v_max_f32_e32 v17, v3, v12
	v_min_f32_e32 v3, v3, v12
	v_max_f32_e32 v12, v4, v7
	v_min_f32_e32 v4, v4, v7
	v_max_f32_e32 v7, v9, v11
	v_min_f32_e32 v9, v9, v11
	v_max_f32_e32 v11, v5, v2
	v_min_f32_e32 v2, v5, v2
	v_max_f32_e32 v5, v6, v15
	v_min_f32_e32 v6, v6, v15
	v_max_f32_e32 v15, v18, v14
	v_min_f32_e32 v14, v18, v14
	v_max_f32_e32 v18, v13, v10
	v_min_f32_e32 v10, v13, v10
	v_max_f32_e32 v13, v8, v16
	v_min_f32_e32 v8, v8, v16
	v_max_f32_e32 v16, v17, v7
	v_min_f32_e32 v7, v17, v7
	v_max_f32_e32 v17, v12, v11
	v_min_f32_e32 v11, v12, v11
	v_max_f32_e32 v12, v3, v9
	v_min_f32_e32 v3, v3, v9
	v_max_f32_e32 v9, v4, v2
	v_min_f32_e32 v2, v4, v2
	v_max_f32_e32 v4, v5, v15
	v_min_f32_e32 v5, v5, v15
	v_max_f32_e32 v15, v6, v14
	v_min_f32_e32 v6, v6, v14
	v_max_f32_e32 v14, v18, v13
	v_min_f32_e32 v13, v18, v13
	v_max_f32_e32 v18, v10, v8
	v_min_f32_e32 v8, v10, v8
	v_max_f32_e32 v10, v16, v17
	v_min_f32_e32 v16, v16, v17
	v_max_f32_e32 v17, v7, v11
	v_min_f32_e32 v7, v7, v11
	v_max_f32_e32 v11, v12, v9
	v_min_f32_e32 v9, v12, v9
	v_max_f32_e32 v12, v3, v2
	v_min_f32_e32 v2, v3, v2
	ds_bpermute_b32 v3, v99, v2
	ds_bpermute_b32 v19, v99, v12
	ds_bpermute_b32 v20, v99, v9
	ds_bpermute_b32 v21, v99, v11
	ds_bpermute_b32 v22, v99, v7
	ds_bpermute_b32 v23, v99, v17
	s_waitcnt lgkmcnt(5)
	ds_bpermute_b32 v24, v99, v16
	ds_bpermute_b32 v33, v99, v4
	v_max_f32_e32 v3, v4, v3
	s_waitcnt lgkmcnt(6)
	ds_bpermute_b32 v25, v99, v10
	ds_bpermute_b32 v32, v99, v5
	v_max_f32_e32 v4, v5, v19
	s_waitcnt lgkmcnt(7)
	ds_bpermute_b32 v26, v99, v8
	ds_bpermute_b32 v31, v99, v15
	v_max_f32_e32 v5, v15, v20
	s_waitcnt lgkmcnt(8)
	ds_bpermute_b32 v27, v99, v18
	ds_bpermute_b32 v30, v99, v6
	v_max_f32_e32 v6, v6, v21
	s_waitcnt lgkmcnt(9)
	ds_bpermute_b32 v28, v99, v13
	ds_bpermute_b32 v29, v99, v14
	v_max_f32_e32 v14, v14, v22
	s_waitcnt lgkmcnt(10)
	v_max_f32_e32 v13, v13, v23
	s_waitcnt lgkmcnt(9)
	v_max_f32_e32 v15, v18, v24
	s_waitcnt lgkmcnt(7)
	v_max_f32_e32 v8, v8, v25
	s_waitcnt lgkmcnt(5)
	v_max_f32_e32 v10, v10, v26
	s_waitcnt lgkmcnt(3)
	v_max_f32_e32 v16, v16, v27
	s_waitcnt lgkmcnt(1)
	v_max_f32_e32 v17, v17, v28
	s_waitcnt lgkmcnt(0)
	v_max_f32_e32 v7, v7, v29
	v_max_f32_e32 v11, v11, v30
	v_max_f32_e32 v9, v9, v31
	v_max_f32_e32 v12, v12, v32
	v_max_f32_e32 v2, v2, v33
	v_max_f32_e32 v18, v3, v10
	v_min_f32_e32 v3, v3, v10
	v_max_f32_e32 v10, v4, v16
	v_min_f32_e32 v4, v4, v16
	v_max_f32_e32 v16, v5, v17
	v_min_f32_e32 v5, v5, v17
	v_max_f32_e32 v17, v6, v7
	v_min_f32_e32 v6, v6, v7
	v_max_f32_e32 v7, v14, v11
	v_min_f32_e32 v11, v14, v11
	v_max_f32_e32 v14, v13, v9
	v_min_f32_e32 v9, v13, v9
	v_max_f32_e32 v13, v15, v12
	v_min_f32_e32 v12, v15, v12
	v_max_f32_e32 v15, v8, v2
	v_min_f32_e32 v2, v8, v2
	v_max_f32_e32 v8, v18, v7
	v_min_f32_e32 v7, v18, v7
	v_max_f32_e32 v18, v10, v14
	v_min_f32_e32 v10, v10, v14
	v_max_f32_e32 v14, v16, v13
	v_min_f32_e32 v13, v16, v13
	v_max_f32_e32 v16, v17, v15
	v_min_f32_e32 v15, v17, v15
	v_max_f32_e32 v17, v3, v11
	v_min_f32_e32 v3, v3, v11
	v_max_f32_e32 v11, v4, v9
	v_min_f32_e32 v4, v4, v9
	v_max_f32_e32 v9, v5, v12
	v_min_f32_e32 v5, v5, v12
	v_max_f32_e32 v12, v6, v2
	v_min_f32_e32 v2, v6, v2
	v_max_f32_e32 v6, v8, v14
	v_min_f32_e32 v8, v8, v14
	v_max_f32_e32 v14, v18, v16
	v_min_f32_e32 v16, v18, v16
	v_max_f32_e32 v18, v7, v13
	v_max_f32_e32 v19, v10, v15
	s_movk_i32 s8, 0x7f
	v_min_f32_e32 v13, v7, v13
	v_min_f32_e32 v10, v10, v15
	v_max_f32_e32 v15, v17, v9
	v_min_f32_e32 v21, v17, v9
	v_max_f32_e32 v17, v11, v12
	v_min_f32_e32 v22, v11, v12
	v_max_f32_e32 v23, v3, v5
	v_min_f32_e32 v3, v3, v5
	v_max_f32_e32 v5, v4, v2
	v_min_f32_e32 v24, v4, v2
	v_max_f32_e32 v9, v18, v19
	v_min_f32_e32 v12, v18, v19
	v_and_b32_sdwa v18, v63, s8 dst_sel:BYTE_1 dst_unused:UNUSED_PAD src0_sel:DWORD src1_sel:DWORD
	v_max_f32_e32 v2, v6, v14
	v_min_f32_e32 v4, v6, v14
	v_max_f32_e32 v11, v13, v10
	v_min_f32_e32 v10, v13, v10
	v_max_f32_e32 v14, v23, v5
	v_min_f32_e32 v13, v23, v5
	v_max_f32_e32 v6, v3, v24
	v_min_f32_e32 v5, v3, v24
	v_and_b32_sdwa v3, v75, s8 dst_sel:BYTE_1 dst_unused:UNUSED_PAD src0_sel:DWORD src1_sel:DWORD
; DEV void ce(float& a, float& b) { float hi = fmaxf(a, b), lo = fminf(a, b); a = hi; b = lo; }
; DEV void phase_peer_score(const Params& p, int layer, int M, char* smem) {
;     ...
; #pragma unroll
;     for (int i = 0; i < 16; i++) R[i] = -3.0e38f;
; #pragma unroll
;     for (int i = 0; i < 16; i++)
; #pragma unroll
;       for (int j = 0; j < 16; j++)
;         if ((i + 1) * (j + 1) <= 16) {
;           float v = L0[i] + L1[j];
;           v = __uint_as_float((__float_as_uint(v) & ~255u) | (unsigned)(i * 16 + j));
; #pragma unroll
;           for (int t = 0; t < 16; t++)
;             if (t >= (i + 1) * (j + 1) - 1) ce(R[t], v);
;         }
;     unsigned char* tab = (unsigned char*)smem + 73728 + (w * 16 + l15) * 32;
; #pragma unroll
;     for (int i = 0; i < 16; i++) { tab[i] = (unsigned char)(__float_as_uint(L0[i]) & 127u); tab[16 + i] = (unsigned char)(__float_as_uint(L1[i]) & 127u); }
	v_bitop3_b16 v18, v71, v18, s8 bitop3:0xec
	v_bitop3_b16 v3, v79, v3, s8 bitop3:0xec
	v_lshlrev_b32_e32 v18, 16, v18
	v_or_b32_sdwa v23, v3, v18 dst_sel:DWORD dst_unused:UNUSED_PAD src0_sel:WORD_0 src1_sel:DWORD
	v_and_b32_sdwa v18, v83, s8 dst_sel:BYTE_1 dst_unused:UNUSED_PAD src0_sel:DWORD src1_sel:DWORD
	v_and_b32_sdwa v3, v91, s8 dst_sel:BYTE_1 dst_unused:UNUSED_PAD src0_sel:DWORD src1_sel:DWORD
	v_bitop3_b16 v18, v87, v18, s8 bitop3:0xec
	v_bitop3_b16 v3, v100, v3, s8 bitop3:0xec
	v_lshlrev_b32_e32 v18, 16, v18
	v_max_f32_e32 v7, v8, v16
	v_min_f32_e32 v8, v8, v16
	v_max_f32_e32 v20, v15, v17
	v_min_f32_e32 v17, v15, v17
	v_max_f32_e32 v16, v21, v22
	v_min_f32_e32 v15, v21, v22
	v_or_b32_sdwa v22, v3, v18 dst_sel:DWORD dst_unused:UNUSED_PAD src0_sel:WORD_0 src1_sel:DWORD
	v_and_b32_sdwa v18, v10, s8 dst_sel:BYTE_1 dst_unused:UNUSED_PAD src0_sel:DWORD src1_sel:DWORD
	v_and_b32_sdwa v3, v12, s8 dst_sel:BYTE_1 dst_unused:UNUSED_PAD src0_sel:DWORD src1_sel:DWORD
	v_bitop3_b16 v18, v11, v18, s8 bitop3:0xec
	v_bitop3_b16 v3, v9, v3, s8 bitop3:0xec
	v_lshlrev_b32_e32 v18, 16, v18
	v_or_b32_sdwa v27, v3, v18 dst_sel:DWORD dst_unused:UNUSED_PAD src0_sel:WORD_0 src1_sel:DWORD
	v_and_b32_sdwa v18, v8, s8 dst_sel:BYTE_1 dst_unused:UNUSED_PAD src0_sel:DWORD src1_sel:DWORD
	v_and_b32_sdwa v3, v4, s8 dst_sel:BYTE_1 dst_unused:UNUSED_PAD src0_sel:DWORD src1_sel:DWORD
	v_bitop3_b16 v18, v7, v18, s8 bitop3:0xec
	v_bitop3_b16 v3, v2, v3, s8 bitop3:0xec
	v_lshlrev_b32_e32 v18, 16, v18
	v_or_b32_sdwa v26, v3, v18 dst_sel:DWORD dst_unused:UNUSED_PAD src0_sel:WORD_0 src1_sel:DWORD
	v_and_b32_sdwa v18, v0, s8 dst_sel:BYTE_1 dst_unused:UNUSED_PAD src0_sel:DWORD src1_sel:DWORD
	v_and_b32_sdwa v3, v39, s8 dst_sel:BYTE_1 dst_unused:UNUSED_PAD src0_sel:DWORD src1_sel:DWORD
	v_bitop3_b16 v18, v43, v18, s8 bitop3:0xec
	v_bitop3_b16 v3, v51, v3, s8 bitop3:0xec
	v_lshlrev_b32_e32 v18, 16, v18
	v_or_b32_sdwa v25, v3, v18 dst_sel:DWORD dst_unused:UNUSED_PAD src0_sel:WORD_0 src1_sel:DWORD
	v_and_b32_sdwa v18, v47, s8 dst_sel:BYTE_1 dst_unused:UNUSED_PAD src0_sel:DWORD src1_sel:DWORD
	v_and_b32_sdwa v3, v59, s8 dst_sel:BYTE_1 dst_unused:UNUSED_PAD src0_sel:DWORD src1_sel:DWORD
	v_bitop3_b16 v18, v55, v18, s8 bitop3:0xec
	v_bitop3_b16 v3, v67, v3, s8 bitop3:0xec
	v_lshlrev_b32_e32 v18, 16, v18
	v_or_b32_sdwa v24, v3, v18 dst_sel:DWORD dst_unused:UNUSED_PAD src0_sel:WORD_0 src1_sel:DWORD
	v_and_b32_sdwa v18, v5, s8 dst_sel:BYTE_1 dst_unused:UNUSED_PAD src0_sel:DWORD src1_sel:DWORD
	v_and_b32_sdwa v3, v13, s8 dst_sel:BYTE_1 dst_unused:UNUSED_PAD src0_sel:DWORD src1_sel:DWORD
	v_bitop3_b16 v18, v6, v18, s8 bitop3:0xec
	v_bitop3_b16 v3, v14, v3, s8 bitop3:0xec
	v_lshlrev_b32_e32 v18, 16, v18
	v_or_b32_sdwa v29, v3, v18 dst_sel:DWORD dst_unused:UNUSED_PAD src0_sel:WORD_0 src1_sel:DWORD
	v_and_b32_sdwa v18, v15, s8 dst_sel:BYTE_1 dst_unused:UNUSED_PAD src0_sel:DWORD src1_sel:DWORD
	v_and_b32_sdwa v3, v17, s8 dst_sel:BYTE_1 dst_unused:UNUSED_PAD src0_sel:DWORD src1_sel:DWORD
	v_bitop3_b16 v18, v16, v18, s8 bitop3:0xec
	v_bitop3_b16 v3, v20, v3, s8 bitop3:0xec
	v_lshlrev_b32_e32 v18, 16, v18
	v_or_b32_sdwa v28, v3, v18 dst_sel:DWORD dst_unused:UNUSED_PAD src0_sel:WORD_0 src1_sel:DWORD
	ds_write_b128 v138, v[22:25]
	ds_write_b128 v138, v[26:29] offset:16
	s_and_saveexec_b64 s[8:9], s[38:39]
	s_cbranch_execz .LBB0_627
	s_lshl_b32 s18, s16, 3
	v_add_f32_e32 v3, v100, v2
	s_andn2_b32 s18, s18, 63
	v_and_b32_e32 v3, 0xffffff00, v3
	v_add_u32_e32 v18, s18, v117
	v_add_f32_e32 v22, v100, v4
	s_movk_i32 s18, 0xff00
	v_min_f32_e32 v21, 0xff61b1e6, v3
	v_and_or_b32 v22, v22, s18, 1
	v_max_f32_e32 v21, 0xff61b1e6, v21
	v_add_f32_e32 v24, v100, v7
	v_min_f32_e32 v23, v21, v22
	v_and_or_b32 v24, v24, s18, 2
	v_max_f32_e32 v23, v21, v23
	v_add_f32_e32 v26, v100, v8
	v_min_f32_e32 v25, v23, v24
	v_and_or_b32 v26, v26, s18, 3
	v_max_f32_e32 v25, v23, v25
	v_add_f32_e32 v28, v100, v9
	v_min_f32_e32 v27, v25, v26
	v_and_or_b32 v28, v28, s18, 4
	v_max_f32_e32 v27, v25, v27
	v_add_f32_e32 v30, v100, v12
	v_min_f32_e32 v29, v27, v28
	v_and_or_b32 v30, v30, s18, 5
	v_max_f32_e32 v29, v27, v29
	v_add_f32_e32 v32, v100, v11
	v_min_f32_e32 v31, v29, v30
	v_and_or_b32 v32, v32, s18, 6
	v_max_f32_e32 v31, v29, v31
	v_add_f32_e32 v95, v100, v10
	v_min_f32_e32 v33, v31, v32
	v_and_or_b32 v95, v95, s18, 7
	v_max_f32_e32 v33, v31, v33
	v_add_f32_e32 v20, v100, v20
	v_min_f32_e32 v99, v33, v95
	v_and_or_b32 v20, v20, s18, 8
	v_max_f32_e32 v99, v33, v99
	v_add_f32_e32 v17, v100, v17
	v_min_f32_e32 v101, v99, v20
	v_and_or_b32 v17, v17, s18, 9
	v_max_f32_e32 v101, v99, v101
	v_add_f32_e32 v16, v100, v16
	v_min_f32_e32 v102, v101, v17
	v_and_or_b32 v16, v16, s18, 10
	v_max_f32_e32 v102, v101, v102
	v_add_f32_e32 v15, v100, v15
	v_min_f32_e32 v103, v102, v16
	v_and_or_b32 v15, v15, s18, 11
	v_max_f32_e32 v103, v102, v103
	v_add_f32_e32 v14, v100, v14
	v_min_f32_e32 v104, v103, v15
	v_and_or_b32 v14, v14, s18, 12
	v_max_f32_e32 v104, v103, v104
	v_add_f32_e32 v13, v100, v13
	v_min_f32_e32 v105, v104, v14
	v_and_or_b32 v13, v13, s18, 13
	v_max_f32_e32 v105, v104, v105
	v_add_f32_e32 v6, v100, v6
	v_min_f32_e32 v106, v105, v13
	v_and_or_b32 v6, v6, s18, 14
	v_max_f32_e32 v106, v105, v106
	v_add_f32_e32 v5, v100, v5
	v_min_f32_e32 v107, v106, v6
	v_and_or_b32 v5, v5, s18, 15
	v_max3_f32 v100, v106, v107, v5
	v_max_f32_e32 v106, v106, v6
	v_add_f32_e32 v6, v91, v2
	v_and_or_b32 v6, v6, s18, 16
	v_max_f32_e32 v5, v21, v22
	v_max_f32_e32 v23, v23, v24
	v_min_f32_e32 v21, v5, v6
	v_max_f32_e32 v25, v25, v26
	v_min_f32_e32 v22, v23, v21
	v_min_f32_e32 v24, v25, v22
	v_max_f32_e32 v22, v25, v22
	v_add_f32_e32 v25, v91, v4
; DEV void ce(float& a, float& b) { float hi = fmaxf(a, b), lo = fminf(a, b); a = hi; b = lo; }
; DEV void phase_peer_score(const Params& p, int layer, int M, char* smem) {
;     ...
; #pragma unroll
;     for (int i = 0; i < 16; i++) R[i] = -3.0e38f;
; #pragma unroll
;     for (int i = 0; i < 16; i++)
; #pragma unroll
;       for (int j = 0; j < 16; j++)
;         if ((i + 1) * (j + 1) <= 16) {
;           float v = L0[i] + L1[j];
;           v = __uint_as_float((__float_as_uint(v) & ~255u) | (unsigned)(i * 16 + j));
; #pragma unroll
;           for (int t = 0; t < 16; t++)
;             if (t >= (i + 1) * (j + 1) - 1) ce(R[t], v);
;         }
	v_and_or_b32 v25, v25, s18, 17
	v_max_f32_e32 v27, v27, v28
	v_max_f32_e32 v29, v29, v30
	v_min_f32_e32 v26, v27, v24
	v_max_f32_e32 v24, v27, v24
	v_min_f32_e32 v27, v22, v25
	v_max_f32_e32 v31, v31, v32
	v_min_f32_e32 v28, v29, v26
	v_max_f32_e32 v26, v29, v26
	v_min_f32_e32 v29, v24, v27
	v_min_f32_e32 v30, v31, v28
	v_max_f32_e32 v28, v31, v28
	v_min_f32_e32 v31, v26, v29
	v_max_f32_e32 v26, v26, v29
	v_add_f32_e32 v29, v91, v7
	v_max_f32_e32 v33, v33, v95
	v_and_or_b32 v29, v29, s18, 18
	v_max_f32_e32 v20, v99, v20
	v_min_f32_e32 v32, v33, v30
	v_min_f32_e32 v95, v20, v32
	v_max_f32_e32 v20, v20, v32
	v_max_f32_e32 v30, v33, v30
	v_min_f32_e32 v32, v28, v31
	v_max_f32_e32 v28, v28, v31
	v_min_f32_e32 v31, v26, v29
	v_max_f32_e32 v17, v101, v17
	v_min_f32_e32 v33, v30, v32
	v_max_f32_e32 v30, v30, v32
	v_min_f32_e32 v32, v28, v31
	v_min_f32_e32 v99, v17, v95
	v_max_f32_e32 v17, v17, v95
	v_min_f32_e32 v95, v20, v33
	v_max_f32_e32 v20, v20, v33
	v_min_f32_e32 v33, v30, v32
	v_max_f32_e32 v30, v30, v32
	v_add_f32_e32 v32, v91, v8
	v_and_or_b32 v32, v32, s18, 19
	v_max_f32_e32 v16, v102, v16
	v_max_f32_e32 v15, v103, v15
	v_min_f32_e32 v101, v16, v99
	v_max_f32_e32 v16, v16, v99
	v_min_f32_e32 v99, v17, v95
	v_max_f32_e32 v17, v17, v95
	v_min_f32_e32 v95, v20, v33
	v_max_f32_e32 v20, v20, v33
	v_min_f32_e32 v33, v30, v32
	v_max_f32_e32 v14, v104, v14
	v_min_f32_e32 v102, v15, v101
	v_max_f32_e32 v15, v15, v101
	v_min_f32_e32 v101, v16, v99
	v_max_f32_e32 v16, v16, v99
	v_min_f32_e32 v99, v17, v95
	v_max_f32_e32 v17, v17, v95
	v_min_f32_e32 v95, v20, v33
	v_min_f32_e32 v103, v14, v102
	v_max_f32_e32 v14, v14, v102
	v_min_f32_e32 v102, v15, v101
	v_max_f32_e32 v15, v15, v101
	v_min_f32_e32 v101, v16, v99
	v_max_f32_e32 v16, v16, v99
	v_min_f32_e32 v99, v17, v95
	v_max_f32_e32 v17, v17, v95
	v_add_f32_e32 v95, v91, v9
	v_max_f32_e32 v13, v105, v13
	v_and_or_b32 v95, v95, s18, 20
	v_min_f32_e32 v104, v13, v103
	v_max_f32_e32 v13, v13, v103
	v_min_f32_e32 v103, v14, v102
	v_min_f32_e32 v105, v106, v104
	v_max_f32_e32 v104, v106, v104
	v_min_f32_e32 v106, v13, v103
	v_max_f32_e32 v14, v14, v102
	v_min_f32_e32 v102, v15, v101
	v_max_f32_e32 v15, v15, v101
	v_min_f32_e32 v101, v16, v99
	v_max_f32_e32 v16, v16, v99
	v_min_f32_e32 v99, v17, v95
	v_add_f32_e32 v12, v91, v12
	v_min_f32_e32 v107, v104, v106
	v_max_f32_e32 v13, v13, v103
	v_min_f32_e32 v103, v14, v102
	v_max_f32_e32 v14, v14, v102
	v_min_f32_e32 v102, v15, v101
	v_max_f32_e32 v15, v15, v101
	v_min_f32_e32 v101, v16, v99
	v_and_or_b32 v12, v12, s18, 21
	v_max_f32_e32 v21, v23, v21
	v_add_f32_e32 v23, v87, v2
	v_max3_f32 v100, v100, v105, v107
	v_max_f32_e32 v104, v104, v106
	v_min_f32_e32 v105, v13, v103
	v_max_f32_e32 v13, v13, v103
	v_min_f32_e32 v103, v14, v102
	v_max_f32_e32 v14, v14, v102
	v_min_f32_e32 v102, v15, v101
	v_max_f32_e32 v15, v15, v101
	v_and_or_b32 v23, v23, s18, 32
	v_min_f32_e32 v106, v104, v105
	v_max_f32_e32 v104, v104, v105
	v_min_f32_e32 v105, v13, v103
	v_max_f32_e32 v13, v13, v103
	v_min_f32_e32 v103, v14, v102
	v_max_f32_e32 v14, v14, v102
	v_min_f32_e32 v101, v15, v12
	v_add_f32_e32 v11, v91, v11
	v_min_f32_e32 v107, v104, v105
	v_max_f32_e32 v104, v104, v105
	v_min_f32_e32 v105, v13, v103
	v_max_f32_e32 v13, v13, v103
	v_min_f32_e32 v102, v14, v101
	v_and_or_b32 v11, v11, s18, 22
	v_max_f32_e32 v22, v22, v25
	v_min_f32_e32 v25, v21, v23
	v_min_f32_e32 v103, v13, v102
	v_max_f32_e32 v13, v13, v102
	v_max_f32_e32 v24, v24, v27
	v_min_f32_e32 v27, v22, v25
	v_min_f32_e32 v102, v13, v11
	v_max_f32_e32 v11, v13, v11
	v_max_f32_e32 v13, v14, v101
	v_max_f32_e32 v14, v16, v99
	v_max_f32_e32 v16, v20, v33
	v_max_f32_e32 v20, v28, v31
	v_max_f32_e32 v26, v26, v29
	v_min_f32_e32 v28, v24, v27
	v_min_f32_e32 v29, v26, v28
	v_max_f32_e32 v26, v26, v28
	v_add_f32_e32 v28, v87, v4
	v_and_or_b32 v28, v28, s18, 33
	v_max_f32_e32 v12, v15, v12
	v_max_f32_e32 v15, v17, v95
	v_max_f32_e32 v17, v30, v32
	v_min_f32_e32 v30, v20, v29
	v_max_f32_e32 v20, v20, v29
	v_min_f32_e32 v29, v26, v28
	v_min_f32_e32 v31, v17, v30
	v_max_f32_e32 v17, v17, v30
	v_min_f32_e32 v30, v20, v29
	v_min_f32_e32 v32, v16, v31
	v_max_f32_e32 v16, v16, v31
	v_min_f32_e32 v31, v17, v30
	v_min_f32_e32 v33, v15, v32
	v_max_f32_e32 v15, v15, v32
	v_min_f32_e32 v32, v16, v31
	v_max_f32_e32 v16, v16, v31
	v_add_f32_e32 v31, v87, v7
	v_and_or_b32 v31, v31, s18, 34
	v_max3_f32 v100, v100, v106, v107
	v_min_f32_e32 v106, v104, v105
	v_max_f32_e32 v104, v104, v105
	v_min_f32_e32 v105, v104, v103
	v_max_f32_e32 v103, v104, v103
	v_add_f32_e32 v10, v91, v10
	v_min_f32_e32 v95, v14, v33
	v_max_f32_e32 v14, v14, v33
	v_min_f32_e32 v33, v15, v32
	v_max_f32_e32 v15, v15, v32
	v_min_f32_e32 v32, v16, v31
	v_max_f32_e32 v22, v22, v25
	v_add_f32_e32 v25, v83, v2
	v_max3_f32 v100, v100, v106, v105
	v_min_f32_e32 v104, v103, v102
	v_and_or_b32 v10, v10, s18, 23
	v_min_f32_e32 v99, v12, v95
	v_max_f32_e32 v12, v12, v95
	v_min_f32_e32 v95, v14, v33
	v_max_f32_e32 v14, v14, v33
	v_min_f32_e32 v33, v15, v32
	v_and_or_b32 v25, v25, s18, 48
	v_max3_f32 v10, v100, v104, v10
	v_min_f32_e32 v100, v13, v99
	v_max_f32_e32 v13, v13, v99
	v_min_f32_e32 v99, v12, v95
	v_max_f32_e32 v12, v12, v95
	v_min_f32_e32 v95, v14, v33
	v_min_f32_e32 v101, v11, v100
	v_max_f32_e32 v11, v11, v100
	v_min_f32_e32 v100, v13, v99
	v_max_f32_e32 v13, v13, v99
	v_min_f32_e32 v99, v12, v95
	v_max_f32_e32 v12, v12, v95
	v_add_f32_e32 v95, v87, v8
	v_max_f32_e32 v24, v24, v27
	v_min_f32_e32 v27, v22, v25
	v_and_or_b32 v95, v95, s18, 35
	v_max_f32_e32 v26, v26, v28
	v_min_f32_e32 v28, v24, v27
	v_max_f32_e32 v91, v103, v102
	v_max_f32_e32 v20, v20, v29
; DEV void ce(float& a, float& b) { float hi = fmaxf(a, b), lo = fminf(a, b); a = hi; b = lo; }
; DEV void phase_peer_score(const Params& p, int layer, int M, char* smem) {
;     ...
; #pragma unroll
;     for (int i = 0; i < 16; i++) R[i] = -3.0e38f;
; #pragma unroll
;     for (int i = 0; i < 16; i++)
; #pragma unroll
;       for (int j = 0; j < 16; j++)
;         if ((i + 1) * (j + 1) <= 16) {
;           float v = L0[i] + L1[j];
;           v = __uint_as_float((__float_as_uint(v) & ~255u) | (unsigned)(i * 16 + j));
; #pragma unroll
;           for (int t = 0; t < 16; t++)
;             if (t >= (i + 1) * (j + 1) - 1) ce(R[t], v);
;         }
	v_min_f32_e32 v29, v26, v28
	v_min_f32_e32 v102, v91, v101
	v_max_f32_e32 v91, v91, v101
	v_min_f32_e32 v101, v11, v100
	v_max_f32_e32 v11, v11, v100
	v_min_f32_e32 v100, v13, v99
	v_max_f32_e32 v13, v13, v99
	v_min_f32_e32 v99, v12, v95
	v_max_f32_e32 v17, v17, v30
	v_min_f32_e32 v30, v20, v29
	v_min_f32_e32 v103, v91, v101
	v_max_f32_e32 v91, v91, v101
	v_min_f32_e32 v101, v11, v100
	v_max_f32_e32 v11, v11, v100
	v_min_f32_e32 v100, v13, v99
	v_add_f32_e32 v9, v87, v9
	v_max_f32_e32 v16, v16, v31
	v_min_f32_e32 v31, v17, v30
	v_max3_f32 v10, v10, v102, v103
	v_min_f32_e32 v102, v91, v101
	v_max_f32_e32 v91, v91, v101
	v_min_f32_e32 v101, v11, v100
	v_and_or_b32 v9, v9, s18, 36
	v_max_f32_e32 v15, v15, v32
	v_min_f32_e32 v32, v16, v31
	v_min_f32_e32 v103, v91, v101
	v_max_f32_e32 v91, v91, v101
	v_max_f32_e32 v14, v14, v33
	v_min_f32_e32 v33, v15, v32
	v_max_f32_e32 v17, v17, v30
	v_add_f32_e32 v30, v83, v4
	v_min_f32_e32 v87, v91, v9
	v_max_f32_e32 v9, v91, v9
	v_max_f32_e32 v12, v12, v95
	v_min_f32_e32 v91, v14, v33
	v_and_or_b32 v30, v30, s18, 49
	v_max_f32_e32 v24, v24, v27
	v_add_f32_e32 v27, v79, v2
	v_max_f32_e32 v13, v13, v99
	v_min_f32_e32 v95, v12, v91
	v_and_or_b32 v27, v27, s18, 64
	v_max_f32_e32 v11, v11, v100
	v_min_f32_e32 v99, v13, v95
	v_max_f32_e32 v16, v16, v31
	v_min_f32_e32 v31, v17, v30
	v_min_f32_e32 v100, v11, v99
	v_max_f32_e32 v15, v15, v32
	v_min_f32_e32 v32, v16, v31
	v_max_f32_e32 v26, v26, v28
	v_min_f32_e32 v28, v24, v27
	v_max3_f32 v10, v10, v102, v103
	v_min_f32_e32 v101, v9, v100
	v_max_f32_e32 v14, v14, v33
	v_min_f32_e32 v33, v15, v32
	v_max_f32_e32 v20, v20, v29
	v_min_f32_e32 v29, v26, v28
	v_max3_f32 v10, v10, v87, v101
	v_max_f32_e32 v12, v12, v91
	v_min_f32_e32 v87, v14, v33
	v_max_f32_e32 v17, v17, v30
	v_min_f32_e32 v30, v20, v29
	v_min_f32_e32 v91, v12, v87
	v_max_f32_e32 v12, v12, v87
	v_add_f32_e32 v87, v83, v7
	v_max_f32_e32 v16, v16, v31
	v_min_f32_e32 v31, v17, v30
	v_and_or_b32 v87, v87, s18, 50
	v_max_f32_e32 v15, v15, v32
	v_min_f32_e32 v32, v16, v31
	v_max_f32_e32 v13, v13, v95
	v_max_f32_e32 v14, v14, v33
	v_min_f32_e32 v33, v15, v32
	v_max_f32_e32 v11, v11, v99
	v_min_f32_e32 v95, v13, v91
	v_max_f32_e32 v13, v13, v91
	v_min_f32_e32 v91, v12, v87
	v_add_f32_e32 v8, v83, v8
	v_max_f32_e32 v12, v12, v87
	v_min_f32_e32 v83, v14, v33
	v_max_f32_e32 v9, v9, v100
	v_min_f32_e32 v99, v11, v95
	v_max_f32_e32 v11, v11, v95
	v_min_f32_e32 v95, v13, v91
	v_max_f32_e32 v13, v13, v91
	v_min_f32_e32 v87, v12, v83
	v_min_f32_e32 v100, v9, v99
	v_max_f32_e32 v9, v9, v99
	v_min_f32_e32 v99, v11, v95
	v_max_f32_e32 v11, v11, v95
	v_min_f32_e32 v91, v13, v87
	v_min_f32_e32 v101, v9, v99
	v_max_f32_e32 v9, v9, v99
	v_min_f32_e32 v95, v11, v91
	v_max3_f32 v10, v10, v100, v101
	v_and_or_b32 v8, v8, s18, 51
	v_min_f32_e32 v99, v9, v95
	v_max3_f32 v8, v10, v8, v99
	v_max_f32_e32 v10, v11, v91
	v_max_f32_e32 v11, v13, v87
	v_max_f32_e32 v13, v14, v33
	v_max_f32_e32 v14, v15, v32
	v_add_f32_e32 v15, v79, v4
	v_and_b32_e32 v15, 0xffffff00, v15
	v_or_b32_e32 v15, 0x41, v15
	v_min_f32_e32 v32, v14, v15
	v_max_f32_e32 v12, v12, v83
	v_min_f32_e32 v33, v13, v32
	v_min_f32_e32 v83, v12, v33
	v_add_f32_e32 v7, v79, v7
	v_min_f32_e32 v87, v11, v83
	v_and_b32_e32 v7, 0xffffff00, v7
	v_max_f32_e32 v9, v9, v95
	v_min_f32_e32 v91, v10, v87
	v_or_b32_e32 v7, 0x42, v7
	v_min_f32_e32 v95, v9, v91
	v_max_f32_e32 v9, v9, v91
	v_min_f32_e32 v79, v9, v7
	v_max_f32_e32 v7, v9, v7
	v_max_f32_e32 v9, v10, v87
	v_max_f32_e32 v10, v11, v83
	v_max_f32_e32 v11, v12, v33
	v_max_f32_e32 v12, v13, v32
	v_max_f32_e32 v13, v14, v15
	v_max_f32_e32 v14, v16, v31
	v_max_f32_e32 v16, v20, v29
	v_add_f32_e32 v20, v75, v2
	v_and_b32_e32 v20, 0xffffff00, v20
	v_or_b32_e32 v20, 0x50, v20
	v_max_f32_e32 v15, v17, v30
	v_max_f32_e32 v17, v26, v28
	v_min_f32_e32 v26, v17, v20
	v_min_f32_e32 v28, v16, v26
	v_max_f32_e32 v16, v16, v26
	v_add_f32_e32 v26, v71, v2
	v_and_b32_e32 v26, 0xffffff00, v26
	v_min_f32_e32 v29, v15, v28
	v_or_b32_e32 v26, 0x60, v26
	v_min_f32_e32 v30, v14, v29
	v_min_f32_e32 v31, v13, v30
	v_max_f32_e32 v15, v15, v28
	v_min_f32_e32 v28, v16, v26
	v_min_f32_e32 v32, v12, v31
	v_max_f32_e32 v14, v14, v29
	v_min_f32_e32 v29, v15, v28
	v_max_f32_e32 v15, v15, v28
	v_add_f32_e32 v28, v63, v2
	v_min_f32_e32 v33, v11, v32
	v_max_f32_e32 v11, v11, v32
	v_add_f32_e32 v32, v75, v4
	v_and_b32_e32 v28, 0xffffff00, v28
	v_and_b32_e32 v32, 0xffffff00, v32
	v_or_b32_e32 v28, 0x70, v28
	v_or_b32_e32 v32, 0x51, v32
	v_max_f32_e32 v13, v13, v30
	v_min_f32_e32 v30, v14, v29
	v_max_f32_e32 v12, v12, v31
	v_min_f32_e32 v31, v13, v30
	v_max_f32_e32 v14, v14, v29
	v_min_f32_e32 v29, v15, v28
	v_max3_f32 v8, v8, v95, v79
	v_min_f32_e32 v79, v10, v33
	v_max_f32_e32 v10, v10, v33
	v_min_f32_e32 v33, v11, v32
	v_max_f32_e32 v11, v11, v32
	v_min_f32_e32 v32, v12, v31
	v_add_f32_e32 v71, v71, v4
	v_max_f32_e32 v13, v13, v30
	v_min_f32_e32 v30, v14, v29
	v_min_f32_e32 v83, v9, v79
	v_max_f32_e32 v9, v9, v79
	v_min_f32_e32 v75, v10, v33
	v_max_f32_e32 v10, v10, v33
	v_min_f32_e32 v33, v11, v32
	v_and_b32_e32 v71, 0xffffff00, v71
	v_max_f32_e32 v12, v12, v31
	v_min_f32_e32 v31, v13, v30
	v_min_f32_e32 v87, v7, v83
	v_max_f32_e32 v7, v7, v83
	v_min_f32_e32 v79, v9, v75
	v_max_f32_e32 v9, v9, v75
	v_min_f32_e32 v75, v10, v33
	v_or_b32_e32 v71, 0x61, v71
	v_max_f32_e32 v11, v11, v32
	v_min_f32_e32 v32, v12, v31
	v_min_f32_e32 v83, v7, v79
	v_max_f32_e32 v7, v7, v79
	v_min_f32_e32 v79, v9, v75
	v_max_f32_e32 v9, v9, v75
	v_max_f32_e32 v10, v10, v33
	v_min_f32_e32 v33, v11, v32
	v_max3_f32 v8, v8, v87, v83
	v_min_f32_e32 v83, v7, v79
	v_max_f32_e32 v7, v7, v79
; DEV void ce(float& a, float& b) { float hi = fmaxf(a, b), lo = fminf(a, b); a = hi; b = lo; }
; DEV void phase_peer_score(const Params& p, int layer, int M, char* smem) {
;     ...
;           float v = L0[i] + L1[j];
;           v = __uint_as_float((__float_as_uint(v) & ~255u) | (unsigned)(i * 16 + j));
; #pragma unroll
;           for (int t = 0; t < 16; t++)
;             if (t >= (i + 1) * (j + 1) - 1) ce(R[t], v);
;         }
;     unsigned char* tab = (unsigned char*)smem + 73728 + (w * 16 + l15) * 32;
; #pragma unroll
;     for (int i = 0; i < 16; i++) { tab[i] = (unsigned char)(__float_as_uint(L0[i]) & 127u); tab[16 + i] = (unsigned char)(__float_as_uint(L1[i]) & 127u); }
;     float ev[16]; float sum = 0.f;
; #pragma unroll
;     for (int t = 0; t < 16; t++) { ev[t] = __expf(R[t] - R[0]); sum += ev[t]; }
;     const float inv = 1.f / sum;
;     int eid[16];
; #pragma unroll
;     for (int t = 0; t < 16; t++) {
;       unsigned code = __float_as_uint(R[t]) & 255u;
;       eid[t] = (int)tab[code >> 4] * 128 + (int)tab[16 + (code & 15u)];
	v_min_f32_e32 v75, v9, v71
	v_max_f32_e32 v9, v9, v71
	v_min_f32_e32 v71, v10, v33
	v_add_f32_e32 v4, v63, v4
	v_min_f32_e32 v79, v7, v75
	v_max_f32_e32 v7, v7, v75
	v_min_f32_e32 v75, v9, v71
	v_and_b32_e32 v4, 0xffffff00, v4
	v_max3_f32 v8, v8, v83, v79
	v_min_f32_e32 v79, v7, v75
	v_or_b32_e32 v4, 0x71, v4
	v_max3_f32 v4, v8, v79, v4
	v_max_f32_e32 v8, v9, v71
	v_max_f32_e32 v9, v10, v33
	v_max_f32_e32 v10, v11, v32
	v_max_f32_e32 v11, v12, v31
	v_max_f32_e32 v12, v13, v30
	v_max_f32_e32 v13, v14, v29
	v_add_f32_e32 v14, v67, v2
	v_and_b32_e32 v14, 0xffffff00, v14
	v_or_b32_e32 v14, 0x80, v14
	v_min_f32_e32 v29, v13, v14
	v_min_f32_e32 v30, v12, v29
	v_max_f32_e32 v12, v12, v29
	v_add_f32_e32 v29, v59, v2
	v_and_b32_e32 v29, 0xffffff00, v29
	v_or_b32_e32 v29, 0x90, v29
	v_min_f32_e32 v31, v11, v30
	v_max_f32_e32 v11, v11, v30
	v_min_f32_e32 v30, v12, v29
	v_min_f32_e32 v32, v10, v31
	v_max_f32_e32 v10, v10, v31
	v_min_f32_e32 v31, v11, v30
	v_max_f32_e32 v11, v11, v30
	v_add_f32_e32 v30, v55, v2
	v_and_b32_e32 v30, 0xffffff00, v30
	v_or_b32_e32 v30, 0xa0, v30
	v_min_f32_e32 v33, v9, v32
	v_max_f32_e32 v9, v9, v32
	v_min_f32_e32 v32, v10, v31
	v_max_f32_e32 v10, v10, v31
	v_min_f32_e32 v31, v11, v30
	v_min_f32_e32 v63, v8, v33
	v_max_f32_e32 v8, v8, v33
	v_min_f32_e32 v33, v9, v32
	v_max_f32_e32 v9, v9, v32
	v_min_f32_e32 v32, v10, v31
	v_max_f32_e32 v10, v10, v31
	v_add_f32_e32 v31, v47, v2
	v_and_b32_e32 v31, 0xffffff00, v31
	v_or_b32_e32 v31, 0xb0, v31
	v_min_f32_e32 v59, v8, v33
	v_max_f32_e32 v8, v8, v33
	v_min_f32_e32 v33, v9, v32
	v_max_f32_e32 v9, v9, v32
	v_min_f32_e32 v32, v10, v31
	v_min_f32_e32 v55, v8, v33
	v_max_f32_e32 v8, v8, v33
	v_min_f32_e32 v33, v9, v32
	v_max_f32_e32 v9, v9, v32
	v_add_f32_e32 v32, v51, v2
	v_max_f32_e32 v7, v7, v75
	v_and_b32_e32 v32, 0xffffff00, v32
	v_min_f32_e32 v67, v7, v63
	v_max_f32_e32 v7, v7, v63
	v_or_b32_e32 v32, 0xc0, v32
	v_min_f32_e32 v63, v7, v59
	v_max_f32_e32 v7, v7, v59
	v_min_f32_e32 v59, v7, v55
	v_max_f32_e32 v7, v7, v55
	v_min_f32_e32 v47, v8, v33
	v_max_f32_e32 v8, v8, v33
	v_min_f32_e32 v33, v9, v32
	v_min_f32_e32 v55, v7, v47
	v_max_f32_e32 v7, v7, v47
	v_min_f32_e32 v47, v8, v33
	v_max_f32_e32 v8, v8, v33
	v_add_f32_e32 v33, v39, v2
	v_and_b32_e32 v33, 0xffffff00, v33
	v_or_b32_e32 v33, 0xd0, v33
	v_min_f32_e32 v51, v7, v47
	v_max_f32_e32 v7, v7, v47
	v_min_f32_e32 v39, v8, v33
	v_min_f32_e32 v47, v7, v39
	v_max_f32_e32 v7, v7, v39
	v_add_f32_e32 v39, v43, v2
	v_and_b32_e32 v39, 0xffffff00, v39
	v_max3_f32 v4, v4, v67, v63
	v_or_b32_e32 v39, 0xe0, v39
	v_add_f32_e32 v0, v0, v2
	v_max3_f32 v4, v4, v59, v55
	v_and_b32_e32 v0, 0xffffff00, v0
	v_max3_f32 v4, v4, v51, v47
	v_min_f32_e32 v43, v7, v39
	v_or_b32_e32 v0, 0xf0, v0
	v_max3_f32 v2, v4, v43, v0
	v_max_f32_e32 v13, v13, v14
	v_max_f32_e32 v14, v5, v6
	v_max_f32_e32 v0, 0xff61b1e6, v3
	v_sub_f32_e32 v5, v14, v0
	v_max_f32_e32 v28, v15, v28
	v_max_f32_e32 v15, v21, v23
	v_mul_f32_e32 v5, 0x3fb8aa3b, v5
	v_exp_f32_e32 v101, v5
	v_sub_f32_e32 v5, v15, v0
	v_max_f32_e32 v29, v12, v29
	v_max_f32_e32 v12, v16, v26
	v_max_f32_e32 v16, v22, v25
	v_mul_f32_e32 v5, 0x3fb8aa3b, v5
	v_exp_f32_e32 v104, v5
	v_sub_f32_e32 v5, v16, v0
	v_max_f32_e32 v4, v7, v39
	v_max_f32_e32 v7, v8, v33
	v_max_f32_e32 v8, v9, v32
	v_max_f32_e32 v9, v10, v31
	v_max_f32_e32 v10, v24, v27
	v_mul_f32_e32 v5, 0x3fb8aa3b, v5
	v_exp_f32_e32 v105, v5
	v_sub_f32_e32 v5, v10, v0
	v_max_f32_e32 v30, v11, v30
	v_max_f32_e32 v11, v17, v20
	v_mul_f32_e32 v5, 0x3fb8aa3b, v5
	v_exp_f32_e32 v102, v5
	v_sub_f32_e32 v5, v11, v0
	v_mul_f32_e32 v5, 0x3fb8aa3b, v5
	v_exp_f32_e32 v103, v5
	v_sub_f32_e32 v5, v12, v0
	v_mul_f32_e32 v5, 0x3fb8aa3b, v5
	v_exp_f32_e32 v110, v5
	v_sub_f32_e32 v5, v28, v0
	v_sub_f32_e32 v3, v0, v0
	v_mul_f32_e32 v5, 0x3fb8aa3b, v5
	v_mul_f32_e32 v3, 0x3fb8aa3b, v3
	v_exp_f32_e32 v111, v5
	v_sub_f32_e32 v5, v13, v0
	v_exp_f32_e32 v100, v3
	v_mul_f32_e32 v5, 0x3fb8aa3b, v5
	v_exp_f32_e32 v112, v5
	v_sub_f32_e32 v5, v29, v0
	v_mul_f32_e32 v5, 0x3fb8aa3b, v5
	v_exp_f32_e32 v113, v5
	v_sub_f32_e32 v5, v30, v0
	v_add_f32_e32 v3, 0, v100
	v_mul_f32_e32 v5, 0x3fb8aa3b, v5
	v_add_f32_e32 v3, v3, v101
	v_exp_f32_e32 v114, v5
	v_sub_f32_e32 v5, v9, v0
	v_add_f32_e32 v3, v3, v104
	v_mul_f32_e32 v5, 0x3fb8aa3b, v5
	v_add_f32_e32 v3, v3, v105
	v_exp_f32_e32 v115, v5
	v_sub_f32_e32 v5, v8, v0
	v_add_f32_e32 v3, v3, v102
	v_mul_f32_e32 v5, 0x3fb8aa3b, v5
	v_add_f32_e32 v3, v3, v103
	v_exp_f32_e32 v106, v5
	v_sub_f32_e32 v5, v7, v0
	v_add_f32_e32 v3, v3, v110
	v_mul_f32_e32 v5, 0x3fb8aa3b, v5
	v_add_f32_e32 v3, v3, v111
	v_exp_f32_e32 v107, v5
	v_sub_f32_e32 v5, v4, v0
	v_add_f32_e32 v3, v3, v112
	v_mul_f32_e32 v5, 0x3fb8aa3b, v5
	v_add_f32_e32 v3, v3, v113
	v_exp_f32_e32 v108, v5
	v_sub_f32_e32 v5, v2, v0
	v_add_f32_e32 v3, v3, v114
	v_mul_f32_e32 v5, 0x3fb8aa3b, v5
	v_add_f32_e32 v3, v3, v115
	v_exp_f32_e32 v109, v5
	v_add_f32_e32 v3, v3, v106
	v_add_f32_e32 v3, v3, v107
	v_add_f32_e32 v3, v3, v108
	v_add_f32_e32 v3, v3, v109
	v_div_scale_f32 v5, s[18:19], v3, v3, 1.0
	v_rcp_f32_e32 v6, v5
	v_ashrrev_i32_e32 v19, 31, v18
	s_lshl_b32 s52, s17, 6
	s_mov_b32 s17, 0x10000
	v_fma_f32 v17, -v5, v6, 1.0
	v_fmac_f32_e32 v6, v17, v6
	v_div_scale_f32 v17, vcc, 1.0, v3, 1.0
	v_mul_f32_e32 v20, v17, v6
	v_fma_f32 v21, -v5, v20, v17
	v_fmac_f32_e32 v20, v21, v6
	v_fma_f32 v5, -v5, v20, v17
	v_div_fmas_f32 v5, v5, v6, v20
	v_div_fixup_f32 v116, v5, v3, 1.0
	v_bfe_u32 v3, v2, 4, 4
	v_and_b32_e32 v2, 15, v2
	v_and_b32_e32 v17, 15, v28
	v_add_u32_e32 v3, v138, v3
	v_add_u32_e32 v2, v138, v2
	v_add_u32_e32 v17, v138, v17
	ds_read_u8 v3, v3
	ds_read_u8 v17, v17 offset:16
	ds_read_u8 v2, v2 offset:16
	v_and_b32_e32 v6, 15, v8
	v_add_u32_e32 v6, v138, v6
	ds_read_u8 v6, v6 offset:16
	v_lshlrev_b64 v[120:121], 9, v[18:19]
	s_waitcnt lgkmcnt(1)
; DEV void phase_peer_score(const Params& p, int layer, int M, char* smem) {
;     ...
;     int eid[16];
; #pragma unroll
;     for (int t = 0; t < 16; t++) {
;       unsigned code = __float_as_uint(R[t]) & 255u;
;       eid[t] = (int)tab[code >> 4] * 128 + (int)tab[16 + (code & 15u)];
;     }
;     if (quad == 0) {
;       int* eo = EIDX + (size_t)m * 128 + h * 16;
;       float* go = GATE + (size_t)m * 128 + h * 16;
;       float* uo = go + (size_t)MT * 128;
	v_lshl_add_u32 v5, v3, 7, v2
	v_bfe_u32 v2, v4, 4, 4
	v_and_b32_e32 v3, 15, v4
	v_add_u32_e32 v2, v138, v2
	v_add_u32_e32 v3, v138, v3
	ds_read_u8 v2, v2
	ds_read_u8 v3, v3 offset:16
	v_lshl_add_u64 v[18:19], s[2:3], 0, v[120:121]
	v_lshl_add_u64 v[118:119], v[18:19], 0, s[52:53]
	v_lshl_add_u64 v[120:121], s[0:1], 0, v[120:121]
	v_lshl_add_u64 v[120:121], v[120:121], 0, s[52:53]
	s_waitcnt lgkmcnt(0)
	v_lshl_add_u32 v4, v2, 7, v3
	v_bfe_u32 v2, v7, 4, 4
	v_and_b32_e32 v3, 15, v7
	v_add_u32_e32 v2, v138, v2
	v_add_u32_e32 v3, v138, v3
	ds_read_u8 v2, v2
	ds_read_u8 v3, v3 offset:16
	v_and_b32_e32 v7, 15, v9
	v_add_u32_e32 v7, v138, v7
	ds_read_u8 v7, v7 offset:16
	s_waitcnt lgkmcnt(1)
	v_lshl_add_u32 v3, v2, 7, v3
	v_bfe_u32 v2, v8, 4, 4
	v_add_u32_e32 v2, v138, v2
	ds_read_u8 v2, v2
	s_waitcnt lgkmcnt(0)
	v_lshl_add_u32 v2, v2, 7, v6
	v_bfe_u32 v6, v9, 4, 4
	v_add_u32_e32 v6, v138, v6
	ds_read_u8 v6, v6
	s_waitcnt lgkmcnt(0)
	v_lshl_add_u32 v9, v6, 7, v7
	v_bfe_u32 v6, v30, 4, 4
	v_and_b32_e32 v7, 15, v30
	v_add_u32_e32 v6, v138, v6
	v_add_u32_e32 v7, v138, v7
	ds_read_u8 v6, v6
	ds_read_u8 v7, v7 offset:16
	s_waitcnt lgkmcnt(0)
	v_lshl_add_u32 v8, v6, 7, v7
	v_bfe_u32 v6, v29, 4, 4
	v_and_b32_e32 v7, 15, v29
	v_add_u32_e32 v6, v138, v6
	v_add_u32_e32 v7, v138, v7
	ds_read_u8 v6, v6
	ds_read_u8 v7, v7 offset:16
	s_waitcnt lgkmcnt(0)
	v_lshl_add_u32 v7, v6, 7, v7
	v_bfe_u32 v6, v13, 4, 4
	v_and_b32_e32 v13, 15, v13
	v_add_u32_e32 v6, v138, v6
	v_add_u32_e32 v13, v138, v13
	ds_read_u8 v6, v6
	ds_read_u8 v13, v13 offset:16
	s_waitcnt lgkmcnt(0)
	v_lshl_add_u32 v6, v6, 7, v13
	v_bfe_u32 v13, v28, 4, 4
	v_add_u32_e32 v13, v138, v13
	ds_read_u8 v13, v13
	s_waitcnt lgkmcnt(0)
	v_lshl_add_u32 v13, v13, 7, v17
	v_bfe_u32 v17, v12, 4, 4
	v_and_b32_e32 v12, 15, v12
	v_add_u32_e32 v17, v138, v17
	v_add_u32_e32 v12, v138, v12
	ds_read_u8 v17, v17
	ds_read_u8 v12, v12 offset:16
	s_waitcnt lgkmcnt(0)
	v_lshl_add_u32 v12, v17, 7, v12
	v_bfe_u32 v17, v11, 4, 4
	v_and_b32_e32 v11, 15, v11
	v_add_u32_e32 v17, v138, v17
	v_add_u32_e32 v11, v138, v11
	ds_read_u8 v17, v17
	ds_read_u8 v11, v11 offset:16
	s_waitcnt lgkmcnt(0)
	v_lshl_add_u32 v11, v17, 7, v11
	v_bfe_u32 v17, v10, 4, 4
	v_and_b32_e32 v10, 15, v10
	v_add_u32_e32 v17, v138, v17
	v_add_u32_e32 v10, v138, v10
	ds_read_u8 v17, v17
	ds_read_u8 v10, v10 offset:16
	s_waitcnt lgkmcnt(0)
	v_lshl_add_u32 v10, v17, 7, v10
	v_bfe_u32 v17, v16, 4, 4
	v_and_b32_e32 v16, 15, v16
	v_add_u32_e32 v17, v138, v17
	v_add_u32_e32 v16, v138, v16
	ds_read_u8 v17, v17
	ds_read_u8 v16, v16 offset:16
	s_waitcnt lgkmcnt(0)
	v_lshl_add_u32 v17, v17, 7, v16
	v_bfe_u32 v16, v15, 4, 4
	v_and_b32_e32 v15, 15, v15
	v_add_u32_e32 v16, v138, v16
	v_add_u32_e32 v15, v138, v15
	ds_read_u8 v16, v16
	ds_read_u8 v15, v15 offset:16
	s_waitcnt lgkmcnt(0)
	v_lshl_add_u32 v16, v16, 7, v15
	v_bfe_u32 v15, v14, 4, 4
	v_and_b32_e32 v14, 15, v14
	v_add_u32_e32 v15, v138, v15
	v_add_u32_e32 v14, v138, v14
	ds_read_u8 v15, v15
	ds_read_u8 v14, v14 offset:16
	s_waitcnt lgkmcnt(0)
	v_lshl_add_u32 v15, v15, 7, v14
	v_bfe_u32 v14, v0, 4, 4
	v_and_b32_e32 v0, 15, v0
	v_add_u32_e32 v14, v138, v14
	v_add_u32_e32 v0, v138, v0
	ds_read_u8 v14, v14
	ds_read_u8 v0, v0 offset:16
	s_waitcnt lgkmcnt(0)
; DEV void phase_peer_score(const Params& p, int layer, int M, char* smem) {
;     ...
;     if (quad == 0) {
;       int* eo = EIDX + (size_t)m * 128 + h * 16;
;       float* go = GATE + (size_t)m * 128 + h * 16;
;       float* uo = go + (size_t)MT * 128;
;       float us[16], vs[16];
; #pragma unroll
;       for (int t = 0; t < 16; t++) { us[t] = USC[eid[t]]; vs[t] = USC[16384 + eid[t]]; }
; #pragma unroll
;       for (int t = 0; t < 16; t += 4) {
;         *(int4*)(eo + t) = make_int4(eid[t], eid[t + 1], eid[t + 2], eid[t + 3]);
;         *(float4*)(go + t) = make_float4(ev[t] * inv * vs[t], ev[t + 1] * inv * vs[t + 1], ev[t + 2] * inv * vs[t + 2], ev[t + 3] * inv * vs[t + 3]);
;         *(float4*)(uo + t) = make_float4(us[t], us[t + 1], us[t + 2], us[t + 3]);
;       }
;     }
	v_lshl_add_u32 v14, v14, 7, v0
	v_lshlrev_b32_e32 v0, 2, v14
	v_lshl_add_u64 v[20:21], s[6:7], 0, v[0:1]
	v_add_co_u32_e32 v20, vcc, s17, v20
	global_load_dword v18, v0, s[6:7]
	s_nop 0
	v_addc_co_u32_e32 v21, vcc, 0, v21, vcc
	global_load_dword v122, v[20:21], off
	v_lshlrev_b32_e32 v0, 2, v15
	v_lshl_add_u64 v[20:21], s[6:7], 0, v[0:1]
	v_add_co_u32_e32 v20, vcc, s17, v20
	global_load_dword v19, v0, s[6:7]
	s_nop 0
	v_addc_co_u32_e32 v21, vcc, 0, v21, vcc
	global_load_dword v123, v[20:21], off
	v_lshlrev_b32_e32 v0, 2, v16
	v_lshl_add_u64 v[22:23], s[6:7], 0, v[0:1]
	v_add_co_u32_e32 v22, vcc, s17, v22
	global_load_dword v20, v0, s[6:7]
	s_nop 0
	v_addc_co_u32_e32 v23, vcc, 0, v23, vcc
	global_load_dword v126, v[22:23], off
	v_lshlrev_b32_e32 v0, 2, v17
	v_lshl_add_u64 v[22:23], s[6:7], 0, v[0:1]
	v_add_co_u32_e32 v22, vcc, s17, v22
	global_load_dword v21, v0, s[6:7]
	s_nop 0
	v_addc_co_u32_e32 v23, vcc, 0, v23, vcc
	global_load_dword v127, v[22:23], off
	v_lshlrev_b32_e32 v0, 2, v10
	v_lshl_add_u64 v[24:25], s[6:7], 0, v[0:1]
	v_add_co_u32_e32 v24, vcc, s17, v24
	global_load_dword v22, v0, s[6:7]
	s_nop 0
	v_addc_co_u32_e32 v25, vcc, 0, v25, vcc
	global_load_dword v124, v[24:25], off
	v_lshlrev_b32_e32 v0, 2, v11
	v_lshl_add_u64 v[24:25], s[6:7], 0, v[0:1]
	v_add_co_u32_e32 v24, vcc, s17, v24
	global_load_dword v23, v0, s[6:7]
	s_nop 0
	v_addc_co_u32_e32 v25, vcc, 0, v25, vcc
	global_load_dword v125, v[24:25], off
	v_lshlrev_b32_e32 v0, 2, v12
	v_lshl_add_u64 v[26:27], s[6:7], 0, v[0:1]
	v_add_co_u32_e32 v26, vcc, s17, v26
	global_load_dword v24, v0, s[6:7]
	s_nop 0
	v_addc_co_u32_e32 v27, vcc, 0, v27, vcc
	global_load_dword v128, v[26:27], off
	v_lshlrev_b32_e32 v0, 2, v13
	v_lshl_add_u64 v[26:27], s[6:7], 0, v[0:1]
	v_add_co_u32_e32 v26, vcc, s17, v26
	global_load_dword v25, v0, s[6:7]
	s_nop 0
	v_addc_co_u32_e32 v27, vcc, 0, v27, vcc
	global_load_dword v129, v[26:27], off
	v_lshlrev_b32_e32 v0, 2, v6
	v_lshl_add_u64 v[28:29], s[6:7], 0, v[0:1]
	v_add_co_u32_e32 v28, vcc, s17, v28
	global_load_dword v26, v0, s[6:7]
	s_nop 0
	v_addc_co_u32_e32 v29, vcc, 0, v29, vcc
	global_load_dword v130, v[28:29], off
	v_lshlrev_b32_e32 v0, 2, v7
	v_lshl_add_u64 v[28:29], s[6:7], 0, v[0:1]
	v_add_co_u32_e32 v28, vcc, s17, v28
	global_load_dword v27, v0, s[6:7]
	s_nop 0
	v_addc_co_u32_e32 v29, vcc, 0, v29, vcc
	global_load_dword v131, v[28:29], off
	v_lshlrev_b32_e32 v0, 2, v8
	v_lshl_add_u64 v[30:31], s[6:7], 0, v[0:1]
	v_add_co_u32_e32 v30, vcc, s17, v30
	global_load_dword v28, v0, s[6:7]
	s_nop 0
	v_addc_co_u32_e32 v31, vcc, 0, v31, vcc
	global_load_dword v132, v[30:31], off
	v_lshlrev_b32_e32 v0, 2, v9
	v_lshl_add_u64 v[30:31], s[6:7], 0, v[0:1]
	v_add_co_u32_e32 v30, vcc, s17, v30
	global_load_dword v29, v0, s[6:7]
	s_nop 0
	v_addc_co_u32_e32 v31, vcc, 0, v31, vcc
	global_load_dword v133, v[30:31], off
	v_lshlrev_b32_e32 v0, 2, v2
	v_lshl_add_u64 v[32:33], s[6:7], 0, v[0:1]
	v_add_co_u32_e32 v32, vcc, s17, v32
	global_load_dword v30, v0, s[6:7]
	s_nop 0
	v_addc_co_u32_e32 v33, vcc, 0, v33, vcc
	global_load_dword v134, v[32:33], off
	v_lshlrev_b32_e32 v0, 2, v3
	v_lshl_add_u64 v[32:33], s[6:7], 0, v[0:1]
	v_add_co_u32_e32 v32, vcc, s17, v32
	global_load_dword v31, v0, s[6:7]
	s_nop 0
	v_addc_co_u32_e32 v33, vcc, 0, v33, vcc
	global_load_dword v135, v[32:33], off
	v_lshlrev_b32_e32 v0, 2, v4
	v_lshl_add_u64 v[136:137], s[6:7], 0, v[0:1]
	v_add_co_u32_e32 v136, vcc, s17, v136
	global_load_dword v32, v0, s[6:7]
	s_nop 0
	v_addc_co_u32_e32 v137, vcc, 0, v137, vcc
	global_load_dword v136, v[136:137], off
	v_lshlrev_b32_e32 v0, 2, v5
	v_lshl_add_u64 v[140:141], s[6:7], 0, v[0:1]
	v_add_co_u32_e32 v140, vcc, s17, v140
	global_load_dword v33, v0, s[6:7]
	s_nop 0
	v_addc_co_u32_e32 v141, vcc, 0, v141, vcc
	global_load_dword v137, v[140:141], off
	s_mov_b32 s17, 0x840000
	global_store_dwordx4 v[120:121], v[14:17], off
	s_nop 1
	v_pk_mul_f32 v[14:15], v[100:101], v[116:117] op_sel_hi:[1,0]
	v_pk_mul_f32 v[16:17], v[104:105], v[116:117] op_sel_hi:[1,0]
	s_waitcnt vmcnt(29)
	v_pk_mul_f32 v[14:15], v[14:15], v[122:123]
	s_waitcnt vmcnt(25)
	v_pk_mul_f32 v[16:17], v[16:17], v[126:127]
	global_store_dwordx4 v[118:119], v[14:17], off
	s_nop 1
	v_add_co_u32_e32 v14, vcc, s17, v118
	s_nop 1
	v_addc_co_u32_e32 v15, vcc, 0, v119, vcc
	global_store_dwordx4 v[14:15], v[18:21], off
	global_store_dwordx4 v[120:121], v[10:13], off offset:16
	s_nop 1
	v_pk_mul_f32 v[10:11], v[102:103], v[116:117] op_sel_hi:[1,0]
	v_pk_mul_f32 v[12:13], v[110:111], v[116:117] op_sel_hi:[1,0]
	s_waitcnt vmcnt(24)
	v_pk_mul_f32 v[10:11], v[10:11], v[124:125]
	s_waitcnt vmcnt(20)
	v_pk_mul_f32 v[12:13], v[12:13], v[128:129]
	global_store_dwordx4 v[118:119], v[10:13], off offset:16
	global_store_dwordx4 v[14:15], v[22:25], off offset:16
	global_store_dwordx4 v[120:121], v[6:9], off offset:32
	s_nop 1
	v_pk_mul_f32 v[6:7], v[112:113], v[116:117] op_sel_hi:[1,0]
	v_pk_mul_f32 v[8:9], v[114:115], v[116:117] op_sel_hi:[1,0]
	s_waitcnt vmcnt(19)
	v_pk_mul_f32 v[6:7], v[6:7], v[130:131]
	s_waitcnt vmcnt(15)
	v_pk_mul_f32 v[8:9], v[8:9], v[132:133]
	global_store_dwordx4 v[118:119], v[6:9], off offset:32
	global_store_dwordx4 v[14:15], v[26:29], off offset:32
	global_store_dwordx4 v[120:121], v[2:5], off offset:48
	s_nop 1
	v_pk_mul_f32 v[2:3], v[106:107], v[116:117] op_sel_hi:[1,0]
	v_pk_mul_f32 v[4:5], v[108:109], v[116:117] op_sel_hi:[1,0]
	s_waitcnt vmcnt(14)
	v_pk_mul_f32 v[2:3], v[2:3], v[134:135]
	s_waitcnt vmcnt(10)
	v_pk_mul_f32 v[4:5], v[4:5], v[136:137]
	global_store_dwordx4 v[118:119], v[2:5], off offset:48
	global_store_dwordx4 v[14:15], v[30:33], off offset:48
	s_branch .LBB0_627
